# bundle: pass A item-top barrier removed + gemm_tile prologue first full wait removed (accumulator clears overlap the DMA) + no-op v_fmac x,0,y instructions dropped from the LRU scans
# speedup vs baseline: 1.0001x; 1.0001x over previous
; DEVI unsigned pk2(float lo, float hi) { f32x2 v = {lo, hi}; bf16x2_t b = __builtin_convertvector(v, bf16x2_t); return __builtin_bit_cast(unsigned, b); }
; DEVI float bflo(unsigned u) { return __uint_as_float(u << 16); }
; DEVI float bfhi(unsigned u) { return __uint_as_float(u & 0xffff0000u); }
; template <bool PASS_C>
; DEVI void lru_item(const P& p, int item, int next_item, uint4& u0, uint4& u1, uint4& u2, float& cpre, char* smem) {
;     ...
;     {
;         const int tok = tid >> 2, cg0 = (tid & 3) * 16;
;         uint4 r[4][2];
; #pragma unroll
;         for (int k = 0; k < 4; ++k) { r[k][0] = *(const uint4*)(us + (tok + k) * 64 + cg0); r[k][1] = *(const uint4*)(us + (tok + k) * 64 + cg0 + 8); }
;         float val[16];
; #pragma unroll
;         for (int e = 0; e < 16; ++e) {
;             const int ch = cg0 + e;
;             float a = prm[4 * 64 + ch];
; #pragma unroll
;             for (int k = 0; k < 4; ++k) {
;                 const uint4 q = r[k][e >> 3];
;                 const unsigned wd = ((e >> 1) & 3) == 0 ? q.x : (((e >> 1) & 3) == 1 ? q.y : (((e >> 1) & 3) == 2 ? q.z : q.w));
;                 a += prm[k * 64 + ch] * ((e & 1) ? bfhi(wd) : bflo(wd));
;             }
;             val[e] = a;
;         }
;         uint4 o;
;         o.x = pk2(val[0], val[1]); o.y = pk2(val[2], val[3]); o.z = pk2(val[4], val[5]); o.w = pk2(val[6], val[7]);
;         *(uint4*)(ucb + tok * 128 + ((((cg0 >> 3) + 0) ^ (tok & 7)) << 4)) = o;
;         o.x = pk2(val[8], val[9]); o.y = pk2(val[10], val[11]); o.z = pk2(val[12], val[13]); o.w = pk2(val[14], val[15]);
;         *(uint4*)(ucb + tok * 128 + ((((cg0 >> 3) + 1) ^ (tok & 7)) << 4)) = o;
;     }
.LBB0_510:
	s_waitcnt lgkmcnt(0)
	s_barrier
	ds_read_b128 v[32:35], v118 offset:35840
	ds_read_b128 v[12:15], v118 offset:35856
	ds_read_b128 v[36:39], v118 offset:35968
	ds_read_b128 v[16:19], v118 offset:35984
	ds_read_b128 v[40:43], v118 offset:36096
	ds_read_b128 v[20:23], v118 offset:36112
	ds_read_b128 v[44:47], v118 offset:36224
	ds_read_b128 v[24:27], v118 offset:36240
	ds_read_b128 v[48:51], v111 offset:33792
	ds_read_b128 v[52:55], v111 offset:32768
	ds_read_b128 v[56:59], v111 offset:32784
	ds_read_b128 v[60:63], v111 offset:32800
	ds_read_b128 v[28:31], v111 offset:32816
	ds_read_b128 v[64:67], v111 offset:33024
	ds_read_b128 v[92:95], v111 offset:33808
	s_waitcnt lgkmcnt(14)
	v_lshlrev_b32_e32 v96, 16, v32
	v_and_b32_e32 v97, 0xffff0000, v32
	s_waitcnt lgkmcnt(5)
	v_pk_fma_f32 v[48:49], v[52:53], v[96:97], v[48:49]
	ds_read_b128 v[96:99], v111 offset:33280
	ds_read_b128 v[146:149], v111 offset:33536
	ds_read_b128 v[150:153], v111 offset:33040
	v_lshlrev_b32_e32 v32, 16, v33
	v_and_b32_e32 v33, 0xffff0000, v33
	v_lshlrev_b32_e32 v154, 16, v36
	v_and_b32_e32 v155, 0xffff0000, v36
	v_lshlrev_b32_e32 v36, 16, v37
	v_and_b32_e32 v37, 0xffff0000, v37
	v_pk_fma_f32 v[32:33], v[54:55], v[32:33], v[50:51]
	v_lshlrev_b32_e32 v158, 16, v40
	v_and_b32_e32 v159, 0xffff0000, v40
	s_waitcnt lgkmcnt(4)
	v_pk_fma_f32 v[48:49], v[64:65], v[154:155], v[48:49]
	ds_read_b128 v[154:157], v111 offset:33296
	v_lshlrev_b32_e32 v40, 16, v41
	v_and_b32_e32 v41, 0xffff0000, v41
	v_pk_fma_f32 v[32:33], v[66:67], v[36:37], v[32:33]
	v_lshlrev_b32_e32 v162, 16, v44
	v_and_b32_e32 v163, 0xffff0000, v44
	s_waitcnt lgkmcnt(3)
	v_pk_fma_f32 v[48:49], v[96:97], v[158:159], v[48:49]
	ds_read_b128 v[158:161], v111 offset:33552
	v_lshlrev_b32_e32 v44, 16, v45
	v_and_b32_e32 v45, 0xffff0000, v45
	v_pk_fma_f32 v[32:33], v[98:99], v[40:41], v[32:33]
	v_lshlrev_b32_e32 v36, 16, v38
	s_waitcnt lgkmcnt(3)
	v_pk_fma_f32 v[98:99], v[148:149], v[44:45], v[32:33]
	v_lshlrev_b32_e32 v32, 16, v34
	v_and_b32_e32 v33, 0xffff0000, v34
	v_and_b32_e32 v37, 0xffff0000, v38
	v_pk_fma_f32 v[32:33], v[56:57], v[32:33], v[92:93]
	v_lshlrev_b32_e32 v40, 16, v42
	v_and_b32_e32 v41, 0xffff0000, v42
	s_waitcnt lgkmcnt(2)
	v_pk_fma_f32 v[32:33], v[150:151], v[36:37], v[32:33]
	v_lshlrev_b32_e32 v44, 16, v46
	v_and_b32_e32 v45, 0xffff0000, v46
	s_waitcnt lgkmcnt(1)
	v_pk_fma_f32 v[32:33], v[154:155], v[40:41], v[32:33]
	v_lshlrev_b32_e32 v34, 16, v39
	s_waitcnt lgkmcnt(0)
	v_pk_fma_f32 v[92:93], v[158:159], v[44:45], v[32:33]
	v_lshlrev_b32_e32 v32, 16, v35
	v_and_b32_e32 v33, 0xffff0000, v35
	v_and_b32_e32 v35, 0xffff0000, v39
	v_pk_fma_f32 v[32:33], v[58:59], v[32:33], v[94:95]
	v_lshlrev_b32_e32 v36, 16, v43
	v_and_b32_e32 v37, 0xffff0000, v43
	v_pk_fma_f32 v[32:33], v[152:153], v[34:35], v[32:33]
	v_lshlrev_b32_e32 v38, 16, v47
	v_and_b32_e32 v39, 0xffff0000, v47
	v_pk_fma_f32 v[32:33], v[156:157], v[36:37], v[32:33]
	v_lshlrev_b32_e32 v44, 16, v12
	v_pk_fma_f32 v[94:95], v[160:161], v[38:39], v[32:33]
	ds_read_b128 v[32:35], v111 offset:33824
	ds_read_b128 v[36:39], v111 offset:33056
	ds_read_b128 v[40:43], v111 offset:33840
	v_and_b32_e32 v45, 0xffff0000, v12
	v_pk_fma_f32 v[96:97], v[146:147], v[162:163], v[48:49]
	v_lshlrev_b32_e32 v12, 16, v13
	s_waitcnt lgkmcnt(2)
	v_pk_fma_f32 v[32:33], v[60:61], v[44:45], v[32:33]
	ds_read_b128 v[44:47], v111 offset:33312
	ds_read_b128 v[48:51], v111 offset:33568
	ds_read_b128 v[52:55], v111 offset:33072
	v_and_b32_e32 v13, 0xffff0000, v13
	v_lshlrev_b32_e32 v56, 16, v16
	v_and_b32_e32 v57, 0xffff0000, v16
	v_lshlrev_b32_e32 v16, 16, v17
	v_and_b32_e32 v17, 0xffff0000, v17
	v_pk_fma_f32 v[12:13], v[62:63], v[12:13], v[34:35]
	v_lshlrev_b32_e32 v64, 16, v20
	v_and_b32_e32 v65, 0xffff0000, v20
	s_waitcnt lgkmcnt(4)
	v_pk_fma_f32 v[32:33], v[36:37], v[56:57], v[32:33]
	ds_read_b128 v[56:59], v111 offset:33328
	v_lshlrev_b32_e32 v20, 16, v21
	v_and_b32_e32 v21, 0xffff0000, v21
	v_pk_fma_f32 v[12:13], v[38:39], v[16:17], v[12:13]
	v_lshlrev_b32_e32 v146, 16, v24
	v_and_b32_e32 v147, 0xffff0000, v24
	s_waitcnt lgkmcnt(3)
	v_pk_fma_f32 v[32:33], v[44:45], v[64:65], v[32:33]
	ds_read_b128 v[64:67], v111 offset:33584
	v_lshlrev_b32_e32 v24, 16, v25
	v_and_b32_e32 v25, 0xffff0000, v25
	v_pk_fma_f32 v[12:13], v[46:47], v[20:21], v[12:13]
	v_lshlrev_b32_e32 v20, 16, v18
	s_waitcnt lgkmcnt(3)
	v_pk_fma_f32 v[16:17], v[50:51], v[24:25], v[12:13]
	v_lshlrev_b32_e32 v12, 16, v14
	v_and_b32_e32 v13, 0xffff0000, v14
	v_and_b32_e32 v21, 0xffff0000, v18
	v_pk_fma_f32 v[12:13], v[28:29], v[12:13], v[40:41]
	v_lshlrev_b32_e32 v24, 16, v22
	v_and_b32_e32 v25, 0xffff0000, v22
	s_waitcnt lgkmcnt(2)
	v_pk_fma_f32 v[12:13], v[52:53], v[20:21], v[12:13]
	v_lshlrev_b32_e32 v34, 16, v26
	v_and_b32_e32 v35, 0xffff0000, v26
	s_waitcnt lgkmcnt(1)
	v_pk_fma_f32 v[12:13], v[56:57], v[24:25], v[12:13]
	v_lshlrev_b32_e32 v14, 16, v19
	s_waitcnt lgkmcnt(0)
	v_pk_fma_f32 v[20:21], v[64:65], v[34:35], v[12:13]
	v_lshlrev_b32_e32 v12, 16, v15
	v_and_b32_e32 v13, 0xffff0000, v15
	v_and_b32_e32 v15, 0xffff0000, v19
	v_pk_fma_f32 v[12:13], v[30:31], v[12:13], v[42:43]
	v_lshlrev_b32_e32 v18, 16, v23
	v_and_b32_e32 v19, 0xffff0000, v23
	v_pk_fma_f32 v[12:13], v[54:55], v[14:15], v[12:13]
	v_lshlrev_b32_e32 v22, 16, v27
	v_and_b32_e32 v23, 0xffff0000, v27
	v_pk_fma_f32 v[12:13], v[58:59], v[18:19], v[12:13]
	v_pk_fma_f32 v[32:33], v[48:49], v[146:147], v[32:33]
	v_pk_fma_f32 v[18:19], v[66:67], v[22:23], v[12:13]
	v_cvt_pk_bf16_f32 v12, v96, v97
	v_cvt_pk_bf16_f32 v13, v98, v99
	v_cvt_pk_bf16_f32 v14, v92, v93
	v_cvt_pk_bf16_f32 v15, v94, v95
	ds_write_b128 v119, v[12:15] offset:44544
	v_cvt_pk_bf16_f32 v12, v32, v33
	v_cvt_pk_bf16_f32 v13, v16, v17
	v_cvt_pk_bf16_f32 v14, v20, v21
	v_cvt_pk_bf16_f32 v15, v18, v19
	ds_write_b128 v120, v[12:15] offset:44544
	v_add_u32_e32 v12, v113, v114
	s_waitcnt lgkmcnt(0)
	s_barrier
; DEVI float bf2f(bf16_t h) { return __uint_as_float(((unsigned)h) << 16); }
; template <bool PASS_C>
; DEVI void lru_item(const P& p, int item, int next_item, uint4& u0, uint4& u1, uint4& u2, float& cpre, char* smem) {
;     ...
;     f32x4 acc[16];
; #pragma unroll
;     for (int n = 0; n < 16; ++n) acc[n] = (f32x4){0.f, 0.f, 0.f, 0.f};
;     {
;         bf16x8 af[2];
; #pragma unroll
;         for (int kk = 0; kk < 2; ++kk) af[kk] = *(const bf16x8*)(ucb + (16 * w + fr) * 128 + (((kk * 4 + fq) ^ (fr & 7)) << 4));
; #pragma unroll
;         for (int n = 0; n < 16; ++n)
; #pragma unroll
;             for (int kk = 0; kk < 2; ++kk) {
;                 const bf16x8 bfr = *(const bf16x8*)(smem + (16 * n + fr) * 128 + (((kk * 4 + fq) ^ (fr & 7)) << 4));
;                 acc[n] = __builtin_amdgcn_mfma_f32_16x16x32_bf16(af[kk], bfr, acc[n], 0, 0, 0);
;             }
;     }
;     float av[4][2][4], bv[4][2][4], apre[4][2], bpre[4][2];
; #pragma unroll
;     for (int nn = 0; nn < 4; ++nn) {
;         const int ch = 16 * nn + fr;
;         float uc[4];
; #pragma unroll
;         for (int j = 0; j < 4; ++j) {
;             const int tl = 16 * w + 4 * fq + j;
;             uc[j] = bf2f(*(const bf16_t*)(ucb + tl * 128 + ((((ch >> 3)) ^ (tl & 7)) << 4) + (ch & 7) * 2));
;         }
; #pragma unroll
;         for (int d = 0; d < 2; ++d) {
;             const float ba = prm[(5 + d) * 64 + ch], bx = prm[(7 + d) * 64 + ch], nsp8 = prm[(9 + d) * 64 + ch];
; #pragma unroll
;             for (int j = 0; j < 4; ++j) {
;                 const float r = __builtin_amdgcn_rcpf(1.0f + __builtin_amdgcn_exp2f(__builtin_fmaf(acc[(2 * d) * 4 + nn][j], -LOG2E, ba)));
;                 const float ig = __builtin_amdgcn_rcpf(1.0f + __builtin_amdgcn_exp2f(__builtin_fmaf(acc[(2 * d + 1) * 4 + nn][j], -LOG2E, bx)));
;                 const float a_ = __builtin_amdgcn_exp2f(nsp8 * r);
;                 av[nn][d][j] = a_;
;                 bv[nn][d][j] = __builtin_amdgcn_sqrtf(__builtin_fmaf(-a_, a_, 1.0f)) * ig * uc[j];
	v_add_u32_e32 v75, v112, v114
	v_add_u32_e32 v20, v113, v115
	v_add_u32_e32 v77, v112, v115
	ds_read_b128 v[12:15], v12 offset:44544
	ds_read_b128 v[92:95], v20 offset:44544
	ds_read_b32 v83, v116 offset:35072
	ds_read_b128 v[232:235], v75
	ds_read_b128 v[236:239], v77
	ds_read_b128 v[240:243], v75 offset:2048
	ds_read_b128 v[244:247], v77 offset:2048
	ds_read_b128 v[248:251], v75 offset:4096
	ds_read_b128 v[158:161], v77 offset:4096
	ds_read_b128 v[252:255], v75 offset:6144
	ds_read_b128 v[218:221], v77 offset:6144
	s_waitcnt lgkmcnt(4)
	v_mfma_f32_16x16x32_bf16 v[146:149], v[12:15], v[232:235], 0
	ds_read_b128 v[222:225], v75 offset:8192
	ds_read_b128 v[226:229], v77 offset:8192
	ds_read_b128 v[96:99], v75 offset:10240
	ds_read_b128 v[154:157], v77 offset:10240
	v_mfma_f32_16x16x32_bf16 v[56:59], v[12:15], v[240:243], 0
	v_mfma_f32_16x16x32_bf16 v[146:149], v[92:95], v[236:239], v[146:149]
	v_mfma_f32_16x16x32_bf16 v[56:59], v[92:95], v[244:247], v[56:59]
	s_waitcnt lgkmcnt(4)
	v_mfma_f32_16x16x32_bf16 v[40:43], v[12:15], v[248:251], 0
	ds_read_b128 v[232:235], v75 offset:12288
	ds_read_b128 v[236:239], v77 offset:12288
	ds_read_b128 v[240:243], v75 offset:14336
	ds_read_b128 v[244:247], v77 offset:14336
	v_mfma_f32_16x16x32_bf16 v[24:27], v[12:15], v[252:255], 0
	v_mfma_f32_16x16x32_bf16 v[40:43], v[92:95], v[158:161], v[40:43]
	v_mfma_f32_16x16x32_bf16 v[24:27], v[92:95], v[218:221], v[24:27]
	s_waitcnt lgkmcnt(4)
	v_mfma_f32_16x16x32_bf16 v[150:153], v[12:15], v[222:225], 0
	ds_read_b128 v[248:251], v75 offset:16384
	ds_read_b128 v[158:161], v77 offset:16384
	ds_read_b128 v[252:255], v75 offset:18432
	ds_read_b128 v[218:221], v77 offset:18432
	v_mfma_f32_16x16x32_bf16 v[52:55], v[12:15], v[96:99], 0
	v_mfma_f32_16x16x32_bf16 v[150:153], v[92:95], v[226:229], v[150:153]
	v_mfma_f32_16x16x32_bf16 v[52:55], v[92:95], v[154:157], v[52:55]
	s_waitcnt lgkmcnt(4)
	v_mfma_f32_16x16x32_bf16 v[36:39], v[12:15], v[232:235], 0
	ds_read_b128 v[222:225], v75 offset:20480
	ds_read_b128 v[226:229], v77 offset:20480
	ds_read_b128 v[96:99], v75 offset:22528
	ds_read_b128 v[154:157], v77 offset:22528
	v_mfma_f32_16x16x32_bf16 v[20:23], v[12:15], v[240:243], 0
	v_mfma_f32_16x16x32_bf16 v[36:39], v[92:95], v[236:239], v[36:39]
	v_mfma_f32_16x16x32_bf16 v[20:23], v[92:95], v[244:247], v[20:23]
	s_waitcnt lgkmcnt(4)
	v_mfma_f32_16x16x32_bf16 v[64:67], v[12:15], v[248:251], 0
	ds_read_b128 v[232:235], v75 offset:24576
	ds_read_b128 v[236:239], v77 offset:24576
	ds_read_b128 v[240:243], v75 offset:26624
	ds_read_b128 v[244:247], v77 offset:26624
	v_mfma_f32_16x16x32_bf16 v[48:51], v[12:15], v[252:255], 0
	v_mfma_f32_16x16x32_bf16 v[64:67], v[92:95], v[158:161], v[64:67]
	v_mfma_f32_16x16x32_bf16 v[48:51], v[92:95], v[218:221], v[48:51]
	s_waitcnt lgkmcnt(4)
	v_mfma_f32_16x16x32_bf16 v[32:35], v[12:15], v[222:225], 0
	ds_read_b128 v[248:251], v75 offset:28672
	ds_read_b128 v[252:255], v75 offset:30720
	ds_read_b128 v[158:161], v77 offset:28672
	v_mfma_f32_16x16x32_bf16 v[16:19], v[12:15], v[96:99], 0
	v_mfma_f32_16x16x32_bf16 v[32:35], v[92:95], v[226:229], v[32:35]
	v_mfma_f32_16x16x32_bf16 v[16:19], v[92:95], v[154:157], v[16:19]
	s_waitcnt lgkmcnt(3)
	v_mfma_f32_16x16x32_bf16 v[60:63], v[12:15], v[232:235], 0
	v_mfma_f32_16x16x32_bf16 v[44:47], v[12:15], v[240:243], 0
	v_mfma_f32_16x16x32_bf16 v[60:63], v[92:95], v[236:239], v[60:63]
	v_mfma_f32_16x16x32_bf16 v[44:47], v[92:95], v[244:247], v[44:47]
	s_waitcnt lgkmcnt(1)
	v_mfma_f32_16x16x32_bf16 v[28:31], v[12:15], v[248:251], 0
	v_mfma_f32_16x16x32_bf16 v[12:15], v[12:15], v[252:255], 0
	ds_read_b128 v[96:99], v77 offset:30720
	ds_read2st64_b32 v[154:155], v116 offset0:133 offset1:135
	ds_read_u16 v246, v121 offset:44544
	ds_read_u16 v247, v122 offset:44544
	ds_read_u16 v248, v123 offset:44544
	ds_read_u16 v249, v124 offset:44544
	ds_read2st64_b32 v[232:233], v116 offset0:134 offset1:136
	ds_read_b32 v250, v116 offset:35328
	v_add_u32_e32 v217, 64, v116
	ds_read2st64_b32 v[234:235], v217 offset0:133 offset1:135
	ds_read_u16 v251, v125 offset:44544
	ds_read_u16 v252, v126 offset:44544
	ds_read_u16 v253, v127 offset:44544
	ds_read_u16 v254, v128 offset:44544
	ds_read_b32 v255, v116 offset:35136
	v_add_u32_e32 v217, 64, v116
	ds_read2st64_b32 v[236:237], v217 offset0:134 offset1:136
	ds_read_b32 v218, v116 offset:35392
	v_add_u32_e32 v217, 0x80, v116
	ds_read2st64_b32 v[238:239], v217 offset0:133 offset1:135
	ds_read_u16 v219, v129 offset:44544
	ds_read_u16 v220, v130 offset:44544
	ds_read_u16 v221, v131 offset:44544
	ds_read_u16 v222, v132 offset:44544
	ds_read_b32 v223, v116 offset:35200
	v_add_u32_e32 v217, 0x80, v116
	ds_read2st64_b32 v[240:241], v217 offset0:134 offset1:136
	ds_read_b32 v224, v116 offset:35456
	v_add_u32_e32 v217, 0xc0, v116
	ds_read2st64_b32 v[242:243], v217 offset0:133 offset1:135
	ds_read_u16 v225, v133 offset:44544
	ds_read_u16 v226, v134 offset:44544
	ds_read_u16 v227, v135 offset:44544
	ds_read_u16 v228, v136 offset:44544
	ds_read_b32 v229, v116 offset:35264
	v_add_u32_e32 v217, 0xc0, v116
	ds_read2st64_b32 v[244:245], v217 offset0:134 offset1:136
	ds_read_b32 v231, v116 offset:35520
	s_waitcnt lgkmcnt(0)
; template <bool PASS_C>
; DEVI void lru_item(const P& p, int item, int next_item, uint4& u0, uint4& u1, uint4& u2, float& cpre, char* smem) {
;     ...
;         for (int d = 0; d < 2; ++d) {
;             const float ba = prm[(5 + d) * 64 + ch], bx = prm[(7 + d) * 64 + ch], nsp8 = prm[(9 + d) * 64 + ch];
; #pragma unroll
;             for (int j = 0; j < 4; ++j) {
;                 const float r = __builtin_amdgcn_rcpf(1.0f + __builtin_amdgcn_exp2f(__builtin_fmaf(acc[(2 * d) * 4 + nn][j], -LOG2E, ba)));
;                 const float ig = __builtin_amdgcn_rcpf(1.0f + __builtin_amdgcn_exp2f(__builtin_fmaf(acc[(2 * d + 1) * 4 + nn][j], -LOG2E, bx)));
;                 const float a_ = __builtin_amdgcn_exp2f(nsp8 * r);
;                 av[nn][d][j] = a_;
;                 bv[nn][d][j] = __builtin_amdgcn_sqrtf(__builtin_fmaf(-a_, a_, 1.0f)) * ig * uc[j];
;             }
;             float A = 1.f, Bq = 0.f;
;             if (d == 0) {
; #pragma unroll
;                 for (int j = 0; j < 4; ++j) { Bq = av[nn][d][j] * Bq + bv[nn][d][j]; A *= av[nn][d][j]; }
;             } else {
; #pragma unroll
;                 for (int j = 3; j >= 0; --j) { Bq = av[nn][d][j] * Bq + bv[nn][d][j]; A *= av[nn][d][j]; }
;             }
;             float Ag[4], Bg[4];
;             rowgather4(A, Ag); rowgather4(Bq, Bg);
;             float AW = 1.f, BW = 0.f, AP = 1.f, BP = 0.f;
;             if (d == 0) {
; #pragma unroll
;                 for (int g = 0; g < 4; ++g) {
;                     if (g == fq) { AP = AW; BP = BW; }
;                     BW = Ag[g] * BW + Bg[g]; AW *= Ag[g];
;                 }
;             } else {
; #pragma unroll
;                 for (int g = 3; g >= 0; --g) {
;                     if (g == fq) { AP = AW; BP = BW; }
;                     BW = Ag[g] * BW + Bg[g]; AW *= Ag[g];
;                 }
;             }
;             apre[nn][d] = AP; bpre[nn][d] = BP;
;             if (fq == 0) { wagg[((w * 2 + d) * 64 + ch) * 2 + 0] = AW; wagg[((w * 2 + d) * 64 + ch) * 2 + 1] = BW; }
	v_fmamk_f32 v81, v146, 0xbfb8aa3b, v154
	v_exp_f32_e32 v81, v81
	v_fmamk_f32 v91, v149, 0xbfb8aa3b, v154
	v_exp_f32_e32 v91, v91
	v_mfma_f32_16x16x32_bf16 v[28:31], v[92:95], v[158:161], v[28:31]
	v_add_f32_e32 v81, 1.0, v81
	v_rcp_f32_e32 v87, v81
	v_fmamk_f32 v81, v147, 0xbfb8aa3b, v154
	v_exp_f32_e32 v89, v81
	v_lshlrev_b32_e32 v81, 16, v249
	v_mul_f32_e32 v85, v83, v87
	v_mfma_f32_16x16x32_bf16 v[12:15], v[92:95], v[96:99], v[12:15]
	v_add_f32_e32 v87, 1.0, v89
	v_fmamk_f32 v89, v148, 0xbfb8aa3b, v154
	v_exp_f32_e32 v89, v89
	v_add_f32_e32 v91, 1.0, v91
	v_fmamk_f32 v93, v150, 0xbfb8aa3b, v155
	v_rcp_f32_e32 v87, v87
	v_add_f32_e32 v89, 1.0, v89
	v_exp_f32_e32 v85, v85
	v_rcp_f32_e32 v89, v89
	v_rcp_f32_e32 v91, v91
	v_exp_f32_e32 v93, v93
	v_mul_f32_e32 v87, v83, v87
	v_mul_f32_e32 v89, v83, v89
	v_mul_f32_e32 v83, v83, v91
	v_add_f32_e32 v91, 1.0, v93
	v_fma_f32 v93, -v85, v85, 1.0
	v_rcp_f32_e32 v91, v91
	v_sqrt_f32_e32 v93, v93
	v_fmamk_f32 v94, v151, 0xbfb8aa3b, v155
	v_exp_f32_e32 v87, v87
	v_exp_f32_e32 v94, v94
	v_lshlrev_b32_e32 v75, 16, v246
	v_mul_f32_e32 v91, v91, v93
	v_mul_f32_e32 v91, v91, v75
	v_mul_f32_e32 v92, v85, v87
	v_add_f32_e32 v85, 1.0, v94
	v_fma_f32 v93, -v87, v87, 1.0
	v_rcp_f32_e32 v85, v85
	v_sqrt_f32_e32 v93, v93
	v_mul_f32_e32 v87, v87, v91
	v_fmamk_f32 v91, v152, 0xbfb8aa3b, v155
	v_exp_f32_e32 v89, v89
	v_exp_f32_e32 v91, v91
	v_lshlrev_b32_e32 v77, 16, v247
	v_mul_f32_e32 v85, v85, v93
	v_fmac_f32_e32 v87, v85, v77
	v_fmamk_f32 v155, v153, 0xbfb8aa3b, v155
	v_exp_f32_e32 v83, v83
	v_mul_f32_e32 v85, v89, v87
	v_add_f32_e32 v87, 1.0, v91
	v_exp_f32_e32 v91, v155
	v_mul_f32_e32 v92, v89, v92
	v_fma_f32 v89, -v89, v89, 1.0
	v_rcp_f32_e32 v87, v87
	v_sqrt_f32_e32 v89, v89
	v_add_f32_e32 v91, 1.0, v91
	v_fma_f32 v93, -v83, v83, 1.0
	v_rcp_f32_e32 v91, v91
	v_sqrt_f32_e32 v93, v93
	v_lshlrev_b32_e32 v79, 16, v248
	v_mul_f32_e32 v87, v87, v89
	v_fmac_f32_e32 v85, v87, v79
	v_mul_f32_e32 v92, v83, v92
	v_mul_f32_e32 v83, v83, v85
	v_mul_f32_e32 v85, v91, v93
	v_fmac_f32_e32 v83, v85, v81
	v_mov_b32_e32 v96, v92
	v_mov_b32_e32 v85, v83
	s_nop 0
	v_permlane16_swap_b32_e32 v92, v96
	v_permlane16_swap_b32_e32 v83, v85
	v_mov_b32_e32 v94, v92
	v_mov_b32_e32 v95, v96
	v_mov_b32_e32 v97, v83
	v_mov_b32_e32 v99, v85
	v_permlane32_swap_b32_e32 v92, v94
	v_permlane32_swap_b32_e32 v96, v95
	v_permlane32_swap_b32_e32 v83, v97
	v_permlane32_swap_b32_e32 v85, v99
	s_and_saveexec_b64 s[12:13], s[8:9]
	s_cbranch_execz .LBB0_512
	v_fmac_f32_e32 v85, v83, v96
	v_mul_f32_e32 v93, v85, v94
	v_pk_mul_f32 v[146:147], v[92:93], v[96:97]
	v_pk_add_f32 v[92:93], v[92:93], v[96:97]
	v_mov_b32_e32 v96, v95
	v_mov_b32_e32 v92, v146
	v_mov_b32_e32 v98, v95
	v_pk_mul_f32 v[146:147], v[146:147], v[94:95]
	v_pk_fma_f32 v[92:93], v[92:93], v[94:95], v[98:99]
	v_pk_mul_f32 v[96:97], v[146:147], v[96:97]
	s_nop 0
	v_mov_b32_e32 v97, v93
	ds_write_b64 v141, v[96:97] offset:52736
.LBB0_512:
	s_or_b64 exec, exec, s[12:13]
	v_fmamk_f32 v67, v67, 0xbfb8aa3b, v232
	v_exp_f32_e32 v67, v67
	v_fmamk_f32 v66, v66, 0xbfb8aa3b, v232
	v_fmamk_f32 v65, v65, 0xbfb8aa3b, v232
	v_fmamk_f32 v64, v64, 0xbfb8aa3b, v232
	v_add_f32_e32 v67, 1.0, v67
	v_exp_f32_e32 v66, v66
	v_exp_f32_e32 v65, v65
	v_rcp_f32_e32 v67, v67
	v_exp_f32_e32 v64, v64
	v_fmamk_f32 v63, v63, 0xbfb8aa3b, v233
	v_add_f32_e32 v66, 1.0, v66
	v_add_f32_e32 v65, 1.0, v65
	v_mul_f32_e32 v67, v250, v67
	v_add_f32_e32 v64, 1.0, v64
	v_exp_f32_e32 v63, v63
	v_rcp_f32_e32 v66, v66
	v_exp_f32_e32 v67, v67
	v_rcp_f32_e32 v65, v65
	v_rcp_f32_e32 v64, v64
	v_add_f32_e32 v63, 1.0, v63
	v_mul_f32_e32 v66, v250, v66
	v_mul_f32_e32 v65, v250, v65
	v_mul_f32_e32 v64, v250, v64
	v_rcp_f32_e32 v83, v63
	v_fma_f32 v63, -v67, v67, 1.0
	v_sqrt_f32_e32 v87, v63
	v_fmamk_f32 v62, v62, 0xbfb8aa3b, v233
	v_exp_f32_e32 v66, v66
	v_exp_f32_e32 v62, v62
	v_mul_f32_e32 v83, v83, v87
	v_mul_f32_e32 v81, v83, v81
	v_mul_f32_e32 v85, v67, v66
	v_add_f32_e32 v62, 1.0, v62
	v_fma_f32 v67, -v66, v66, 1.0
	v_rcp_f32_e32 v62, v62
	v_sqrt_f32_e32 v67, v67
	v_fmamk_f32 v61, v61, 0xbfb8aa3b, v233
	v_exp_f32_e32 v65, v65
	v_exp_f32_e32 v61, v61
	v_fmamk_f32 v93, v60, 0xbfb8aa3b, v233
	v_exp_f32_e32 v64, v64
	v_mul_f32_e32 v66, v66, v81
	v_mul_f32_e32 v62, v62, v67
	v_exp_f32_e32 v60, v93
	v_fmac_f32_e32 v66, v62, v79
	v_mul_f32_e32 v85, v65, v85
	v_mul_f32_e32 v62, v65, v66
	v_add_f32_e32 v61, 1.0, v61
	v_fma_f32 v65, -v65, v65, 1.0
	v_rcp_f32_e32 v61, v61
	v_sqrt_f32_e32 v65, v65
	v_add_f32_e32 v60, 1.0, v60
	v_fma_f32 v66, -v64, v64, 1.0
	v_rcp_f32_e32 v60, v60
	v_sqrt_f32_e32 v66, v66
	v_mul_f32_e32 v61, v61, v65
	v_fmac_f32_e32 v62, v61, v77
	v_mul_f32_e32 v61, v64, v62
	v_mul_f32_e32 v60, v60, v66
	v_mul_f32_e32 v63, v64, v85
	v_fmac_f32_e32 v61, v60, v75
	v_mov_b32_e32 v62, v63
	v_mov_b32_e32 v67, v61
	s_nop 0
	v_permlane16_swap_b32_e32 v63, v62
	v_permlane16_swap_b32_e32 v61, v67
	v_mov_b32_e32 v64, v63
	v_mov_b32_e32 v66, v62
	v_mov_b32_e32 v60, v61
	v_mov_b32_e32 v65, v67
	v_permlane32_swap_b32_e32 v63, v64
	v_permlane32_swap_b32_e32 v62, v66
	v_permlane32_swap_b32_e32 v61, v60
	v_permlane32_swap_b32_e32 v67, v65
	s_and_saveexec_b64 s[12:13], s[8:9]
	s_cbranch_execz .LBB0_514
	v_fmac_f32_e32 v60, v65, v64
	v_mul_f32_e32 v65, v60, v62
	v_pk_mul_f32 v[92:93], v[64:65], v[66:67]
	v_pk_add_f32 v[64:65], v[64:65], v[66:67]
	v_mov_b32_e32 v66, v63
	v_mov_b32_e32 v64, v92
	v_mov_b32_e32 v60, v63
	v_pk_mul_f32 v[92:93], v[92:93], v[62:63]
	v_pk_fma_f32 v[60:61], v[64:65], v[62:63], v[60:61]
	v_pk_mul_f32 v[66:67], v[92:93], v[66:67]
	s_nop 0
	v_mov_b32_e32 v67, v61
	ds_write_b64 v141, v[66:67] offset:53248
; template <bool PASS_C>
; DEVI void lru_item(const P& p, int item, int next_item, uint4& u0, uint4& u1, uint4& u2, float& cpre, char* smem) {
;     ...
;         for (int d = 0; d < 2; ++d) {
;             const float ba = prm[(5 + d) * 64 + ch], bx = prm[(7 + d) * 64 + ch], nsp8 = prm[(9 + d) * 64 + ch];
; #pragma unroll
;             for (int j = 0; j < 4; ++j) {
;                 const float r = __builtin_amdgcn_rcpf(1.0f + __builtin_amdgcn_exp2f(__builtin_fmaf(acc[(2 * d) * 4 + nn][j], -LOG2E, ba)));
;                 const float ig = __builtin_amdgcn_rcpf(1.0f + __builtin_amdgcn_exp2f(__builtin_fmaf(acc[(2 * d + 1) * 4 + nn][j], -LOG2E, bx)));
;                 const float a_ = __builtin_amdgcn_exp2f(nsp8 * r);
;                 av[nn][d][j] = a_;
;                 bv[nn][d][j] = __builtin_amdgcn_sqrtf(__builtin_fmaf(-a_, a_, 1.0f)) * ig * uc[j];
;             }
;             float A = 1.f, Bq = 0.f;
;             if (d == 0) {
; #pragma unroll
;                 for (int j = 0; j < 4; ++j) { Bq = av[nn][d][j] * Bq + bv[nn][d][j]; A *= av[nn][d][j]; }
;             } else {
; #pragma unroll
;                 for (int j = 3; j >= 0; --j) { Bq = av[nn][d][j] * Bq + bv[nn][d][j]; A *= av[nn][d][j]; }
;             }
;             float Ag[4], Bg[4];
;             rowgather4(A, Ag); rowgather4(Bq, Bg);
;             float AW = 1.f, BW = 0.f, AP = 1.f, BP = 0.f;
;             if (d == 0) {
; #pragma unroll
;                 for (int g = 0; g < 4; ++g) {
;                     if (g == fq) { AP = AW; BP = BW; }
;                     BW = Ag[g] * BW + Bg[g]; AW *= Ag[g];
;                 }
;             } else {
; #pragma unroll
;                 for (int g = 3; g >= 0; --g) {
;                     if (g == fq) { AP = AW; BP = BW; }
;                     BW = Ag[g] * BW + Bg[g]; AW *= Ag[g];
;                 }
;             }
;             apre[nn][d] = AP; bpre[nn][d] = BP;
;             if (fq == 0) { wagg[((w * 2 + d) * 64 + ch) * 2 + 0] = AW; wagg[((w * 2 + d) * 64 + ch) * 2 + 1] = BW; }
.LBB0_514:
	s_or_b64 exec, exec, s[12:13]
	v_lshlrev_b32_e32 v60, 16, v251
	v_lshlrev_b32_e32 v61, 16, v252
	v_lshlrev_b32_e32 v62, 16, v253
	v_fmamk_f32 v56, v56, 0xbfb8aa3b, v234
	v_exp_f32_e32 v56, v56
	v_fmamk_f32 v57, v57, 0xbfb8aa3b, v234
	v_fmamk_f32 v58, v58, 0xbfb8aa3b, v234
	v_fmamk_f32 v59, v59, 0xbfb8aa3b, v234
	v_add_f32_e32 v56, 1.0, v56
	v_rcp_f32_e32 v56, v56
	v_exp_f32_e32 v57, v57
	v_exp_f32_e32 v58, v58
	v_exp_f32_e32 v59, v59
	v_fmamk_f32 v52, v52, 0xbfb8aa3b, v235
	v_mul_f32_e32 v56, v255, v56
	v_add_f32_e32 v57, 1.0, v57
	v_add_f32_e32 v58, 1.0, v58
	v_add_f32_e32 v59, 1.0, v59
	v_exp_f32_e32 v52, v52
	v_rcp_f32_e32 v57, v57
	v_exp_f32_e32 v56, v56
	v_rcp_f32_e32 v58, v58
	v_rcp_f32_e32 v59, v59
	v_add_f32_e32 v52, 1.0, v52
	v_mul_f32_e32 v57, v255, v57
	v_mul_f32_e32 v58, v255, v58
	v_mul_f32_e32 v59, v255, v59
	v_rcp_f32_e32 v65, v52
	v_fma_f32 v52, -v56, v56, 1.0
	v_sqrt_f32_e32 v75, v52
	v_fmamk_f32 v53, v53, 0xbfb8aa3b, v235
	v_exp_f32_e32 v57, v57
	v_exp_f32_e32 v53, v53
	v_mul_f32_e32 v65, v65, v75
	v_mul_f32_e32 v65, v65, v60
	v_mul_f32_e32 v66, v56, v57
	v_add_f32_e32 v53, 1.0, v53
	v_fma_f32 v56, -v57, v57, 1.0
	v_fmamk_f32 v54, v54, 0xbfb8aa3b, v235
	v_exp_f32_e32 v58, v58
	v_rcp_f32_e32 v53, v53
	v_sqrt_f32_e32 v56, v56
	v_exp_f32_e32 v54, v54
	v_fmamk_f32 v67, v55, 0xbfb8aa3b, v235
	v_exp_f32_e32 v59, v59
	v_exp_f32_e32 v55, v67
	v_mul_f32_e32 v57, v57, v65
	v_mul_f32_e32 v53, v53, v56
	v_add_f32_e32 v54, 1.0, v54
	v_fma_f32 v56, -v58, v58, 1.0
	v_fmac_f32_e32 v57, v53, v61
	v_rcp_f32_e32 v54, v54
	v_sqrt_f32_e32 v56, v56
	v_mul_f32_e32 v53, v58, v57
	v_add_f32_e32 v55, 1.0, v55
	v_fma_f32 v57, -v59, v59, 1.0
	v_rcp_f32_e32 v55, v55
	v_sqrt_f32_e32 v57, v57
	v_mul_f32_e32 v54, v54, v56
	v_fmac_f32_e32 v53, v54, v62
	v_lshlrev_b32_e32 v63, 16, v254
	v_mul_f32_e32 v66, v58, v66
	v_mul_f32_e32 v53, v59, v53
	v_mul_f32_e32 v54, v55, v57
	v_mul_f32_e32 v52, v59, v66
	v_fmac_f32_e32 v53, v54, v63
	v_mov_b32_e32 v56, v52
	v_mov_b32_e32 v58, v53
	s_nop 0
	v_permlane16_swap_b32_e32 v52, v56
	v_permlane16_swap_b32_e32 v53, v58
	v_mov_b32_e32 v54, v52
	v_mov_b32_e32 v55, v56
	v_mov_b32_e32 v57, v53
	v_mov_b32_e32 v59, v58
	v_permlane32_swap_b32_e32 v52, v54
	v_permlane32_swap_b32_e32 v56, v55
	v_permlane32_swap_b32_e32 v53, v57
	v_permlane32_swap_b32_e32 v58, v59
	s_and_saveexec_b64 s[12:13], s[8:9]
	s_cbranch_execz .LBB0_516
	v_fmac_f32_e32 v58, v53, v56
	v_mul_f32_e32 v53, v58, v54
	v_pk_mul_f32 v[66:67], v[52:53], v[56:57]
	v_pk_add_f32 v[52:53], v[52:53], v[56:57]
	v_mov_b32_e32 v56, v55
	v_mov_b32_e32 v52, v66
	v_mov_b32_e32 v58, v55
	v_pk_mul_f32 v[66:67], v[66:67], v[54:55]
	v_pk_fma_f32 v[52:53], v[52:53], v[54:55], v[58:59]
	v_pk_mul_f32 v[56:57], v[66:67], v[56:57]
	s_nop 0
	v_mov_b32_e32 v57, v53
	ds_write_b64 v142, v[56:57] offset:52736
.LBB0_516:
	s_or_b64 exec, exec, s[12:13]
	v_fmamk_f32 v51, v51, 0xbfb8aa3b, v236
	v_exp_f32_e32 v51, v51
	v_fmamk_f32 v50, v50, 0xbfb8aa3b, v236
	v_exp_f32_e32 v50, v50
	v_fmamk_f32 v49, v49, 0xbfb8aa3b, v236
	v_exp_f32_e32 v49, v49
	v_add_f32_e32 v51, 1.0, v51
	v_fmamk_f32 v48, v48, 0xbfb8aa3b, v236
	v_rcp_f32_e32 v51, v51
	v_exp_f32_e32 v48, v48
	v_add_f32_e32 v50, 1.0, v50
	v_rcp_f32_e32 v50, v50
	v_add_f32_e32 v49, 1.0, v49
	v_fmamk_f32 v47, v47, 0xbfb8aa3b, v237
	v_mul_f32_e32 v51, v218, v51
	v_rcp_f32_e32 v49, v49
	v_add_f32_e32 v48, 1.0, v48
	v_exp_f32_e32 v47, v47
	v_exp_f32_e32 v51, v51
	v_rcp_f32_e32 v48, v48
	v_mul_f32_e32 v50, v218, v50
	v_exp_f32_e32 v50, v50
	v_mul_f32_e32 v49, v218, v49
	v_add_f32_e32 v47, 1.0, v47
	v_exp_f32_e32 v49, v49
	v_mul_f32_e32 v48, v218, v48
	v_rcp_f32_e32 v54, v47
	v_fma_f32 v47, -v51, v51, 1.0
	v_exp_f32_e32 v48, v48
	v_sqrt_f32_e32 v55, v47
	v_fmamk_f32 v46, v46, 0xbfb8aa3b, v237
	v_mul_f32_e32 v52, v51, v50
	v_exp_f32_e32 v46, v46
	v_mul_f32_e32 v52, v49, v52
	v_mul_f32_e32 v47, v48, v52
	v_mul_f32_e32 v52, v54, v55
	v_mul_f32_e32 v52, v52, v63
	v_add_f32_e32 v46, 1.0, v46
	v_fma_f32 v51, -v50, v50, 1.0
	v_rcp_f32_e32 v46, v46
	v_sqrt_f32_e32 v51, v51
	v_fmamk_f32 v45, v45, 0xbfb8aa3b, v237
	v_exp_f32_e32 v45, v45
	v_fmamk_f32 v53, v44, 0xbfb8aa3b, v237
	v_mul_f32_e32 v50, v50, v52
	v_mul_f32_e32 v46, v46, v51
	v_exp_f32_e32 v44, v53
	v_fmac_f32_e32 v50, v46, v62
	v_mul_f32_e32 v46, v49, v50
	v_add_f32_e32 v45, 1.0, v45
	v_fma_f32 v49, -v49, v49, 1.0
	v_rcp_f32_e32 v45, v45
	v_sqrt_f32_e32 v49, v49
	v_add_f32_e32 v44, 1.0, v44
	v_fma_f32 v50, -v48, v48, 1.0
	v_rcp_f32_e32 v44, v44
	v_sqrt_f32_e32 v50, v50
	v_mul_f32_e32 v45, v45, v49
	v_fmac_f32_e32 v46, v45, v61
	v_mul_f32_e32 v45, v48, v46
	v_mul_f32_e32 v44, v44, v50
	v_fmac_f32_e32 v45, v44, v60
	v_mov_b32_e32 v46, v47
	v_mov_b32_e32 v51, v45
	s_nop 0
	v_permlane16_swap_b32_e32 v47, v46
	v_permlane16_swap_b32_e32 v45, v51
	v_mov_b32_e32 v48, v47
	v_mov_b32_e32 v50, v46
	v_mov_b32_e32 v44, v45
	v_mov_b32_e32 v49, v51
	v_permlane32_swap_b32_e32 v47, v48
	v_permlane32_swap_b32_e32 v46, v50
	v_permlane32_swap_b32_e32 v45, v44
	v_permlane32_swap_b32_e32 v51, v49
	s_and_saveexec_b64 s[12:13], s[8:9]
	s_cbranch_execz .LBB0_518
	v_fmac_f32_e32 v44, v49, v48
	v_mul_f32_e32 v49, v44, v46
	v_pk_mul_f32 v[52:53], v[48:49], v[50:51]
	v_pk_add_f32 v[48:49], v[48:49], v[50:51]
	v_mov_b32_e32 v50, v47
	v_mov_b32_e32 v48, v52
	v_mov_b32_e32 v44, v47
	v_pk_mul_f32 v[52:53], v[52:53], v[46:47]
	v_pk_fma_f32 v[44:45], v[48:49], v[46:47], v[44:45]
	v_pk_mul_f32 v[50:51], v[52:53], v[50:51]
	s_nop 0
	v_mov_b32_e32 v51, v45
	ds_write_b64 v142, v[50:51] offset:53248
; template <bool PASS_C>
; DEVI void lru_item(const P& p, int item, int next_item, uint4& u0, uint4& u1, uint4& u2, float& cpre, char* smem) {
;     ...
;         for (int d = 0; d < 2; ++d) {
;             const float ba = prm[(5 + d) * 64 + ch], bx = prm[(7 + d) * 64 + ch], nsp8 = prm[(9 + d) * 64 + ch];
; #pragma unroll
;             for (int j = 0; j < 4; ++j) {
;                 const float r = __builtin_amdgcn_rcpf(1.0f + __builtin_amdgcn_exp2f(__builtin_fmaf(acc[(2 * d) * 4 + nn][j], -LOG2E, ba)));
;                 const float ig = __builtin_amdgcn_rcpf(1.0f + __builtin_amdgcn_exp2f(__builtin_fmaf(acc[(2 * d + 1) * 4 + nn][j], -LOG2E, bx)));
;                 const float a_ = __builtin_amdgcn_exp2f(nsp8 * r);
;                 av[nn][d][j] = a_;
;                 bv[nn][d][j] = __builtin_amdgcn_sqrtf(__builtin_fmaf(-a_, a_, 1.0f)) * ig * uc[j];
;             }
;             float A = 1.f, Bq = 0.f;
;             if (d == 0) {
; #pragma unroll
;                 for (int j = 0; j < 4; ++j) { Bq = av[nn][d][j] * Bq + bv[nn][d][j]; A *= av[nn][d][j]; }
;             } else {
; #pragma unroll
;                 for (int j = 3; j >= 0; --j) { Bq = av[nn][d][j] * Bq + bv[nn][d][j]; A *= av[nn][d][j]; }
;             }
;             float Ag[4], Bg[4];
;             rowgather4(A, Ag); rowgather4(Bq, Bg);
;             float AW = 1.f, BW = 0.f, AP = 1.f, BP = 0.f;
;             if (d == 0) {
; #pragma unroll
;                 for (int g = 0; g < 4; ++g) {
;                     if (g == fq) { AP = AW; BP = BW; }
;                     BW = Ag[g] * BW + Bg[g]; AW *= Ag[g];
;                 }
;             } else {
; #pragma unroll
;                 for (int g = 3; g >= 0; --g) {
;                     if (g == fq) { AP = AW; BP = BW; }
;                     BW = Ag[g] * BW + Bg[g]; AW *= Ag[g];
;                 }
;             }
;             apre[nn][d] = AP; bpre[nn][d] = BP;
;             if (fq == 0) { wagg[((w * 2 + d) * 64 + ch) * 2 + 0] = AW; wagg[((w * 2 + d) * 64 + ch) * 2 + 1] = BW; }
.LBB0_518:
	s_or_b64 exec, exec, s[12:13]
	v_lshlrev_b32_e32 v44, 16, v219
	v_lshlrev_b32_e32 v45, 16, v220
	v_lshlrev_b32_e32 v46, 16, v221
	v_fmamk_f32 v40, v40, 0xbfb8aa3b, v238
	v_exp_f32_e32 v40, v40
	v_fmamk_f32 v41, v41, 0xbfb8aa3b, v238
	v_fmamk_f32 v42, v42, 0xbfb8aa3b, v238
	v_fmamk_f32 v43, v43, 0xbfb8aa3b, v238
	v_add_f32_e32 v40, 1.0, v40
	v_rcp_f32_e32 v40, v40
	v_exp_f32_e32 v41, v41
	v_exp_f32_e32 v42, v42
	v_exp_f32_e32 v43, v43
	v_fmamk_f32 v36, v36, 0xbfb8aa3b, v239
	v_mul_f32_e32 v40, v223, v40
	v_add_f32_e32 v41, 1.0, v41
	v_add_f32_e32 v42, 1.0, v42
	v_add_f32_e32 v43, 1.0, v43
	v_exp_f32_e32 v36, v36
	v_rcp_f32_e32 v41, v41
	v_exp_f32_e32 v40, v40
	v_rcp_f32_e32 v42, v42
	v_rcp_f32_e32 v43, v43
	v_add_f32_e32 v36, 1.0, v36
	v_mul_f32_e32 v41, v223, v41
	v_mul_f32_e32 v42, v223, v42
	v_mul_f32_e32 v43, v223, v43
	v_rcp_f32_e32 v49, v36
	v_fma_f32 v36, -v40, v40, 1.0
	v_sqrt_f32_e32 v52, v36
	v_fmamk_f32 v37, v37, 0xbfb8aa3b, v239
	v_exp_f32_e32 v41, v41
	v_exp_f32_e32 v37, v37
	v_mul_f32_e32 v49, v49, v52
	v_mul_f32_e32 v49, v49, v44
	v_mul_f32_e32 v50, v40, v41
	v_add_f32_e32 v37, 1.0, v37
	v_fma_f32 v40, -v41, v41, 1.0
	v_fmamk_f32 v38, v38, 0xbfb8aa3b, v239
	v_exp_f32_e32 v42, v42
	v_rcp_f32_e32 v37, v37
	v_sqrt_f32_e32 v40, v40
	v_exp_f32_e32 v38, v38
	v_fmamk_f32 v51, v39, 0xbfb8aa3b, v239
	v_exp_f32_e32 v43, v43
	v_exp_f32_e32 v39, v51
	v_mul_f32_e32 v41, v41, v49
	v_mul_f32_e32 v37, v37, v40
	v_add_f32_e32 v38, 1.0, v38
	v_fma_f32 v40, -v42, v42, 1.0
	v_fmac_f32_e32 v41, v37, v45
	v_rcp_f32_e32 v38, v38
	v_sqrt_f32_e32 v40, v40
	v_mul_f32_e32 v37, v42, v41
	v_add_f32_e32 v39, 1.0, v39
	v_fma_f32 v41, -v43, v43, 1.0
	v_rcp_f32_e32 v39, v39
	v_sqrt_f32_e32 v41, v41
	v_mul_f32_e32 v38, v38, v40
	v_fmac_f32_e32 v37, v38, v46
	v_lshlrev_b32_e32 v47, 16, v222
	v_mul_f32_e32 v50, v42, v50
	v_mul_f32_e32 v37, v43, v37
	v_mul_f32_e32 v38, v39, v41
	v_mul_f32_e32 v36, v43, v50
	v_fmac_f32_e32 v37, v38, v47
	v_mov_b32_e32 v40, v36
	v_mov_b32_e32 v42, v37
	s_nop 0
	v_permlane16_swap_b32_e32 v36, v40
	v_permlane16_swap_b32_e32 v37, v42
	v_mov_b32_e32 v38, v36
	v_mov_b32_e32 v39, v40
	v_mov_b32_e32 v41, v37
	v_mov_b32_e32 v43, v42
	v_permlane32_swap_b32_e32 v36, v38
	v_permlane32_swap_b32_e32 v40, v39
	v_permlane32_swap_b32_e32 v37, v41
	v_permlane32_swap_b32_e32 v42, v43
	s_and_saveexec_b64 s[12:13], s[8:9]
	s_cbranch_execz .LBB0_520
	v_fmac_f32_e32 v42, v37, v40
	v_mul_f32_e32 v37, v42, v38
	v_pk_mul_f32 v[50:51], v[36:37], v[40:41]
	v_pk_add_f32 v[36:37], v[36:37], v[40:41]
	v_mov_b32_e32 v40, v39
	v_mov_b32_e32 v36, v50
	v_mov_b32_e32 v42, v39
	v_pk_mul_f32 v[50:51], v[50:51], v[38:39]
	v_pk_fma_f32 v[36:37], v[36:37], v[38:39], v[42:43]
	v_pk_mul_f32 v[40:41], v[50:51], v[40:41]
	s_nop 0
	v_mov_b32_e32 v41, v37
	ds_write_b64 v143, v[40:41] offset:52736
.LBB0_520:
	s_or_b64 exec, exec, s[12:13]
	v_fmamk_f32 v35, v35, 0xbfb8aa3b, v240
	v_exp_f32_e32 v35, v35
	v_fmamk_f32 v34, v34, 0xbfb8aa3b, v240
	v_exp_f32_e32 v34, v34
	v_fmamk_f32 v33, v33, 0xbfb8aa3b, v240
	v_exp_f32_e32 v33, v33
	v_add_f32_e32 v35, 1.0, v35
	v_fmamk_f32 v32, v32, 0xbfb8aa3b, v240
	v_rcp_f32_e32 v35, v35
	v_exp_f32_e32 v32, v32
	v_add_f32_e32 v34, 1.0, v34
	v_rcp_f32_e32 v34, v34
	v_add_f32_e32 v33, 1.0, v33
	v_fmamk_f32 v31, v31, 0xbfb8aa3b, v241
	v_mul_f32_e32 v35, v224, v35
	v_rcp_f32_e32 v33, v33
	v_add_f32_e32 v32, 1.0, v32
	v_exp_f32_e32 v31, v31
	v_exp_f32_e32 v35, v35
	v_rcp_f32_e32 v32, v32
	v_mul_f32_e32 v34, v224, v34
	v_exp_f32_e32 v34, v34
	v_mul_f32_e32 v33, v224, v33
	v_add_f32_e32 v31, 1.0, v31
	v_exp_f32_e32 v33, v33
	v_mul_f32_e32 v32, v224, v32
	v_rcp_f32_e32 v38, v31
	v_fma_f32 v31, -v35, v35, 1.0
	v_exp_f32_e32 v32, v32
	v_sqrt_f32_e32 v39, v31
	v_fmamk_f32 v30, v30, 0xbfb8aa3b, v241
	v_mul_f32_e32 v36, v35, v34
	v_exp_f32_e32 v30, v30
	v_mul_f32_e32 v36, v33, v36
	v_mul_f32_e32 v31, v32, v36
	v_mul_f32_e32 v36, v38, v39
	v_mul_f32_e32 v36, v36, v47
	v_add_f32_e32 v30, 1.0, v30
	v_fma_f32 v35, -v34, v34, 1.0
	v_rcp_f32_e32 v30, v30
	v_sqrt_f32_e32 v35, v35
	v_fmamk_f32 v29, v29, 0xbfb8aa3b, v241
	v_exp_f32_e32 v29, v29
	v_fmamk_f32 v37, v28, 0xbfb8aa3b, v241
	v_mul_f32_e32 v34, v34, v36
	v_mul_f32_e32 v30, v30, v35
	v_exp_f32_e32 v28, v37
	v_fmac_f32_e32 v34, v30, v46
	v_mul_f32_e32 v30, v33, v34
	v_add_f32_e32 v29, 1.0, v29
	v_fma_f32 v33, -v33, v33, 1.0
	v_rcp_f32_e32 v29, v29
	v_sqrt_f32_e32 v33, v33
	v_add_f32_e32 v28, 1.0, v28
	v_fma_f32 v34, -v32, v32, 1.0
	v_rcp_f32_e32 v28, v28
	v_sqrt_f32_e32 v34, v34
	v_mul_f32_e32 v29, v29, v33
	v_fmac_f32_e32 v30, v29, v45
	v_mul_f32_e32 v29, v32, v30
	v_mul_f32_e32 v28, v28, v34
	v_fmac_f32_e32 v29, v28, v44
	v_mov_b32_e32 v30, v31
	v_mov_b32_e32 v35, v29
	s_nop 0
	v_permlane16_swap_b32_e32 v31, v30
	v_permlane16_swap_b32_e32 v29, v35
	v_mov_b32_e32 v32, v31
	v_mov_b32_e32 v34, v30
	v_mov_b32_e32 v28, v29
	v_mov_b32_e32 v33, v35
	v_permlane32_swap_b32_e32 v31, v32
	v_permlane32_swap_b32_e32 v30, v34
	v_permlane32_swap_b32_e32 v29, v28
	v_permlane32_swap_b32_e32 v35, v33
	s_and_saveexec_b64 s[12:13], s[8:9]
	s_cbranch_execz .LBB0_522
	v_fmac_f32_e32 v28, v33, v32
	v_mul_f32_e32 v33, v28, v30
	v_pk_mul_f32 v[36:37], v[32:33], v[34:35]
	v_pk_add_f32 v[32:33], v[32:33], v[34:35]
	v_mov_b32_e32 v34, v31
	v_mov_b32_e32 v32, v36
	v_mov_b32_e32 v28, v31
	v_pk_mul_f32 v[36:37], v[36:37], v[30:31]
	v_pk_fma_f32 v[28:29], v[32:33], v[30:31], v[28:29]
	v_pk_mul_f32 v[34:35], v[36:37], v[34:35]
	s_nop 0
	v_mov_b32_e32 v35, v29
	ds_write_b64 v143, v[34:35] offset:53248
; template <bool PASS_C>
; DEVI void lru_item(const P& p, int item, int next_item, uint4& u0, uint4& u1, uint4& u2, float& cpre, char* smem) {
;     ...
;         for (int d = 0; d < 2; ++d) {
;             const float ba = prm[(5 + d) * 64 + ch], bx = prm[(7 + d) * 64 + ch], nsp8 = prm[(9 + d) * 64 + ch];
; #pragma unroll
;             for (int j = 0; j < 4; ++j) {
;                 const float r = __builtin_amdgcn_rcpf(1.0f + __builtin_amdgcn_exp2f(__builtin_fmaf(acc[(2 * d) * 4 + nn][j], -LOG2E, ba)));
;                 const float ig = __builtin_amdgcn_rcpf(1.0f + __builtin_amdgcn_exp2f(__builtin_fmaf(acc[(2 * d + 1) * 4 + nn][j], -LOG2E, bx)));
;                 const float a_ = __builtin_amdgcn_exp2f(nsp8 * r);
;                 av[nn][d][j] = a_;
;                 bv[nn][d][j] = __builtin_amdgcn_sqrtf(__builtin_fmaf(-a_, a_, 1.0f)) * ig * uc[j];
;             }
;             float A = 1.f, Bq = 0.f;
;             if (d == 0) {
; #pragma unroll
;                 for (int j = 0; j < 4; ++j) { Bq = av[nn][d][j] * Bq + bv[nn][d][j]; A *= av[nn][d][j]; }
;             } else {
; #pragma unroll
;                 for (int j = 3; j >= 0; --j) { Bq = av[nn][d][j] * Bq + bv[nn][d][j]; A *= av[nn][d][j]; }
;             }
;             float Ag[4], Bg[4];
;             rowgather4(A, Ag); rowgather4(Bq, Bg);
;             float AW = 1.f, BW = 0.f, AP = 1.f, BP = 0.f;
;             if (d == 0) {
; #pragma unroll
;                 for (int g = 0; g < 4; ++g) {
;                     if (g == fq) { AP = AW; BP = BW; }
;                     BW = Ag[g] * BW + Bg[g]; AW *= Ag[g];
;                 }
;             } else {
; #pragma unroll
;                 for (int g = 3; g >= 0; --g) {
;                     if (g == fq) { AP = AW; BP = BW; }
;                     BW = Ag[g] * BW + Bg[g]; AW *= Ag[g];
;                 }
;             }
;             apre[nn][d] = AP; bpre[nn][d] = BP;
;             if (fq == 0) { wagg[((w * 2 + d) * 64 + ch) * 2 + 0] = AW; wagg[((w * 2 + d) * 64 + ch) * 2 + 1] = BW; }
.LBB0_522:
	s_or_b64 exec, exec, s[12:13]
	v_lshlrev_b32_e32 v28, 16, v225
	v_lshlrev_b32_e32 v29, 16, v226
	v_lshlrev_b32_e32 v30, 16, v227
	v_fmamk_f32 v24, v24, 0xbfb8aa3b, v242
	v_exp_f32_e32 v24, v24
	v_fmamk_f32 v25, v25, 0xbfb8aa3b, v242
	v_fmamk_f32 v26, v26, 0xbfb8aa3b, v242
	v_fmamk_f32 v27, v27, 0xbfb8aa3b, v242
	v_add_f32_e32 v24, 1.0, v24
	v_rcp_f32_e32 v24, v24
	v_exp_f32_e32 v25, v25
	v_exp_f32_e32 v26, v26
	v_exp_f32_e32 v27, v27
	v_fmamk_f32 v20, v20, 0xbfb8aa3b, v243
	v_mul_f32_e32 v24, v229, v24
	v_add_f32_e32 v25, 1.0, v25
	v_add_f32_e32 v26, 1.0, v26
	v_add_f32_e32 v27, 1.0, v27
	v_exp_f32_e32 v20, v20
	v_rcp_f32_e32 v25, v25
	v_exp_f32_e32 v24, v24
	v_rcp_f32_e32 v26, v26
	v_rcp_f32_e32 v27, v27
	v_add_f32_e32 v20, 1.0, v20
	v_mul_f32_e32 v25, v229, v25
	v_mul_f32_e32 v26, v229, v26
	v_mul_f32_e32 v27, v229, v27
	v_rcp_f32_e32 v33, v20
	v_fma_f32 v20, -v24, v24, 1.0
	v_sqrt_f32_e32 v36, v20
	v_fmamk_f32 v21, v21, 0xbfb8aa3b, v243
	v_exp_f32_e32 v25, v25
	v_exp_f32_e32 v21, v21
	v_mul_f32_e32 v33, v33, v36
	v_mul_f32_e32 v33, v33, v28
	v_mul_f32_e32 v34, v24, v25
	v_add_f32_e32 v21, 1.0, v21
	v_fma_f32 v24, -v25, v25, 1.0
	v_fmamk_f32 v22, v22, 0xbfb8aa3b, v243
	v_exp_f32_e32 v26, v26
	v_rcp_f32_e32 v21, v21
	v_sqrt_f32_e32 v24, v24
	v_exp_f32_e32 v22, v22
	v_fmamk_f32 v35, v23, 0xbfb8aa3b, v243
	v_exp_f32_e32 v27, v27
	v_exp_f32_e32 v23, v35
	v_mul_f32_e32 v25, v25, v33
	v_mul_f32_e32 v21, v21, v24
	v_add_f32_e32 v22, 1.0, v22
	v_fma_f32 v24, -v26, v26, 1.0
	v_fmac_f32_e32 v25, v21, v29
	v_rcp_f32_e32 v22, v22
	v_sqrt_f32_e32 v24, v24
	v_mul_f32_e32 v21, v26, v25
	v_add_f32_e32 v23, 1.0, v23
	v_fma_f32 v25, -v27, v27, 1.0
	v_rcp_f32_e32 v23, v23
	v_sqrt_f32_e32 v25, v25
	v_mul_f32_e32 v22, v22, v24
	v_fmac_f32_e32 v21, v22, v30
	v_lshlrev_b32_e32 v31, 16, v228
	v_mul_f32_e32 v34, v26, v34
	v_mul_f32_e32 v21, v27, v21
	v_mul_f32_e32 v22, v23, v25
	v_mul_f32_e32 v20, v27, v34
	v_fmac_f32_e32 v21, v22, v31
	v_mov_b32_e32 v24, v20
	v_mov_b32_e32 v26, v21
	s_nop 0
	v_permlane16_swap_b32_e32 v20, v24
	v_permlane16_swap_b32_e32 v21, v26
	v_mov_b32_e32 v22, v20
	v_mov_b32_e32 v23, v24
	v_mov_b32_e32 v25, v21
	v_mov_b32_e32 v27, v26
	v_permlane32_swap_b32_e32 v20, v22
	v_permlane32_swap_b32_e32 v24, v23
	v_permlane32_swap_b32_e32 v21, v25
	v_permlane32_swap_b32_e32 v26, v27
	s_and_saveexec_b64 s[12:13], s[8:9]
	s_cbranch_execz .LBB0_524
	v_fmac_f32_e32 v26, v21, v24
	v_mul_f32_e32 v21, v26, v22
	v_pk_mul_f32 v[34:35], v[20:21], v[24:25]
	v_pk_add_f32 v[20:21], v[20:21], v[24:25]
	v_mov_b32_e32 v24, v23
	v_mov_b32_e32 v20, v34
	v_mov_b32_e32 v26, v23
	v_pk_mul_f32 v[34:35], v[34:35], v[22:23]
	v_pk_fma_f32 v[20:21], v[20:21], v[22:23], v[26:27]
	v_pk_mul_f32 v[24:25], v[34:35], v[24:25]
	s_nop 0
	v_mov_b32_e32 v25, v21
	ds_write_b64 v144, v[24:25] offset:52736
.LBB0_524:
	s_or_b64 exec, exec, s[12:13]
	v_fmamk_f32 v19, v19, 0xbfb8aa3b, v244
	v_exp_f32_e32 v19, v19
	v_fmamk_f32 v18, v18, 0xbfb8aa3b, v244
	v_exp_f32_e32 v18, v18
	v_fmamk_f32 v17, v17, 0xbfb8aa3b, v244
	v_exp_f32_e32 v17, v17
	v_add_f32_e32 v19, 1.0, v19
	v_fmamk_f32 v16, v16, 0xbfb8aa3b, v244
	v_rcp_f32_e32 v19, v19
	v_exp_f32_e32 v16, v16
	v_add_f32_e32 v18, 1.0, v18
	v_rcp_f32_e32 v18, v18
	v_add_f32_e32 v17, 1.0, v17
	v_fmamk_f32 v15, v15, 0xbfb8aa3b, v245
	v_mul_f32_e32 v19, v231, v19
	v_rcp_f32_e32 v17, v17
	v_add_f32_e32 v16, 1.0, v16
	v_exp_f32_e32 v15, v15
	v_exp_f32_e32 v19, v19
	v_rcp_f32_e32 v16, v16
	v_mul_f32_e32 v18, v231, v18
	v_exp_f32_e32 v18, v18
	v_mul_f32_e32 v17, v231, v17
	v_add_f32_e32 v15, 1.0, v15
	v_exp_f32_e32 v17, v17
	v_mul_f32_e32 v16, v231, v16
	v_rcp_f32_e32 v22, v15
	v_fma_f32 v15, -v19, v19, 1.0
	v_exp_f32_e32 v16, v16
	v_sqrt_f32_e32 v23, v15
	v_fmamk_f32 v14, v14, 0xbfb8aa3b, v245
	v_mul_f32_e32 v20, v19, v18
	v_exp_f32_e32 v14, v14
	v_mul_f32_e32 v20, v17, v20
	v_mul_f32_e32 v15, v16, v20
	v_mul_f32_e32 v20, v22, v23
	v_mul_f32_e32 v20, v20, v31
	v_add_f32_e32 v14, 1.0, v14
	v_fma_f32 v19, -v18, v18, 1.0
	v_rcp_f32_e32 v14, v14
	v_sqrt_f32_e32 v19, v19
	v_fmamk_f32 v13, v13, 0xbfb8aa3b, v245
	v_exp_f32_e32 v13, v13
	v_fmamk_f32 v21, v12, 0xbfb8aa3b, v245
	v_mul_f32_e32 v18, v18, v20
	v_mul_f32_e32 v14, v14, v19
	v_exp_f32_e32 v12, v21
	v_fmac_f32_e32 v18, v14, v30
	v_mul_f32_e32 v14, v17, v18
	v_add_f32_e32 v13, 1.0, v13
	v_fma_f32 v17, -v17, v17, 1.0
	v_rcp_f32_e32 v13, v13
	v_sqrt_f32_e32 v17, v17
	v_add_f32_e32 v12, 1.0, v12
	v_fma_f32 v18, -v16, v16, 1.0
	v_rcp_f32_e32 v12, v12
	v_sqrt_f32_e32 v18, v18
	v_mul_f32_e32 v13, v13, v17
	v_fmac_f32_e32 v14, v13, v29
	v_mul_f32_e32 v13, v16, v14
	v_mul_f32_e32 v12, v12, v18
	v_fmac_f32_e32 v13, v12, v28
	v_mov_b32_e32 v14, v15
	v_mov_b32_e32 v19, v13
	s_nop 0
	v_permlane16_swap_b32_e32 v15, v14
	v_permlane16_swap_b32_e32 v13, v19
	v_mov_b32_e32 v16, v15
	v_mov_b32_e32 v18, v14
	v_mov_b32_e32 v12, v13
	v_mov_b32_e32 v17, v19
	v_permlane32_swap_b32_e32 v15, v16
	v_permlane32_swap_b32_e32 v14, v18
	v_permlane32_swap_b32_e32 v13, v12
	v_permlane32_swap_b32_e32 v19, v17
	s_and_saveexec_b64 s[12:13], s[8:9]
	s_cbranch_execz .LBB0_526
	v_fmac_f32_e32 v12, v17, v16
	v_mul_f32_e32 v17, v12, v14
	v_pk_mul_f32 v[20:21], v[16:17], v[18:19]
	v_pk_add_f32 v[16:17], v[16:17], v[18:19]
	v_mov_b32_e32 v18, v15
	v_mov_b32_e32 v16, v20
	v_mov_b32_e32 v12, v15
	v_pk_mul_f32 v[20:21], v[20:21], v[14:15]
	v_pk_fma_f32 v[12:13], v[16:17], v[14:15], v[12:13]
	v_pk_mul_f32 v[18:19], v[20:21], v[18:19]
	s_nop 0
	v_mov_b32_e32 v19, v13
	ds_write_b64 v144, v[18:19] offset:53248

; DEVI void lru_carry_item(const P& p, int it) {
;     const int gid = it * 256 + threadIdx.x, b = gid >> 11, d = (gid >> 10) & 1, ch = gid & 1023;
;     const float2* ab = (const float2*)(p.ws + OFF_AGG) + (size_t)(b * NCH) * 2048 + d * 1024 + ch;
;     float* cin = (float*)(p.ws + OFF_CIN) + (size_t)(b * NCH) * 2048 + d * 1024 + ch;
;     float hh = 0.f;
;     for (int s0 = 0; s0 < NCH; s0 += 17) {
;         float2 v[17];
; #pragma unroll
;         for (int u_ = 0; u_ < 17; ++u_) { const int i = s0 + u_; const int cc = d == 0 ? i : (i < 4 ? 3 - i : 71 - i); v[u_] = ab[(size_t)cc * 2048]; }
; #pragma unroll
;         for (int u_ = 0; u_ < 17; ++u_) { const int i = s0 + u_; const int cc = d == 0 ? i : (i < 4 ? 3 - i : 71 - i); cin[(size_t)cc * 2048] = hh; hh = v[u_].x * hh + v[u_].y; }
;     }
.LBB0_653:
	v_ashrrev_i32_e32 v0, 11, v18
	v_mul_i32_i24_e32 v14, 0x44, v0
	v_ashrrev_i32_e32 v15, 31, v14
	v_bfe_u32 v4, v18, 10, 1
	v_lshlrev_b64 v[16:17], 14, v[14:15]
	v_and_b32_e32 v2, 0x3ff, v18
	v_lshlrev_b32_e32 v0, 13, v4
	v_lshl_add_u64 v[16:17], s[0:1], 0, v[16:17]
	v_lshlrev_b64 v[14:15], 13, v[14:15]
	v_lshl_add_u64 v[16:17], v[16:17], 0, v[0:1]
	v_lshlrev_b32_e32 v0, 3, v2
	v_bfe_i32 v6, v18, 10, 1
	v_lshl_add_u64 v[14:15], s[2:3], 0, v[14:15]
	v_lshl_add_u64 v[16:17], v[16:17], 0, v[0:1]
	v_lshlrev_b32_e32 v0, 12, v4
	v_and_b32_e32 v70, 3, v6
	v_lshl_add_u64 v[14:15], v[14:15], 0, v[0:1]
	v_lshlrev_b32_e32 v0, 2, v2
	v_add_u32_e32 v72, 1, v4
	v_lshl_add_u64 v[14:15], v[14:15], 0, v[0:1]
	v_lshlrev_b32_e32 v0, 14, v70
	v_sub_u32_e32 v73, 2, v4
	v_cmp_eq_u32_e32 vcc, 0, v4
	v_lshl_add_u64 v[36:37], v[16:17], 0, v[0:1]
	v_lshlrev_b32_e32 v0, 14, v72
	v_cndmask_b32_e64 v74, 0, 3, vcc
	v_lshl_add_u64 v[38:39], v[16:17], 0, v[0:1]
	v_lshlrev_b32_e32 v0, 14, v73
	v_cndmask_b32_e64 v76, v19, 4, vcc
	global_load_dwordx2 v[36:37], v[36:37], off
	s_nop 0
	global_load_dwordx2 v[38:39], v[38:39], off
	v_lshl_add_u64 v[40:41], v[16:17], 0, v[0:1]
	v_lshlrev_b32_e32 v0, 14, v74
	v_cndmask_b32_e64 v78, v20, 5, vcc
	v_lshl_add_u64 v[42:43], v[16:17], 0, v[0:1]
	v_lshlrev_b32_e32 v0, 14, v76
	v_cndmask_b32_e64 v80, v21, 6, vcc
	global_load_dwordx2 v[40:41], v[40:41], off
	s_nop 0
	global_load_dwordx2 v[42:43], v[42:43], off
	v_lshl_add_u64 v[44:45], v[16:17], 0, v[0:1]
	v_lshlrev_b32_e32 v0, 14, v78
	v_cndmask_b32_e64 v82, 64, 7, vcc
	v_lshl_add_u64 v[46:47], v[16:17], 0, v[0:1]
	v_lshlrev_b32_e32 v0, 14, v80
	v_cndmask_b32_e64 v84, 63, 8, vcc
	global_load_dwordx2 v[44:45], v[44:45], off
	s_nop 0
	global_load_dwordx2 v[46:47], v[46:47], off
	v_lshl_add_u64 v[48:49], v[16:17], 0, v[0:1]
	v_lshlrev_b32_e32 v0, 14, v82
	v_cndmask_b32_e64 v86, 62, 9, vcc
	v_lshl_add_u64 v[50:51], v[16:17], 0, v[0:1]
	v_lshlrev_b32_e32 v0, 14, v84
	v_cndmask_b32_e64 v88, 61, 10, vcc
	global_load_dwordx2 v[48:49], v[48:49], off
	s_nop 0
	global_load_dwordx2 v[50:51], v[50:51], off
	v_lshl_add_u64 v[52:53], v[16:17], 0, v[0:1]
	v_lshlrev_b32_e32 v0, 14, v86
	v_cndmask_b32_e64 v90, 60, 11, vcc
	v_lshl_add_u64 v[54:55], v[16:17], 0, v[0:1]
	v_lshlrev_b32_e32 v0, 14, v88
	v_cndmask_b32_e64 v92, 59, 12, vcc
	global_load_dwordx2 v[52:53], v[52:53], off
	s_nop 0
	global_load_dwordx2 v[54:55], v[54:55], off
	v_lshl_add_u64 v[56:57], v[16:17], 0, v[0:1]
	v_lshlrev_b32_e32 v0, 14, v90
	v_cndmask_b32_e64 v94, 58, 13, vcc
	v_lshl_add_u64 v[58:59], v[16:17], 0, v[0:1]
	v_lshlrev_b32_e32 v0, 14, v92
	v_cndmask_b32_e64 v96, 57, 14, vcc
	global_load_dwordx2 v[56:57], v[56:57], off
	s_nop 0
	global_load_dwordx2 v[58:59], v[58:59], off
	v_lshl_add_u64 v[60:61], v[16:17], 0, v[0:1]
	v_lshlrev_b32_e32 v0, 14, v94
	v_cndmask_b32_e64 v98, 56, 15, vcc
	v_lshl_add_u64 v[62:63], v[16:17], 0, v[0:1]
	v_lshlrev_b32_e32 v0, 14, v96
	global_load_dwordx2 v[60:61], v[60:61], off
	s_nop 0
	global_load_dwordx2 v[62:63], v[62:63], off
	v_lshl_add_u64 v[64:65], v[16:17], 0, v[0:1]
	v_lshlrev_b32_e32 v0, 14, v98
	v_lshl_add_u64 v[66:67], v[16:17], 0, v[0:1]
	global_load_dwordx2 v[64:65], v[64:65], off
	s_nop 0
	global_load_dwordx2 v[66:67], v[66:67], off
	v_cndmask_b32_e64 v100, 55, 16, vcc
	v_lshlrev_b32_e32 v0, 14, v100
	v_lshl_add_u64 v[68:69], v[16:17], 0, v[0:1]
	v_lshlrev_b32_e32 v0, 13, v70
	v_lshl_add_u64 v[70:71], v[14:15], 0, v[0:1]
	v_lshlrev_b32_e32 v0, 13, v72
	global_load_dwordx2 v[68:69], v[68:69], off
	v_cndmask_b32_e64 v136, 54, 17, vcc
	global_store_dword v[70:71], v1, off
	v_lshl_add_u64 v[70:71], v[14:15], 0, v[0:1]
	v_lshlrev_b32_e32 v0, 13, v73
	v_lshl_add_u64 v[72:73], v[14:15], 0, v[0:1]
	v_lshlrev_b32_e32 v0, 13, v74
	v_lshl_add_u64 v[74:75], v[14:15], 0, v[0:1]
	v_lshlrev_b32_e32 v0, 13, v76
	v_lshl_add_u64 v[76:77], v[14:15], 0, v[0:1]
	v_lshlrev_b32_e32 v0, 13, v78
	v_lshl_add_u64 v[78:79], v[14:15], 0, v[0:1]
	v_lshlrev_b32_e32 v0, 13, v80
	v_lshl_add_u64 v[80:81], v[14:15], 0, v[0:1]
	v_lshlrev_b32_e32 v0, 13, v82
	v_lshl_add_u64 v[82:83], v[14:15], 0, v[0:1]
	v_lshlrev_b32_e32 v0, 13, v84
	v_lshl_add_u64 v[84:85], v[14:15], 0, v[0:1]
	v_lshlrev_b32_e32 v0, 13, v86
	v_lshl_add_u64 v[86:87], v[14:15], 0, v[0:1]
	v_lshlrev_b32_e32 v0, 13, v88
	v_lshl_add_u64 v[88:89], v[14:15], 0, v[0:1]
	v_lshlrev_b32_e32 v0, 13, v90
	v_lshl_add_u64 v[90:91], v[14:15], 0, v[0:1]
	v_lshlrev_b32_e32 v0, 13, v92
	v_lshl_add_u64 v[92:93], v[14:15], 0, v[0:1]
	v_lshlrev_b32_e32 v0, 13, v94
	v_lshl_add_u64 v[94:95], v[14:15], 0, v[0:1]
	v_lshlrev_b32_e32 v0, 13, v96
	v_lshl_add_u64 v[96:97], v[14:15], 0, v[0:1]
	v_lshlrev_b32_e32 v0, 13, v98
	v_lshl_add_u64 v[98:99], v[14:15], 0, v[0:1]
	v_lshlrev_b32_e32 v0, 13, v100
	s_waitcnt vmcnt(17)
	v_cndmask_b32_e64 v138, 53, 18, vcc
	v_lshl_add_u64 v[100:101], v[14:15], 0, v[0:1]
	v_lshlrev_b32_e32 v0, 14, v136
	s_waitcnt vmcnt(16)
	v_fmac_f32_e32 v39, v37, v38
	v_cndmask_b32_e64 v140, 52, 19, vcc
	v_lshl_add_u64 v[102:103], v[16:17], 0, v[0:1]
	v_lshlrev_b32_e32 v0, 14, v138
	s_waitcnt vmcnt(15)
	v_fmac_f32_e32 v41, v39, v40
	v_cndmask_b32_e64 v142, 51, 20, vcc
	v_lshl_add_u64 v[104:105], v[16:17], 0, v[0:1]
	v_lshlrev_b32_e32 v0, 14, v140
	s_waitcnt vmcnt(14)
	v_fmac_f32_e32 v43, v41, v42
	v_cndmask_b32_e64 v144, 50, 21, vcc
	v_lshl_add_u64 v[106:107], v[16:17], 0, v[0:1]
	v_lshlrev_b32_e32 v0, 14, v142
	s_waitcnt vmcnt(13)
	v_fmac_f32_e32 v45, v43, v44
	v_cndmask_b32_e64 v146, 49, 22, vcc
	v_lshl_add_u64 v[108:109], v[16:17], 0, v[0:1]
	v_lshlrev_b32_e32 v0, 14, v144
	s_waitcnt vmcnt(12)
; DEVI void lru_carry_item(const P& p, int it) {
;     ...
;     for (int s0 = 0; s0 < NCH; s0 += 17) {
;         float2 v[17];
; #pragma unroll
;         for (int u_ = 0; u_ < 17; ++u_) { const int i = s0 + u_; const int cc = d == 0 ? i : (i < 4 ? 3 - i : 71 - i); v[u_] = ab[(size_t)cc * 2048]; }
; #pragma unroll
;         for (int u_ = 0; u_ < 17; ++u_) { const int i = s0 + u_; const int cc = d == 0 ? i : (i < 4 ? 3 - i : 71 - i); cin[(size_t)cc * 2048] = hh; hh = v[u_].x * hh + v[u_].y; }
;     }
	v_fmac_f32_e32 v47, v45, v46
	v_cndmask_b32_e64 v148, 48, 23, vcc
	v_lshl_add_u64 v[110:111], v[16:17], 0, v[0:1]
	v_lshlrev_b32_e32 v0, 14, v146
	s_waitcnt vmcnt(11)
	v_fmac_f32_e32 v49, v47, v48
	v_cndmask_b32_e64 v150, 47, 24, vcc
	v_lshl_add_u64 v[112:113], v[16:17], 0, v[0:1]
	v_lshlrev_b32_e32 v0, 14, v148
	s_waitcnt vmcnt(10)
	v_fmac_f32_e32 v51, v49, v50
	v_cndmask_b32_e64 v152, 46, 25, vcc
	v_lshl_add_u64 v[114:115], v[16:17], 0, v[0:1]
	v_lshlrev_b32_e32 v0, 14, v150
	s_waitcnt vmcnt(9)
	v_fmac_f32_e32 v53, v51, v52
	v_cndmask_b32_e64 v154, 45, 26, vcc
	v_lshl_add_u64 v[116:117], v[16:17], 0, v[0:1]
	v_lshlrev_b32_e32 v0, 14, v152
	s_waitcnt vmcnt(8)
	v_fmac_f32_e32 v55, v53, v54
	v_cndmask_b32_e64 v156, 44, 27, vcc
	v_lshl_add_u64 v[118:119], v[16:17], 0, v[0:1]
	v_lshlrev_b32_e32 v0, 14, v154
	s_waitcnt vmcnt(7)
	v_fmac_f32_e32 v57, v55, v56
	v_cndmask_b32_e64 v158, 43, 28, vcc
	v_lshl_add_u64 v[120:121], v[16:17], 0, v[0:1]
	v_lshlrev_b32_e32 v0, 14, v156
	s_waitcnt vmcnt(6)
	v_fmac_f32_e32 v59, v57, v58
	v_cndmask_b32_e64 v160, 42, 29, vcc
	v_lshl_add_u64 v[122:123], v[16:17], 0, v[0:1]
	v_lshlrev_b32_e32 v0, 14, v158
	s_waitcnt vmcnt(5)
	v_fmac_f32_e32 v61, v59, v60
	v_cndmask_b32_e64 v162, 41, 30, vcc
	v_lshl_add_u64 v[124:125], v[16:17], 0, v[0:1]
	v_lshlrev_b32_e32 v0, 14, v160
	s_waitcnt vmcnt(4)
	v_fmac_f32_e32 v63, v61, v62
	v_cndmask_b32_e64 v164, 40, 31, vcc
	v_lshl_add_u64 v[126:127], v[16:17], 0, v[0:1]
	v_lshlrev_b32_e32 v0, 14, v162
	s_waitcnt vmcnt(3)
	v_fmac_f32_e32 v65, v63, v64
	v_cndmask_b32_e64 v166, 39, 32, vcc
	v_lshl_add_u64 v[128:129], v[16:17], 0, v[0:1]
	v_lshlrev_b32_e32 v0, 14, v164
	s_waitcnt vmcnt(2)
	v_fmac_f32_e32 v67, v65, v66
	v_lshl_add_u64 v[130:131], v[16:17], 0, v[0:1]
	v_lshlrev_b32_e32 v0, 14, v166
	global_store_dword v[70:71], v37, off
	global_store_dword v[72:73], v39, off
	global_store_dword v[74:75], v41, off
	global_store_dword v[76:77], v43, off
	global_store_dword v[78:79], v45, off
	global_store_dword v[80:81], v47, off
	global_store_dword v[82:83], v49, off
	global_store_dword v[84:85], v51, off
	global_store_dword v[86:87], v53, off
	global_store_dword v[88:89], v55, off
	global_store_dword v[90:91], v57, off
	global_store_dword v[92:93], v59, off
	global_store_dword v[94:95], v61, off
	global_store_dword v[96:97], v63, off
	global_store_dword v[98:99], v65, off
	global_store_dword v[100:101], v67, off
	v_lshl_add_u64 v[132:133], v[16:17], 0, v[0:1]
	global_load_dwordx2 v[60:61], v[102:103], off
	global_load_dwordx2 v[62:63], v[104:105], off
	global_load_dwordx2 v[64:65], v[106:107], off
	global_load_dwordx2 v[70:71], v[108:109], off
	global_load_dwordx2 v[72:73], v[110:111], off
	global_load_dwordx2 v[74:75], v[112:113], off
	global_load_dwordx2 v[76:77], v[114:115], off
	global_load_dwordx2 v[78:79], v[116:117], off
	global_load_dwordx2 v[80:81], v[118:119], off
	global_load_dwordx2 v[82:83], v[120:121], off
	global_load_dwordx2 v[84:85], v[122:123], off
	global_load_dwordx2 v[86:87], v[124:125], off
	global_load_dwordx2 v[88:89], v[126:127], off
	global_load_dwordx2 v[90:91], v[128:129], off
	global_load_dwordx2 v[92:93], v[130:131], off
	global_load_dwordx2 v[94:95], v[132:133], off
	v_cndmask_b32_e64 v168, 38, 33, vcc
	v_lshlrev_b32_e32 v0, 14, v168
	v_lshl_add_u64 v[134:135], v[16:17], 0, v[0:1]
	v_lshlrev_b32_e32 v0, 13, v136
	v_lshl_add_u64 v[136:137], v[14:15], 0, v[0:1]
	v_lshlrev_b32_e32 v0, 13, v138
	v_lshl_add_u64 v[138:139], v[14:15], 0, v[0:1]
	v_lshlrev_b32_e32 v0, 13, v140
	v_lshl_add_u64 v[140:141], v[14:15], 0, v[0:1]
	v_lshlrev_b32_e32 v0, 13, v142
	v_lshl_add_u64 v[142:143], v[14:15], 0, v[0:1]
	v_lshlrev_b32_e32 v0, 13, v144
	v_lshl_add_u64 v[144:145], v[14:15], 0, v[0:1]
	v_lshlrev_b32_e32 v0, 13, v146
	v_lshl_add_u64 v[146:147], v[14:15], 0, v[0:1]
	v_lshlrev_b32_e32 v0, 13, v148
	v_lshl_add_u64 v[148:149], v[14:15], 0, v[0:1]
	v_lshlrev_b32_e32 v0, 13, v150
	v_lshl_add_u64 v[150:151], v[14:15], 0, v[0:1]
	v_lshlrev_b32_e32 v0, 13, v152
	v_lshl_add_u64 v[152:153], v[14:15], 0, v[0:1]
	v_lshlrev_b32_e32 v0, 13, v154
	v_lshl_add_u64 v[154:155], v[14:15], 0, v[0:1]
	v_lshlrev_b32_e32 v0, 13, v156
	v_lshl_add_u64 v[156:157], v[14:15], 0, v[0:1]
	v_lshlrev_b32_e32 v0, 13, v158
	v_lshl_add_u64 v[158:159], v[14:15], 0, v[0:1]
	v_lshlrev_b32_e32 v0, 13, v160
	v_lshl_add_u64 v[160:161], v[14:15], 0, v[0:1]
	v_lshlrev_b32_e32 v0, 13, v162
	v_lshl_add_u64 v[162:163], v[14:15], 0, v[0:1]
	v_lshlrev_b32_e32 v0, 13, v164
	v_lshl_add_u64 v[164:165], v[14:15], 0, v[0:1]
	v_lshlrev_b32_e32 v0, 13, v166
	v_cndmask_b32_e64 v183, 37, 34, vcc
	v_lshl_add_u64 v[166:167], v[14:15], 0, v[0:1]
	v_lshlrev_b32_e32 v0, 13, v168
	s_waitcnt vmcnt(33)
	v_fmac_f32_e32 v69, v67, v68
	v_add_u32_e32 v173, 35, v4
	v_lshl_add_u64 v[168:169], v[14:15], 0, v[0:1]
	v_lshlrev_b32_e32 v0, 14, v183
	v_sub_u32_e32 v177, 36, v4
	v_lshl_add_u64 v[170:171], v[16:17], 0, v[0:1]
	v_lshlrev_b32_e32 v0, 14, v173
	global_load_dwordx2 v[102:103], v[134:135], off
	v_cndmask_b32_e64 v210, 34, 37, vcc
	v_lshl_add_u64 v[184:185], v[16:17], 0, v[0:1]
	v_lshlrev_b32_e32 v0, 14, v177
	v_cndmask_b32_e64 v211, 33, 38, vcc
	v_lshl_add_u64 v[186:187], v[16:17], 0, v[0:1]
	v_lshlrev_b32_e32 v0, 14, v210
	v_cndmask_b32_e64 v212, 32, 39, vcc
	v_lshl_add_u64 v[188:189], v[16:17], 0, v[0:1]
	v_lshlrev_b32_e32 v0, 14, v211
	v_cndmask_b32_e64 v213, 31, 40, vcc
	v_lshl_add_u64 v[190:191], v[16:17], 0, v[0:1]
	v_lshlrev_b32_e32 v0, 14, v212
	v_cndmask_b32_e64 v214, 30, 41, vcc
	v_lshl_add_u64 v[192:193], v[16:17], 0, v[0:1]
	v_lshlrev_b32_e32 v0, 14, v213
	v_cndmask_b32_e64 v215, 29, 42, vcc
	v_lshl_add_u64 v[194:195], v[16:17], 0, v[0:1]
	v_lshlrev_b32_e32 v0, 14, v214
	v_cndmask_b32_e64 v217, 28, 43, vcc
	s_waitcnt vmcnt(16)
; DEVI void lru_carry_item(const P& p, int it) {
;     ...
;     for (int s0 = 0; s0 < NCH; s0 += 17) {
;         float2 v[17];
; #pragma unroll
;         for (int u_ = 0; u_ < 17; ++u_) { const int i = s0 + u_; const int cc = d == 0 ? i : (i < 4 ? 3 - i : 71 - i); v[u_] = ab[(size_t)cc * 2048]; }
; #pragma unroll
;         for (int u_ = 0; u_ < 17; ++u_) { const int i = s0 + u_; const int cc = d == 0 ? i : (i < 4 ? 3 - i : 71 - i); cin[(size_t)cc * 2048] = hh; hh = v[u_].x * hh + v[u_].y; }
;     }
	v_fmac_f32_e32 v61, v69, v60
	s_waitcnt vmcnt(15)
	v_fmac_f32_e32 v63, v61, v62
	s_waitcnt vmcnt(14)
	v_fmac_f32_e32 v65, v63, v64
	s_waitcnt vmcnt(13)
	v_fmac_f32_e32 v71, v65, v70
	s_waitcnt vmcnt(12)
	v_fmac_f32_e32 v73, v71, v72
	s_waitcnt vmcnt(11)
	v_fmac_f32_e32 v75, v73, v74
	s_waitcnt vmcnt(10)
	v_fmac_f32_e32 v77, v75, v76
	s_waitcnt vmcnt(9)
	v_fmac_f32_e32 v79, v77, v78
	v_lshl_add_u64 v[196:197], v[16:17], 0, v[0:1]
	v_lshlrev_b32_e32 v0, 14, v215
	s_waitcnt vmcnt(8)
	v_fmac_f32_e32 v81, v79, v80
	v_cndmask_b32_e64 v218, 27, 44, vcc
	v_lshl_add_u64 v[198:199], v[16:17], 0, v[0:1]
	v_lshlrev_b32_e32 v0, 14, v217
	s_waitcnt vmcnt(7)
	v_fmac_f32_e32 v83, v81, v82
	v_cndmask_b32_e64 v219, 26, 45, vcc
	v_lshl_add_u64 v[200:201], v[16:17], 0, v[0:1]
	v_lshlrev_b32_e32 v0, 14, v218
	s_waitcnt vmcnt(6)
	v_fmac_f32_e32 v85, v83, v84
	v_cndmask_b32_e64 v220, 25, 46, vcc
	v_lshl_add_u64 v[202:203], v[16:17], 0, v[0:1]
	v_lshlrev_b32_e32 v0, 14, v219
	s_waitcnt vmcnt(5)
	v_fmac_f32_e32 v87, v85, v86
	v_cndmask_b32_e64 v221, 24, 47, vcc
	v_lshl_add_u64 v[204:205], v[16:17], 0, v[0:1]
	v_lshlrev_b32_e32 v0, 14, v220
	s_waitcnt vmcnt(4)
	v_fmac_f32_e32 v89, v87, v88
	v_cndmask_b32_e64 v222, 23, 48, vcc
	v_lshl_add_u64 v[206:207], v[16:17], 0, v[0:1]
	v_lshlrev_b32_e32 v0, 14, v221
	s_waitcnt vmcnt(3)
	v_fmac_f32_e32 v91, v89, v90
	v_cndmask_b32_e64 v223, 22, 49, vcc
	v_lshl_add_u64 v[208:209], v[16:17], 0, v[0:1]
	v_lshlrev_b32_e32 v0, 14, v222
	s_waitcnt vmcnt(2)
	v_fmac_f32_e32 v93, v91, v92
	v_lshl_add_u64 v[36:37], v[16:17], 0, v[0:1]
	v_lshlrev_b32_e32 v0, 14, v223
	s_waitcnt vmcnt(1)
	v_fmac_f32_e32 v95, v93, v94
	v_lshl_add_u64 v[38:39], v[16:17], 0, v[0:1]
	global_store_dword v[136:137], v69, off
	global_store_dword v[138:139], v61, off
	global_store_dword v[140:141], v63, off
	global_store_dword v[142:143], v65, off
	global_store_dword v[144:145], v71, off
	global_store_dword v[146:147], v73, off
	global_store_dword v[148:149], v75, off
	global_store_dword v[150:151], v77, off
	global_store_dword v[152:153], v79, off
	global_store_dword v[154:155], v81, off
	global_store_dword v[156:157], v83, off
	global_store_dword v[158:159], v85, off
	global_store_dword v[160:161], v87, off
	global_store_dword v[162:163], v89, off
	global_store_dword v[164:165], v91, off
	global_store_dword v[166:167], v93, off
	global_store_dword v[168:169], v95, off
	global_load_dwordx2 v[60:61], v[170:171], off
	global_load_dwordx2 v[62:63], v[184:185], off
	global_load_dwordx2 v[64:65], v[186:187], off
	global_load_dwordx2 v[68:69], v[188:189], off
	global_load_dwordx2 v[70:71], v[190:191], off
	global_load_dwordx2 v[72:73], v[192:193], off
	global_load_dwordx2 v[74:75], v[194:195], off
	global_load_dwordx2 v[76:77], v[196:197], off
	global_load_dwordx2 v[78:79], v[198:199], off
	global_load_dwordx2 v[80:81], v[200:201], off
	global_load_dwordx2 v[82:83], v[202:203], off
	global_load_dwordx2 v[84:85], v[204:205], off
	global_load_dwordx2 v[86:87], v[206:207], off
	global_load_dwordx2 v[88:89], v[208:209], off
	s_nop 0
	global_load_dwordx2 v[36:37], v[36:37], off
	s_nop 0
	global_load_dwordx2 v[38:39], v[38:39], off
	v_cndmask_b32_e64 v224, 21, 50, vcc
	v_lshlrev_b32_e32 v0, 14, v224
	v_lshl_add_u64 v[40:41], v[16:17], 0, v[0:1]
	v_lshlrev_b32_e32 v0, 13, v183
	v_lshl_add_u64 v[42:43], v[14:15], 0, v[0:1]
	v_lshlrev_b32_e32 v0, 13, v173
	v_lshl_add_u64 v[44:45], v[14:15], 0, v[0:1]
	v_lshlrev_b32_e32 v0, 13, v177
	v_lshl_add_u64 v[46:47], v[14:15], 0, v[0:1]
	v_lshlrev_b32_e32 v0, 13, v210
	v_lshl_add_u64 v[48:49], v[14:15], 0, v[0:1]
	v_lshlrev_b32_e32 v0, 13, v211
	v_lshl_add_u64 v[50:51], v[14:15], 0, v[0:1]
	v_lshlrev_b32_e32 v0, 13, v212
	v_lshl_add_u64 v[52:53], v[14:15], 0, v[0:1]
	v_lshlrev_b32_e32 v0, 13, v213
	v_lshl_add_u64 v[54:55], v[14:15], 0, v[0:1]
	v_lshlrev_b32_e32 v0, 13, v214
	v_lshl_add_u64 v[56:57], v[14:15], 0, v[0:1]
	v_lshlrev_b32_e32 v0, 13, v215
	v_lshl_add_u64 v[58:59], v[14:15], 0, v[0:1]
	v_lshlrev_b32_e32 v0, 13, v217
	v_lshl_add_u64 v[96:97], v[14:15], 0, v[0:1]
	v_lshlrev_b32_e32 v0, 13, v218
	v_lshl_add_u64 v[98:99], v[14:15], 0, v[0:1]
	v_lshlrev_b32_e32 v0, 13, v219
	v_lshl_add_u64 v[100:101], v[14:15], 0, v[0:1]
	v_lshlrev_b32_e32 v0, 13, v220
	v_lshl_add_u64 v[66:67], v[14:15], 0, v[0:1]
	v_lshlrev_b32_e32 v0, 13, v221
	v_lshl_add_u64 v[104:105], v[14:15], 0, v[0:1]
	v_lshlrev_b32_e32 v0, 13, v222
	v_lshl_add_u64 v[106:107], v[14:15], 0, v[0:1]
	v_lshlrev_b32_e32 v0, 13, v223
	v_cndmask_b32_e64 v6, 20, 51, vcc
	v_lshl_add_u64 v[108:109], v[14:15], 0, v[0:1]
	v_lshlrev_b32_e32 v0, 13, v224
	s_waitcnt vmcnt(33)
	v_fmac_f32_e32 v103, v95, v102
	v_cndmask_b32_e64 v8, 19, 52, vcc
	v_lshl_add_u64 v[110:111], v[14:15], 0, v[0:1]
	v_lshlrev_b32_e32 v0, 14, v6
	v_cndmask_b32_e64 v10, 18, 53, vcc
	v_lshl_add_u64 v[90:91], v[16:17], 0, v[0:1]
	v_lshlrev_b32_e32 v0, 14, v8
	global_load_dwordx2 v[40:41], v[40:41], off
	v_cndmask_b32_e64 v12, 17, 54, vcc
	v_lshl_add_u64 v[92:93], v[16:17], 0, v[0:1]
	v_lshlrev_b32_e32 v0, 14, v10
	v_cndmask_b32_e64 v24, 16, 55, vcc
	v_lshl_add_u64 v[112:113], v[16:17], 0, v[0:1]
	v_lshlrev_b32_e32 v0, 14, v12
	v_cndmask_b32_e64 v25, 15, 56, vcc
	v_lshl_add_u64 v[114:115], v[16:17], 0, v[0:1]
	v_lshlrev_b32_e32 v0, 14, v24
	v_cndmask_b32_e64 v26, 14, 57, vcc
	v_lshl_add_u64 v[116:117], v[16:17], 0, v[0:1]
	v_lshlrev_b32_e32 v0, 14, v25
	v_cndmask_b32_e64 v27, 13, 58, vcc
	v_lshl_add_u64 v[118:119], v[16:17], 0, v[0:1]
	v_lshlrev_b32_e32 v0, 14, v26
	v_cndmask_b32_e64 v28, 12, 59, vcc
	v_lshl_add_u64 v[120:121], v[16:17], 0, v[0:1]
	v_lshlrev_b32_e32 v0, 14, v27
	v_cndmask_b32_e64 v29, 11, 60, vcc
	s_waitcnt vmcnt(16)
; DEVI void lru_carry_item(const P& p, int it) {
;     ...
;     for (int s0 = 0; s0 < NCH; s0 += 17) {
;         float2 v[17];
; #pragma unroll
;         for (int u_ = 0; u_ < 17; ++u_) { const int i = s0 + u_; const int cc = d == 0 ? i : (i < 4 ? 3 - i : 71 - i); v[u_] = ab[(size_t)cc * 2048]; }
; #pragma unroll
;         for (int u_ = 0; u_ < 17; ++u_) { const int i = s0 + u_; const int cc = d == 0 ? i : (i < 4 ? 3 - i : 71 - i); cin[(size_t)cc * 2048] = hh; hh = v[u_].x * hh + v[u_].y; }
;     }
	v_fmac_f32_e32 v61, v103, v60
	s_waitcnt vmcnt(15)
	v_fmac_f32_e32 v63, v61, v62
	s_waitcnt vmcnt(14)
	v_fmac_f32_e32 v65, v63, v64
	s_waitcnt vmcnt(13)
	v_fmac_f32_e32 v69, v65, v68
	s_waitcnt vmcnt(12)
	v_fmac_f32_e32 v71, v69, v70
	s_waitcnt vmcnt(11)
	v_fmac_f32_e32 v73, v71, v72
	s_waitcnt vmcnt(10)
	v_fmac_f32_e32 v75, v73, v74
	s_waitcnt vmcnt(9)
	v_fmac_f32_e32 v77, v75, v76
	v_lshl_add_u64 v[122:123], v[16:17], 0, v[0:1]
	v_lshlrev_b32_e32 v0, 14, v28
	s_waitcnt vmcnt(8)
	v_fmac_f32_e32 v79, v77, v78
	v_cndmask_b32_e64 v30, 10, 61, vcc
	v_lshl_add_u64 v[124:125], v[16:17], 0, v[0:1]
	v_lshlrev_b32_e32 v0, 14, v29
	s_waitcnt vmcnt(7)
	v_fmac_f32_e32 v81, v79, v80
	v_cndmask_b32_e64 v31, 9, 62, vcc
	v_lshl_add_u64 v[126:127], v[16:17], 0, v[0:1]
	v_lshlrev_b32_e32 v0, 14, v30
	s_waitcnt vmcnt(6)
	v_fmac_f32_e32 v83, v81, v82
	v_cndmask_b32_e64 v32, 8, 63, vcc
	v_lshl_add_u64 v[128:129], v[16:17], 0, v[0:1]
	v_lshlrev_b32_e32 v0, 14, v31
	s_waitcnt vmcnt(5)
	v_fmac_f32_e32 v85, v83, v84
	v_cndmask_b32_e64 v33, 7, 64, vcc
	v_lshl_add_u64 v[130:131], v[16:17], 0, v[0:1]
	v_lshlrev_b32_e32 v0, 14, v32
	s_waitcnt vmcnt(4)
	v_fmac_f32_e32 v87, v85, v86
	v_cndmask_b32_e32 v34, 6, v21, vcc
	v_lshl_add_u64 v[132:133], v[16:17], 0, v[0:1]
	v_lshlrev_b32_e32 v0, 14, v33
	s_waitcnt vmcnt(3)
	v_fmac_f32_e32 v89, v87, v88
	v_cndmask_b32_e32 v35, 5, v20, vcc
	v_lshl_add_u64 v[134:135], v[16:17], 0, v[0:1]
	v_lshlrev_b32_e32 v0, 14, v34
	s_waitcnt vmcnt(2)
	v_fmac_f32_e32 v37, v89, v36
	v_lshl_add_u64 v[136:137], v[16:17], 0, v[0:1]
	v_lshlrev_b32_e32 v0, 14, v35
	s_waitcnt vmcnt(1)
	v_fmac_f32_e32 v39, v37, v38
	v_lshl_add_u64 v[16:17], v[16:17], 0, v[0:1]
	global_store_dword v[42:43], v103, off
	global_store_dword v[44:45], v61, off
	global_store_dword v[46:47], v63, off
	global_store_dword v[48:49], v65, off
	global_store_dword v[50:51], v69, off
	global_store_dword v[52:53], v71, off
	global_store_dword v[54:55], v73, off
	global_store_dword v[56:57], v75, off
	global_store_dword v[58:59], v77, off
	global_store_dword v[96:97], v79, off
	global_store_dword v[98:99], v81, off
	global_store_dword v[100:101], v83, off
	global_store_dword v[66:67], v85, off
	global_store_dword v[104:105], v87, off
	global_store_dword v[106:107], v89, off
	global_store_dword v[108:109], v37, off
	global_store_dword v[110:111], v39, off
	global_load_dwordx2 v[36:37], v[90:91], off
	s_nop 0
	global_load_dwordx2 v[42:43], v[92:93], off
	global_load_dwordx2 v[44:45], v[112:113], off
	global_load_dwordx2 v[46:47], v[114:115], off
	global_load_dwordx2 v[48:49], v[116:117], off
	global_load_dwordx2 v[50:51], v[118:119], off
	global_load_dwordx2 v[52:53], v[120:121], off
	global_load_dwordx2 v[54:55], v[122:123], off
	global_load_dwordx2 v[56:57], v[124:125], off
	global_load_dwordx2 v[58:59], v[126:127], off
	global_load_dwordx2 v[60:61], v[128:129], off
	global_load_dwordx2 v[62:63], v[130:131], off
	global_load_dwordx2 v[64:65], v[132:133], off
	global_load_dwordx2 v[66:67], v[134:135], off
	global_load_dwordx2 v[68:69], v[136:137], off
	s_nop 0
	global_load_dwordx2 v[16:17], v[16:17], off
	v_mov_b32_e32 v3, v1
	v_mov_b32_e32 v5, v1
	v_mov_b32_e32 v7, v1
	s_waitcnt vmcnt(33)
	v_fmac_f32_e32 v41, v39, v40
	v_mov_b32_e32 v9, v1
	v_mov_b32_e32 v11, v1
	v_mov_b32_e32 v13, v1
	v_mov_b32_e32 v71, v1
	v_mov_b32_e32 v73, v1
	v_mov_b32_e32 v75, v1
	v_mov_b32_e32 v77, v1
	v_mov_b32_e32 v79, v1
	v_mov_b32_e32 v81, v1
	v_mov_b32_e32 v83, v1
	v_mov_b32_e32 v85, v1
	v_mov_b32_e32 v87, v1
	v_mov_b32_e32 v89, v1
	s_add_i32 s5, s5, s27
	v_lshlrev_b32_e32 v2, 13, v6
	v_lshlrev_b32_e32 v4, 13, v8
	v_lshlrev_b32_e32 v6, 13, v10
	v_lshlrev_b32_e32 v8, 13, v12
	v_lshlrev_b32_e32 v10, 13, v24
	v_lshlrev_b32_e32 v12, 13, v25
	v_lshlrev_b32_e32 v70, 13, v26
	v_lshlrev_b32_e32 v72, 13, v27
	v_lshlrev_b32_e32 v74, 13, v28
	v_lshlrev_b32_e32 v76, 13, v29
	v_lshlrev_b32_e32 v78, 13, v30
	v_lshlrev_b32_e32 v80, 13, v31
	v_lshlrev_b32_e32 v82, 13, v32
	v_lshlrev_b32_e32 v84, 13, v33
	v_lshlrev_b32_e32 v86, 13, v34
	v_lshlrev_b32_e32 v88, 13, v35
	v_cndmask_b32_e32 v0, v22, v23, vcc
	v_add_u32_e32 v18, s4, v18
	s_cmp_gt_i32 s5, 63
	v_lshl_add_u64 v[2:3], v[14:15], 0, v[2:3]
	v_lshl_add_u64 v[4:5], v[14:15], 0, v[4:5]
	v_lshl_add_u64 v[6:7], v[14:15], 0, v[6:7]
	v_lshl_add_u64 v[8:9], v[14:15], 0, v[8:9]
	v_lshl_add_u64 v[10:11], v[14:15], 0, v[10:11]
	v_lshl_add_u64 v[12:13], v[14:15], 0, v[12:13]
	v_lshl_add_u64 v[24:25], v[14:15], 0, v[70:71]
	v_lshl_add_u64 v[26:27], v[14:15], 0, v[72:73]
	v_lshl_add_u64 v[28:29], v[14:15], 0, v[74:75]
	v_lshl_add_u64 v[30:31], v[14:15], 0, v[76:77]
	v_lshl_add_u64 v[32:33], v[14:15], 0, v[78:79]
	v_lshl_add_u64 v[34:35], v[14:15], 0, v[80:81]
	v_lshl_add_u64 v[70:71], v[14:15], 0, v[82:83]
	v_lshl_add_u64 v[72:73], v[14:15], 0, v[84:85]
	v_lshl_add_u64 v[74:75], v[14:15], 0, v[86:87]
	v_lshl_add_u64 v[76:77], v[14:15], 0, v[88:89]
	v_lshl_add_u64 v[14:15], v[14:15], 0, v[0:1]
	global_store_dword v[2:3], v41, off
	s_waitcnt vmcnt(16)
	v_fmac_f32_e32 v37, v41, v36
	s_waitcnt vmcnt(15)
	v_fmac_f32_e32 v43, v37, v42
	s_waitcnt vmcnt(14)
	v_fmac_f32_e32 v45, v43, v44
	s_waitcnt vmcnt(13)
	v_fmac_f32_e32 v47, v45, v46
	s_waitcnt vmcnt(12)
	v_fmac_f32_e32 v49, v47, v48
	s_waitcnt vmcnt(11)
	v_fmac_f32_e32 v51, v49, v50
	s_waitcnt vmcnt(10)
	v_fmac_f32_e32 v53, v51, v52
	s_waitcnt vmcnt(9)
	v_fmac_f32_e32 v55, v53, v54
	s_waitcnt vmcnt(8)
	v_fmac_f32_e32 v57, v55, v56
	s_waitcnt vmcnt(7)
	v_fmac_f32_e32 v59, v57, v58
	s_waitcnt vmcnt(6)
	v_fmac_f32_e32 v61, v59, v60
	s_waitcnt vmcnt(5)
	v_fmac_f32_e32 v63, v61, v62
	s_waitcnt vmcnt(4)
	v_fmac_f32_e32 v65, v63, v64
	s_waitcnt vmcnt(3)
	v_fmac_f32_e32 v67, v65, v66
	s_waitcnt vmcnt(2)
	v_fmac_f32_e32 v69, v67, v68
	s_waitcnt vmcnt(1)
	v_fmac_f32_e32 v17, v69, v16
	global_store_dword v[4:5], v37, off
	global_store_dword v[6:7], v43, off
	global_store_dword v[8:9], v45, off
	global_store_dword v[10:11], v47, off
	global_store_dword v[12:13], v49, off
	global_store_dword v[24:25], v51, off
	global_store_dword v[26:27], v53, off
	global_store_dword v[28:29], v55, off
	global_store_dword v[30:31], v57, off
	global_store_dword v[32:33], v59, off
	global_store_dword v[34:35], v61, off
	global_store_dword v[70:71], v63, off
	global_store_dword v[72:73], v65, off
	global_store_dword v[74:75], v67, off
	global_store_dword v[76:77], v69, off
	global_store_dword v[14:15], v17, off
	s_cbranch_scc0 .LBB0_653

; DEVI unsigned pk2(float lo, float hi) { f32x2 v = {lo, hi}; bf16x2_t b = __builtin_convertvector(v, bf16x2_t); return __builtin_bit_cast(unsigned, b); }
; DEVI float bflo(unsigned u) { return __uint_as_float(u << 16); }
; DEVI float bfhi(unsigned u) { return __uint_as_float(u & 0xffff0000u); }
; template <bool PASS_C>
; DEVI void lru_item(const P& p, int item, int next_item, uint4& u0, uint4& u1, uint4& u2, float& cpre, char* smem) {
;     ...
;     {
;         const int tok = tid >> 2, cg0 = (tid & 3) * 16;
;         uint4 r[4][2];
; #pragma unroll
;         for (int k = 0; k < 4; ++k) { r[k][0] = *(const uint4*)(us + (tok + k) * 64 + cg0); r[k][1] = *(const uint4*)(us + (tok + k) * 64 + cg0 + 8); }
;         float val[16];
; #pragma unroll
;         for (int e = 0; e < 16; ++e) {
;             const int ch = cg0 + e;
;             float a = prm[4 * 64 + ch];
; #pragma unroll
;             for (int k = 0; k < 4; ++k) {
;                 const uint4 q = r[k][e >> 3];
;                 const unsigned wd = ((e >> 1) & 3) == 0 ? q.x : (((e >> 1) & 3) == 1 ? q.y : (((e >> 1) & 3) == 2 ? q.z : q.w));
;                 a += prm[k * 64 + ch] * ((e & 1) ? bfhi(wd) : bflo(wd));
;             }
;             val[e] = a;
;         }
;         uint4 o;
;         o.x = pk2(val[0], val[1]); o.y = pk2(val[2], val[3]); o.z = pk2(val[4], val[5]); o.w = pk2(val[6], val[7]);
;         *(uint4*)(ucb + tok * 128 + ((((cg0 >> 3) + 0) ^ (tok & 7)) << 4)) = o;
;         o.x = pk2(val[8], val[9]); o.y = pk2(val[10], val[11]); o.z = pk2(val[12], val[13]); o.w = pk2(val[14], val[15]);
;         *(uint4*)(ucb + tok * 128 + ((((cg0 >> 3) + 1) ^ (tok & 7)) << 4)) = o;
;     }
.LBB0_739:
	v_lshlrev_b64 v[106:107], 10, v[22:23]
	s_waitcnt lgkmcnt(0)
	s_barrier
	ds_read_b128 v[42:45], v127 offset:35840
	ds_read_b128 v[22:25], v127 offset:35856
	ds_read_b128 v[46:49], v127 offset:35968
	ds_read_b128 v[26:29], v127 offset:35984
	ds_read_b128 v[50:53], v127 offset:36096
	ds_read_b128 v[30:33], v127 offset:36112
	ds_read_b128 v[54:57], v127 offset:36224
	ds_read_b128 v[34:37], v127 offset:36240
	ds_read_b128 v[58:61], v117 offset:33792
	ds_read_b128 v[62:65], v117 offset:32768
	ds_read_b128 v[66:69], v117 offset:32784
	ds_read_b128 v[70:73], v117 offset:32800
	ds_read_b128 v[38:41], v117 offset:32816
	ds_read_b128 v[74:77], v117 offset:33024
	ds_read_b128 v[158:161], v117 offset:33808
	s_waitcnt lgkmcnt(14)
	v_lshlrev_b32_e32 v162, 16, v42
	v_and_b32_e32 v163, 0xffff0000, v42
	s_waitcnt lgkmcnt(5)
	v_pk_fma_f32 v[58:59], v[62:63], v[162:163], v[58:59]
	ds_read_b128 v[162:165], v117 offset:33280
	ds_read_b128 v[166:169], v117 offset:33536
	ds_read_b128 v[184:187], v117 offset:33040
	v_lshlrev_b32_e32 v42, 16, v43
	v_and_b32_e32 v43, 0xffff0000, v43
	v_lshlrev_b32_e32 v170, 16, v46
	v_and_b32_e32 v171, 0xffff0000, v46
	v_lshlrev_b32_e32 v46, 16, v47
	v_and_b32_e32 v47, 0xffff0000, v47
	v_pk_fma_f32 v[42:43], v[64:65], v[42:43], v[60:61]
	v_lshlrev_b32_e32 v192, 16, v50
	v_and_b32_e32 v193, 0xffff0000, v50
	s_waitcnt lgkmcnt(4)
	v_pk_fma_f32 v[58:59], v[74:75], v[170:171], v[58:59]
	ds_read_b128 v[188:191], v117 offset:33296
	v_lshlrev_b32_e32 v50, 16, v51
	v_and_b32_e32 v51, 0xffff0000, v51
	v_pk_fma_f32 v[42:43], v[76:77], v[46:47], v[42:43]
	v_lshlrev_b32_e32 v196, 16, v54
	v_and_b32_e32 v197, 0xffff0000, v54
	s_waitcnt lgkmcnt(3)
	v_pk_fma_f32 v[58:59], v[162:163], v[192:193], v[58:59]
	ds_read_b128 v[192:195], v117 offset:33552
	v_lshlrev_b32_e32 v54, 16, v55
	v_and_b32_e32 v55, 0xffff0000, v55
	v_pk_fma_f32 v[42:43], v[164:165], v[50:51], v[42:43]
	v_lshlrev_b32_e32 v46, 16, v48
	s_waitcnt lgkmcnt(3)
	v_pk_fma_f32 v[164:165], v[168:169], v[54:55], v[42:43]
	v_lshlrev_b32_e32 v42, 16, v44
	v_and_b32_e32 v43, 0xffff0000, v44
	v_and_b32_e32 v47, 0xffff0000, v48
	v_pk_fma_f32 v[42:43], v[66:67], v[42:43], v[158:159]
	v_lshlrev_b32_e32 v50, 16, v52
	v_and_b32_e32 v51, 0xffff0000, v52
	s_waitcnt lgkmcnt(2)
	v_pk_fma_f32 v[42:43], v[184:185], v[46:47], v[42:43]
	v_lshlrev_b32_e32 v54, 16, v56
	v_and_b32_e32 v55, 0xffff0000, v56
	s_waitcnt lgkmcnt(1)
	v_pk_fma_f32 v[42:43], v[188:189], v[50:51], v[42:43]
	v_lshlrev_b32_e32 v44, 16, v49
	s_waitcnt lgkmcnt(0)
	v_pk_fma_f32 v[158:159], v[192:193], v[54:55], v[42:43]
	v_lshlrev_b32_e32 v42, 16, v45
	v_and_b32_e32 v43, 0xffff0000, v45
	v_and_b32_e32 v45, 0xffff0000, v49
	v_pk_fma_f32 v[42:43], v[68:69], v[42:43], v[160:161]
	v_lshlrev_b32_e32 v46, 16, v53
	v_and_b32_e32 v47, 0xffff0000, v53
	v_pk_fma_f32 v[42:43], v[186:187], v[44:45], v[42:43]
	v_lshlrev_b32_e32 v48, 16, v57
	v_and_b32_e32 v49, 0xffff0000, v57
	v_pk_fma_f32 v[42:43], v[190:191], v[46:47], v[42:43]
	v_lshlrev_b32_e32 v54, 16, v22
	v_pk_fma_f32 v[160:161], v[194:195], v[48:49], v[42:43]
	ds_read_b128 v[42:45], v117 offset:33824
	ds_read_b128 v[46:49], v117 offset:33056
	ds_read_b128 v[50:53], v117 offset:33840
	v_and_b32_e32 v55, 0xffff0000, v22
	v_pk_fma_f32 v[162:163], v[166:167], v[196:197], v[58:59]
	v_lshlrev_b32_e32 v22, 16, v23
	s_waitcnt lgkmcnt(2)
	v_pk_fma_f32 v[42:43], v[70:71], v[54:55], v[42:43]
	ds_read_b128 v[54:57], v117 offset:33312
	ds_read_b128 v[58:61], v117 offset:33568
	ds_read_b128 v[62:65], v117 offset:33072
	v_and_b32_e32 v23, 0xffff0000, v23
	v_lshlrev_b32_e32 v66, 16, v26
	v_and_b32_e32 v67, 0xffff0000, v26
	v_lshlrev_b32_e32 v26, 16, v27
	v_and_b32_e32 v27, 0xffff0000, v27
	v_pk_fma_f32 v[22:23], v[72:73], v[22:23], v[44:45]
	v_lshlrev_b32_e32 v74, 16, v30
	v_and_b32_e32 v75, 0xffff0000, v30
	s_waitcnt lgkmcnt(4)
	v_pk_fma_f32 v[42:43], v[46:47], v[66:67], v[42:43]
	ds_read_b128 v[66:69], v117 offset:33328
	v_lshlrev_b32_e32 v30, 16, v31
	v_and_b32_e32 v31, 0xffff0000, v31
	v_pk_fma_f32 v[22:23], v[48:49], v[26:27], v[22:23]
	v_lshlrev_b32_e32 v166, 16, v34
	v_and_b32_e32 v167, 0xffff0000, v34
	s_waitcnt lgkmcnt(3)
	v_pk_fma_f32 v[42:43], v[54:55], v[74:75], v[42:43]
	ds_read_b128 v[74:77], v117 offset:33584
	v_lshlrev_b32_e32 v34, 16, v35
	v_and_b32_e32 v35, 0xffff0000, v35
	v_pk_fma_f32 v[22:23], v[56:57], v[30:31], v[22:23]
	v_lshlrev_b32_e32 v30, 16, v28
	s_waitcnt lgkmcnt(3)
	v_pk_fma_f32 v[26:27], v[60:61], v[34:35], v[22:23]
	v_lshlrev_b32_e32 v22, 16, v24
	v_and_b32_e32 v23, 0xffff0000, v24
	v_and_b32_e32 v31, 0xffff0000, v28
	v_pk_fma_f32 v[22:23], v[38:39], v[22:23], v[50:51]
	v_lshlrev_b32_e32 v34, 16, v32
	v_and_b32_e32 v35, 0xffff0000, v32
	s_waitcnt lgkmcnt(2)
	v_pk_fma_f32 v[22:23], v[62:63], v[30:31], v[22:23]
	v_lshlrev_b32_e32 v44, 16, v36
	v_and_b32_e32 v45, 0xffff0000, v36
	s_waitcnt lgkmcnt(1)
	v_pk_fma_f32 v[22:23], v[66:67], v[34:35], v[22:23]
	v_lshlrev_b32_e32 v24, 16, v29
	s_waitcnt lgkmcnt(0)
	v_pk_fma_f32 v[30:31], v[74:75], v[44:45], v[22:23]
	v_lshlrev_b32_e32 v22, 16, v25
	v_and_b32_e32 v23, 0xffff0000, v25
	v_and_b32_e32 v25, 0xffff0000, v29
	v_pk_fma_f32 v[22:23], v[40:41], v[22:23], v[52:53]
	v_lshlrev_b32_e32 v28, 16, v33
	v_and_b32_e32 v29, 0xffff0000, v33
	v_pk_fma_f32 v[22:23], v[64:65], v[24:25], v[22:23]
	v_lshlrev_b32_e32 v32, 16, v37
	v_and_b32_e32 v33, 0xffff0000, v37
	v_pk_fma_f32 v[22:23], v[68:69], v[28:29], v[22:23]
	v_pk_fma_f32 v[42:43], v[58:59], v[166:167], v[42:43]
	v_pk_fma_f32 v[28:29], v[76:77], v[32:33], v[22:23]
	v_cvt_pk_bf16_f32 v22, v162, v163
	v_cvt_pk_bf16_f32 v23, v164, v165
	v_cvt_pk_bf16_f32 v24, v158, v159
	v_cvt_pk_bf16_f32 v25, v160, v161
	ds_write_b128 v128, v[22:25] offset:44544
	v_cvt_pk_bf16_f32 v22, v42, v43
	v_cvt_pk_bf16_f32 v23, v26, v27
	v_cvt_pk_bf16_f32 v24, v30, v31
	v_cvt_pk_bf16_f32 v25, v28, v29
	ds_write_b128 v129, v[22:25] offset:44544
	v_add_u32_e32 v22, v119, v120
	s_waitcnt lgkmcnt(0)
	s_barrier
; DEVI float bf2f(bf16_t h) { return __uint_as_float(((unsigned)h) << 16); }
; template <bool PASS_C>
; DEVI void lru_item(const P& p, int item, int next_item, uint4& u0, uint4& u1, uint4& u2, float& cpre, char* smem) {
;     ...
;     {
;         bf16x8 af[2];
; #pragma unroll
;         for (int kk = 0; kk < 2; ++kk) af[kk] = *(const bf16x8*)(ucb + (16 * w + fr) * 128 + (((kk * 4 + fq) ^ (fr & 7)) << 4));
; #pragma unroll
;         for (int n = 0; n < 16; ++n)
; #pragma unroll
;             for (int kk = 0; kk < 2; ++kk) {
;                 const bf16x8 bfr = *(const bf16x8*)(smem + (16 * n + fr) * 128 + (((kk * 4 + fq) ^ (fr & 7)) << 4));
;                 acc[n] = __builtin_amdgcn_mfma_f32_16x16x32_bf16(af[kk], bfr, acc[n], 0, 0, 0);
;             }
;     }
;     float av[4][2][4], bv[4][2][4], apre[4][2], bpre[4][2];
; #pragma unroll
;     for (int nn = 0; nn < 4; ++nn) {
;         const int ch = 16 * nn + fr;
;         float uc[4];
; #pragma unroll
;         for (int j = 0; j < 4; ++j) {
;             const int tl = 16 * w + 4 * fq + j;
;             uc[j] = bf2f(*(const bf16_t*)(ucb + tl * 128 + ((((ch >> 3)) ^ (tl & 7)) << 4) + (ch & 7) * 2));
;         }
; #pragma unroll
;         for (int d = 0; d < 2; ++d) {
;             const float ba = prm[(5 + d) * 64 + ch], bx = prm[(7 + d) * 64 + ch], nsp8 = prm[(9 + d) * 64 + ch];
	v_add_u32_e32 v87, v118, v120
	v_add_u32_e32 v30, v119, v121
	v_add_u32_e32 v89, v118, v121
	ds_read_b128 v[26:29], v22 offset:44544
	ds_read_b128 v[158:161], v30 offset:44544
	ds_read_b32 v93, v122 offset:35072
	ds_read_b128 v[232:235], v87
	ds_read_b128 v[236:239], v89
	ds_read_b128 v[240:243], v87 offset:2048
	ds_read_b128 v[244:247], v89 offset:2048
	ds_read_b128 v[248:251], v87 offset:4096
	ds_read_b128 v[192:195], v89 offset:4096
	ds_read_b128 v[252:255], v87 offset:6144
	ds_read_b128 v[218:221], v89 offset:6144
	s_waitcnt lgkmcnt(4)
	v_mfma_f32_16x16x32_bf16 v[166:169], v[26:29], v[232:235], 0
	ds_read_b128 v[222:225], v87 offset:8192
	ds_read_b128 v[226:229], v89 offset:8192
	ds_read_b128 v[162:165], v87 offset:10240
	ds_read_b128 v[188:191], v89 offset:10240
	v_mfma_f32_16x16x32_bf16 v[62:65], v[26:29], v[240:243], 0
	v_mfma_f32_16x16x32_bf16 v[166:169], v[158:161], v[236:239], v[166:169]
	v_mfma_f32_16x16x32_bf16 v[62:65], v[158:161], v[244:247], v[62:65]
	s_waitcnt lgkmcnt(4)
	v_mfma_f32_16x16x32_bf16 v[46:49], v[26:29], v[248:251], 0
	ds_read_b128 v[232:235], v87 offset:12288
	ds_read_b128 v[236:239], v89 offset:12288
	ds_read_b128 v[240:243], v87 offset:14336
	ds_read_b128 v[244:247], v89 offset:14336
	v_mfma_f32_16x16x32_bf16 v[30:33], v[26:29], v[252:255], 0
	v_mfma_f32_16x16x32_bf16 v[46:49], v[158:161], v[192:195], v[46:49]
	v_mfma_f32_16x16x32_bf16 v[30:33], v[158:161], v[218:221], v[30:33]
	s_waitcnt lgkmcnt(4)
	v_mfma_f32_16x16x32_bf16 v[184:187], v[26:29], v[222:225], 0
	ds_read_b128 v[248:251], v87 offset:16384
	ds_read_b128 v[192:195], v89 offset:16384
	ds_read_b128 v[252:255], v87 offset:18432
	ds_read_b128 v[218:221], v89 offset:18432
	v_mfma_f32_16x16x32_bf16 v[66:69], v[26:29], v[162:165], 0
	v_mfma_f32_16x16x32_bf16 v[184:187], v[158:161], v[226:229], v[184:187]
	v_mfma_f32_16x16x32_bf16 v[66:69], v[158:161], v[188:191], v[66:69]
	s_waitcnt lgkmcnt(4)
	v_mfma_f32_16x16x32_bf16 v[50:53], v[26:29], v[232:235], 0
	ds_read_b128 v[222:225], v87 offset:20480
	ds_read_b128 v[226:229], v89 offset:20480
	ds_read_b128 v[162:165], v87 offset:22528
	ds_read_b128 v[188:191], v89 offset:22528
	v_mfma_f32_16x16x32_bf16 v[34:37], v[26:29], v[240:243], 0
	v_mfma_f32_16x16x32_bf16 v[50:53], v[158:161], v[236:239], v[50:53]
	v_mfma_f32_16x16x32_bf16 v[34:37], v[158:161], v[244:247], v[34:37]
	s_waitcnt lgkmcnt(4)
	v_mfma_f32_16x16x32_bf16 v[70:73], v[26:29], v[248:251], 0
	ds_read_b128 v[232:235], v87 offset:24576
	ds_read_b128 v[236:239], v89 offset:24576
	ds_read_b128 v[240:243], v87 offset:26624
	ds_read_b128 v[244:247], v89 offset:26624
	v_mfma_f32_16x16x32_bf16 v[54:57], v[26:29], v[252:255], 0
	v_mfma_f32_16x16x32_bf16 v[70:73], v[158:161], v[192:195], v[70:73]
	v_mfma_f32_16x16x32_bf16 v[54:57], v[158:161], v[218:221], v[54:57]
	s_waitcnt lgkmcnt(4)
	v_mfma_f32_16x16x32_bf16 v[38:41], v[26:29], v[222:225], 0
	ds_read_b128 v[248:251], v87 offset:28672
	ds_read_b128 v[252:255], v87 offset:30720
	ds_read_b128 v[192:195], v89 offset:28672
	v_mfma_f32_16x16x32_bf16 v[22:25], v[26:29], v[162:165], 0
	v_mfma_f32_16x16x32_bf16 v[38:41], v[158:161], v[226:229], v[38:41]
	v_mfma_f32_16x16x32_bf16 v[22:25], v[158:161], v[188:191], v[22:25]
	s_waitcnt lgkmcnt(3)
	v_mfma_f32_16x16x32_bf16 v[74:77], v[26:29], v[232:235], 0
	v_mfma_f32_16x16x32_bf16 v[58:61], v[26:29], v[240:243], 0
	v_mfma_f32_16x16x32_bf16 v[74:77], v[158:161], v[236:239], v[74:77]
	v_mfma_f32_16x16x32_bf16 v[58:61], v[158:161], v[244:247], v[58:61]
	s_waitcnt lgkmcnt(1)
	v_mfma_f32_16x16x32_bf16 v[42:45], v[26:29], v[248:251], 0
	v_mfma_f32_16x16x32_bf16 v[26:29], v[26:29], v[252:255], 0
	ds_read_b128 v[162:165], v89 offset:30720
	ds_read2st64_b32 v[170:171], v122 offset0:133 offset1:135
	ds_read_u16 v246, v130 offset:44544
	ds_read_u16 v247, v131 offset:44544
	ds_read_u16 v248, v132 offset:44544
	ds_read_u16 v249, v133 offset:44544
	ds_read2st64_b32 v[232:233], v122 offset0:134 offset1:136
	ds_read_b32 v250, v122 offset:35328
	v_add_u32_e32 v217, 64, v122
	ds_read2st64_b32 v[234:235], v217 offset0:133 offset1:135
	ds_read_u16 v251, v134 offset:44544
	ds_read_u16 v252, v135 offset:44544
	ds_read_u16 v253, v136 offset:44544
	ds_read_u16 v254, v137 offset:44544
	ds_read_b32 v255, v122 offset:35136
	v_add_u32_e32 v217, 64, v122
	ds_read2st64_b32 v[236:237], v217 offset0:134 offset1:136
	ds_read_b32 v218, v122 offset:35392
	v_add_u32_e32 v217, 0x80, v122
	ds_read2st64_b32 v[238:239], v217 offset0:133 offset1:135
	ds_read_u16 v219, v138 offset:44544
	ds_read_u16 v220, v139 offset:44544
	ds_read_u16 v221, v140 offset:44544
	ds_read_u16 v222, v141 offset:44544
	ds_read_b32 v223, v122 offset:35200
	v_add_u32_e32 v217, 0x80, v122
	ds_read2st64_b32 v[240:241], v217 offset0:134 offset1:136
	ds_read_b32 v224, v122 offset:35456
	v_add_u32_e32 v217, 0xc0, v122
	ds_read2st64_b32 v[242:243], v217 offset0:133 offset1:135
	ds_read_u16 v225, v142 offset:44544
	ds_read_u16 v226, v143 offset:44544
	ds_read_u16 v227, v144 offset:44544
	ds_read_u16 v228, v145 offset:44544
	ds_read_b32 v229, v122 offset:35264
	v_add_u32_e32 v217, 0xc0, v122
	ds_read2st64_b32 v[244:245], v217 offset0:134 offset1:136
	ds_read_b32 v231, v122 offset:35520
	s_waitcnt lgkmcnt(0)
; template <bool PASS_C>
; DEVI void lru_item(const P& p, int item, int next_item, uint4& u0, uint4& u1, uint4& u2, float& cpre, char* smem) {
;     ...
;         for (int d = 0; d < 2; ++d) {
;             const float ba = prm[(5 + d) * 64 + ch], bx = prm[(7 + d) * 64 + ch], nsp8 = prm[(9 + d) * 64 + ch];
; #pragma unroll
;             for (int j = 0; j < 4; ++j) {
;                 const float r = __builtin_amdgcn_rcpf(1.0f + __builtin_amdgcn_exp2f(__builtin_fmaf(acc[(2 * d) * 4 + nn][j], -LOG2E, ba)));
;                 const float ig = __builtin_amdgcn_rcpf(1.0f + __builtin_amdgcn_exp2f(__builtin_fmaf(acc[(2 * d + 1) * 4 + nn][j], -LOG2E, bx)));
;                 const float a_ = __builtin_amdgcn_exp2f(nsp8 * r);
;                 av[nn][d][j] = a_;
;                 bv[nn][d][j] = __builtin_amdgcn_sqrtf(__builtin_fmaf(-a_, a_, 1.0f)) * ig * uc[j];
;             }
;             float A = 1.f, Bq = 0.f;
;             if (d == 0) {
; #pragma unroll
;                 for (int j = 0; j < 4; ++j) { Bq = av[nn][d][j] * Bq + bv[nn][d][j]; A *= av[nn][d][j]; }
;             } else {
; #pragma unroll
;                 for (int j = 3; j >= 0; --j) { Bq = av[nn][d][j] * Bq + bv[nn][d][j]; A *= av[nn][d][j]; }
;             }
;             float Ag[4], Bg[4];
;             rowgather4(A, Ag); rowgather4(Bq, Bg);
;             float AW = 1.f, BW = 0.f, AP = 1.f, BP = 0.f;
;             if (d == 0) {
; #pragma unroll
;                 for (int g = 0; g < 4; ++g) {
;                     if (g == fq) { AP = AW; BP = BW; }
;                     BW = Ag[g] * BW + Bg[g]; AW *= Ag[g];
;                 }
;             } else {
; #pragma unroll
;                 for (int g = 3; g >= 0; --g) {
;                     if (g == fq) { AP = AW; BP = BW; }
;                     BW = Ag[g] * BW + Bg[g]; AW *= Ag[g];
;                 }
;             }
;             apre[nn][d] = AP; bpre[nn][d] = BP;
;             if (fq == 0) { wagg[((w * 2 + d) * 64 + ch) * 2 + 0] = AW; wagg[((w * 2 + d) * 64 + ch) * 2 + 1] = BW; }
;         }
	v_fmamk_f32 v95, v166, 0xbfb8aa3b, v170
	v_exp_f32_e32 v95, v95
	v_mfma_f32_16x16x32_bf16 v[42:45], v[158:161], v[192:195], v[42:45]
	v_fmamk_f32 v99, v168, 0xbfb8aa3b, v170
	v_fmamk_f32 v101, v186, 0xbfb8aa3b, v171
	v_exp_f32_e32 v99, v99
	v_mfma_f32_16x16x32_bf16 v[26:29], v[158:161], v[162:165], v[26:29]
	v_lshlrev_b32_e32 v164, 16, v246
	v_lshlrev_b32_e32 v161, 16, v247
	v_add_f32_e32 v87, 1.0, v95
	v_fmamk_f32 v89, v184, 0xbfb8aa3b, v171
	v_exp_f32_e32 v89, v89
	v_rcp_f32_e32 v87, v87
	v_lshlrev_b32_e32 v162, 16, v248
	v_add_f32_e32 v95, 1.0, v89
	v_mul_f32_e32 v87, v93, v87
	v_exp_f32_e32 v89, v87
	v_rcp_f32_e32 v87, v95
	v_fmamk_f32 v95, v167, 0xbfb8aa3b, v170
	v_exp_f32_e32 v95, v95
	v_lshlrev_b32_e32 v163, 16, v249
	v_fma_f32 v97, -v89, v89, 1.0
	v_sqrt_f32_e32 v97, v97
	v_add_f32_e32 v91, 1.0, v95
	v_rcp_f32_e32 v91, v91
	v_fmamk_f32 v95, v185, 0xbfb8aa3b, v171
	v_exp_f32_e32 v95, v95
	v_mul_f32_e32 v87, v87, v97
	v_mul_f32_e32 v91, v93, v91
	v_exp_f32_e32 v91, v91
	v_add_f32_e32 v95, 1.0, v95
	v_rcp_f32_e32 v95, v95
	v_exp_f32_e32 v101, v101
	v_fma_f32 v97, -v91, v91, 1.0
	v_sqrt_f32_e32 v97, v97
	v_fmamk_f32 v171, v187, 0xbfb8aa3b, v171
	v_exp_f32_e32 v105, v171
	v_mul_f32_e32 v87, v87, v164
	v_mul_f32_e32 v97, v95, v97
	v_add_f32_e32 v95, 1.0, v99
	v_add_f32_e32 v99, 1.0, v101
	v_fmamk_f32 v101, v169, 0xbfb8aa3b, v170
	v_exp_f32_e32 v101, v101
	v_rcp_f32_e32 v95, v95
	v_rcp_f32_e32 v99, v99
	v_add_f32_e32 v101, 1.0, v101
	v_rcp_f32_e32 v101, v101
	v_mul_f32_e32 v95, v93, v95
	v_exp_f32_e32 v95, v95
	v_mul_f32_e32 v93, v93, v101
	v_exp_f32_e32 v101, v93
	v_add_f32_e32 v93, 1.0, v105
	v_fma_f32 v103, -v95, v95, 1.0
	v_rcp_f32_e32 v105, v93
	v_fma_f32 v93, -v101, v101, 1.0
	v_sqrt_f32_e32 v103, v103
	v_sqrt_f32_e32 v157, v93
	v_mul_f32_e32 v93, v97, v161
	v_mul_f32_e32 v97, v99, v103
	v_mul_f32_e32 v99, v105, v157
	v_fma_f32 v105, 0, v89, v87
	v_mul_f32_e32 v97, v97, v162
	v_mul_f32_e32 v103, v89, v91
	v_fma_f32 v105, v91, v105, v93
	v_mul_f32_e32 v99, v99, v163
	v_mul_f32_e32 v103, v95, v103
	v_fma_f32 v105, v95, v105, v97
	v_mul_f32_e32 v103, v101, v103
	v_fma_f32 v105, v101, v105, v99
	v_mov_b32_e32 v159, v103
	v_mov_b32_e32 v157, v105
	s_nop 0
	v_permlane16_swap_b32_e32 v103, v159
	v_permlane16_swap_b32_e32 v105, v157
	v_mov_b32_e32 v160, v103
	v_mov_b32_e32 v158, v105
	s_nop 0
	v_permlane32_swap_b32_e32 v103, v160
	v_mov_b32_e32 v165, v159
	v_permlane32_swap_b32_e32 v105, v158
	v_mov_b32_e32 v166, v157
	v_permlane32_swap_b32_e32 v159, v165
	s_nop 0
	v_permlane32_swap_b32_e32 v157, v166
	v_fmac_f32_e32 v157, v105, v159
	v_mul_f32_e32 v159, v103, v159
	v_fmac_f32_e32 v158, v157, v160
	v_mul_f32_e32 v160, v159, v160
	s_and_saveexec_b64 s[28:29], s[10:11]
	v_mul_f32_e32 v167, v158, v165
	v_mul_f32_e32 v168, v160, v165
	v_add_f32_e32 v169, v167, v166
	ds_write_b64 v149, v[168:169] offset:52736
	s_or_b64 exec, exec, s[28:29]
	v_fmamk_f32 v70, v70, 0xbfb8aa3b, v232
	v_exp_f32_e32 v70, v70
	v_fmamk_f32 v71, v71, 0xbfb8aa3b, v232
	v_exp_f32_e32 v71, v71
	v_fmamk_f32 v74, v74, 0xbfb8aa3b, v233
	v_add_f32_e32 v70, 1.0, v70
	v_rcp_f32_e32 v70, v70
	v_add_f32_e32 v71, 1.0, v71
	v_exp_f32_e32 v74, v74
	v_rcp_f32_e32 v71, v71
	v_mul_f32_e32 v70, v250, v70
	v_exp_f32_e32 v70, v70
	v_fmamk_f32 v75, v75, 0xbfb8aa3b, v233
	v_add_f32_e32 v74, 1.0, v74
	v_mul_f32_e32 v71, v250, v71
	v_fma_f32 v168, -v70, v70, 1.0
	v_fmamk_f32 v72, v72, 0xbfb8aa3b, v232
	v_fmamk_f32 v73, v73, 0xbfb8aa3b, v232
	v_exp_f32_e32 v75, v75
	v_rcp_f32_e32 v74, v74
	v_exp_f32_e32 v71, v71
	v_sqrt_f32_e32 v168, v168
	v_exp_f32_e32 v72, v72
	v_exp_f32_e32 v73, v73
	v_add_f32_e32 v75, 1.0, v75
	v_fma_f32 v169, -v71, v71, 1.0
	v_mul_f32_e32 v74, v74, v168
	v_fmamk_f32 v76, v76, 0xbfb8aa3b, v233
	v_add_f32_e32 v72, 1.0, v72
	v_add_f32_e32 v73, 1.0, v73
	v_rcp_f32_e32 v75, v75
	v_mul_f32_e32 v74, v74, v164
	v_sqrt_f32_e32 v164, v169
	v_exp_f32_e32 v76, v76
	v_rcp_f32_e32 v72, v72
	v_rcp_f32_e32 v73, v73
	v_fmamk_f32 v167, v77, 0xbfb8aa3b, v233
	v_mul_f32_e32 v164, v75, v164
	v_add_f32_e32 v75, 1.0, v76
	v_mul_f32_e32 v72, v250, v72
	v_exp_f32_e32 v77, v167
	v_mul_f32_e32 v73, v250, v73
	v_exp_f32_e32 v72, v72
	v_rcp_f32_e32 v76, v75
	v_exp_f32_e32 v75, v73
	v_add_f32_e32 v73, 1.0, v77
	v_fma_f32 v166, -v72, v72, 1.0
	v_rcp_f32_e32 v77, v73
	v_fma_f32 v73, -v75, v75, 1.0
	v_sqrt_f32_e32 v165, v166
	v_sqrt_f32_e32 v166, v73
	v_mul_f32_e32 v73, v164, v161
	v_mul_f32_e32 v161, v75, v72
	v_mul_f32_e32 v76, v76, v165
	v_mul_f32_e32 v77, v77, v166
	v_mul_f32_e32 v77, v77, v163
	v_mul_f32_e32 v161, v71, v161
	v_mul_f32_e32 v76, v76, v162
	v_mul_f32_e32 v165, v70, v161
	v_fma_f32 v161, 0, v75, v77
	v_fma_f32 v161, v72, v161, v76
	v_fma_f32 v161, v71, v161, v73
	v_fma_f32 v168, v70, v161, v74
	v_mov_b32_e32 v167, v165
	v_mov_b32_e32 v161, v168
	s_nop 0
	v_permlane16_swap_b32_e32 v165, v167
	v_permlane16_swap_b32_e32 v168, v161
	v_mov_b32_e32 v162, v167
	v_mov_b32_e32 v164, v161
	v_mov_b32_e32 v166, v165
	v_permlane32_swap_b32_e32 v167, v162
	v_mov_b32_e32 v163, v168
	v_permlane32_swap_b32_e32 v161, v164
	v_permlane32_swap_b32_e32 v165, v166
	v_permlane32_swap_b32_e32 v168, v163
	v_fmac_f32_e32 v163, v164, v166
	v_mul_f32_e32 v166, v166, v162
	v_fmac_f32_e32 v161, v163, v167
	v_mul_f32_e32 v167, v166, v167
	s_and_saveexec_b64 s[28:29], s[10:11]
	v_mul_f32_e32 v169, v161, v165
	v_mul_f32_e32 v170, v167, v165
	v_add_f32_e32 v171, v169, v168
	ds_write_b64 v149, v[170:171] offset:53248
	s_or_b64 exec, exec, s[28:29]
	v_lshlrev_b32_e32 v185, 16, v251
	v_lshlrev_b32_e32 v183, 16, v252
	v_lshlrev_b32_e32 v177, 16, v253
	v_fmamk_f32 v62, v62, 0xbfb8aa3b, v234
	v_exp_f32_e32 v62, v62
; template <bool PASS_C>
; DEVI void lru_item(const P& p, int item, int next_item, uint4& u0, uint4& u1, uint4& u2, float& cpre, char* smem) {
;     ...
;         for (int d = 0; d < 2; ++d) {
;             const float ba = prm[(5 + d) * 64 + ch], bx = prm[(7 + d) * 64 + ch], nsp8 = prm[(9 + d) * 64 + ch];
; #pragma unroll
;             for (int j = 0; j < 4; ++j) {
;                 const float r = __builtin_amdgcn_rcpf(1.0f + __builtin_amdgcn_exp2f(__builtin_fmaf(acc[(2 * d) * 4 + nn][j], -LOG2E, ba)));
;                 const float ig = __builtin_amdgcn_rcpf(1.0f + __builtin_amdgcn_exp2f(__builtin_fmaf(acc[(2 * d + 1) * 4 + nn][j], -LOG2E, bx)));
;                 const float a_ = __builtin_amdgcn_exp2f(nsp8 * r);
;                 av[nn][d][j] = a_;
;                 bv[nn][d][j] = __builtin_amdgcn_sqrtf(__builtin_fmaf(-a_, a_, 1.0f)) * ig * uc[j];
;             }
;             float A = 1.f, Bq = 0.f;
;             if (d == 0) {
; #pragma unroll
;                 for (int j = 0; j < 4; ++j) { Bq = av[nn][d][j] * Bq + bv[nn][d][j]; A *= av[nn][d][j]; }
;             } else {
; #pragma unroll
;                 for (int j = 3; j >= 0; --j) { Bq = av[nn][d][j] * Bq + bv[nn][d][j]; A *= av[nn][d][j]; }
;             }
;             float Ag[4], Bg[4];
;             rowgather4(A, Ag); rowgather4(Bq, Bg);
;             float AW = 1.f, BW = 0.f, AP = 1.f, BP = 0.f;
;             if (d == 0) {
; #pragma unroll
;                 for (int g = 0; g < 4; ++g) {
;                     if (g == fq) { AP = AW; BP = BW; }
;                     BW = Ag[g] * BW + Bg[g]; AW *= Ag[g];
;                 }
;             } else {
; #pragma unroll
;                 for (int g = 3; g >= 0; --g) {
;                     if (g == fq) { AP = AW; BP = BW; }
;                     BW = Ag[g] * BW + Bg[g]; AW *= Ag[g];
;                 }
;             }
;             apre[nn][d] = AP; bpre[nn][d] = BP;
;             if (fq == 0) { wagg[((w * 2 + d) * 64 + ch) * 2 + 0] = AW; wagg[((w * 2 + d) * 64 + ch) * 2 + 1] = BW; }
;         }
	v_fmamk_f32 v63, v63, 0xbfb8aa3b, v234
	v_fmamk_f32 v66, v66, 0xbfb8aa3b, v235
	v_exp_f32_e32 v63, v63
	v_add_f32_e32 v62, 1.0, v62
	v_rcp_f32_e32 v62, v62
	v_exp_f32_e32 v66, v66
	v_add_f32_e32 v63, 1.0, v63
	v_rcp_f32_e32 v63, v63
	v_mul_f32_e32 v62, v255, v62
	v_add_f32_e32 v165, 1.0, v66
	v_exp_f32_e32 v66, v62
	v_rcp_f32_e32 v62, v165
	v_fmamk_f32 v67, v67, 0xbfb8aa3b, v235
	v_mul_f32_e32 v63, v255, v63
	v_fma_f32 v165, -v66, v66, 1.0
	v_sqrt_f32_e32 v165, v165
	v_exp_f32_e32 v67, v67
	v_exp_f32_e32 v63, v63
	v_fmamk_f32 v64, v64, 0xbfb8aa3b, v234
	v_exp_f32_e32 v64, v64
	v_mul_f32_e32 v62, v62, v165
	v_add_f32_e32 v67, 1.0, v67
	v_fma_f32 v165, -v63, v63, 1.0
	v_rcp_f32_e32 v67, v67
	v_sqrt_f32_e32 v165, v165
	v_add_f32_e32 v64, 1.0, v64
	v_rcp_f32_e32 v64, v64
	v_fmamk_f32 v65, v65, 0xbfb8aa3b, v234
	v_mul_f32_e32 v67, v67, v165
	v_exp_f32_e32 v165, v65
	v_mul_f32_e32 v64, v255, v64
	v_exp_f32_e32 v65, v64
	v_fmamk_f32 v68, v68, 0xbfb8aa3b, v235
	v_add_f32_e32 v64, 1.0, v165
	v_rcp_f32_e32 v64, v64
	v_fmamk_f32 v169, v69, 0xbfb8aa3b, v235
	v_exp_f32_e32 v168, v169
	v_exp_f32_e32 v68, v68
	v_mul_f32_e32 v64, v255, v64
	v_exp_f32_e32 v69, v64
	v_add_f32_e32 v64, 1.0, v168
	v_add_f32_e32 v68, 1.0, v68
	v_fma_f32 v165, -v65, v65, 1.0
	v_rcp_f32_e32 v168, v64
	v_fma_f32 v64, -v69, v69, 1.0
	v_rcp_f32_e32 v68, v68
	v_sqrt_f32_e32 v165, v165
	v_sqrt_f32_e32 v169, v64
	v_mul_f32_e32 v62, v62, v185
	v_mul_f32_e32 v64, v67, v183
	v_mul_f32_e32 v67, v68, v165
	v_mul_f32_e32 v68, v168, v169
	v_fma_f32 v168, 0, v66, v62
	v_lshlrev_b32_e32 v184, 16, v254
	v_mul_f32_e32 v67, v67, v177
	v_mul_f32_e32 v165, v66, v63
	v_fma_f32 v168, v63, v168, v64
	v_mul_f32_e32 v68, v68, v184
	v_mul_f32_e32 v165, v65, v165
	v_fma_f32 v168, v65, v168, v67
	v_mul_f32_e32 v165, v69, v165
	v_fma_f32 v168, v69, v168, v68
	v_mov_b32_e32 v171, v165
	v_mov_b32_e32 v169, v168
	s_nop 0
	v_permlane16_swap_b32_e32 v165, v171
	v_permlane16_swap_b32_e32 v168, v169
	v_mov_b32_e32 v173, v165
	v_mov_b32_e32 v170, v168
	s_nop 0
	v_permlane32_swap_b32_e32 v165, v173
	v_mov_b32_e32 v187, v171
	v_permlane32_swap_b32_e32 v168, v170
	v_mov_b32_e32 v188, v169
	v_permlane32_swap_b32_e32 v171, v187
	s_nop 0
	v_permlane32_swap_b32_e32 v169, v188
	v_fmac_f32_e32 v169, v168, v171
	v_mul_f32_e32 v171, v165, v171
	v_fmac_f32_e32 v170, v169, v173
	v_mul_f32_e32 v173, v171, v173
	s_and_saveexec_b64 s[28:29], s[10:11]
	v_mul_f32_e32 v189, v170, v187
	v_mul_f32_e32 v190, v173, v187
	v_add_f32_e32 v191, v189, v188
	ds_write_b64 v150, v[190:191] offset:52736
	s_or_b64 exec, exec, s[28:29]
	v_fmamk_f32 v54, v54, 0xbfb8aa3b, v236
	v_exp_f32_e32 v54, v54
	v_fmamk_f32 v55, v55, 0xbfb8aa3b, v236
	v_exp_f32_e32 v55, v55
	v_fmamk_f32 v58, v58, 0xbfb8aa3b, v237
	v_add_f32_e32 v54, 1.0, v54
	v_rcp_f32_e32 v54, v54
	v_add_f32_e32 v55, 1.0, v55
	v_exp_f32_e32 v58, v58
	v_rcp_f32_e32 v55, v55
	v_mul_f32_e32 v54, v218, v54
	v_exp_f32_e32 v54, v54
	v_fmamk_f32 v56, v56, 0xbfb8aa3b, v236
	v_fmamk_f32 v59, v59, 0xbfb8aa3b, v237
	v_add_f32_e32 v58, 1.0, v58
	v_mul_f32_e32 v55, v218, v55
	v_fma_f32 v189, -v54, v54, 1.0
	v_exp_f32_e32 v56, v56
	v_fmamk_f32 v57, v57, 0xbfb8aa3b, v236
	v_exp_f32_e32 v59, v59
	v_rcp_f32_e32 v58, v58
	v_exp_f32_e32 v55, v55
	v_sqrt_f32_e32 v189, v189
	v_exp_f32_e32 v57, v57
	v_add_f32_e32 v56, 1.0, v56
	v_add_f32_e32 v59, 1.0, v59
	v_fma_f32 v190, -v55, v55, 1.0
	v_mul_f32_e32 v58, v58, v189
	v_fmamk_f32 v60, v60, 0xbfb8aa3b, v237
	v_rcp_f32_e32 v56, v56
	v_add_f32_e32 v57, 1.0, v57
	v_rcp_f32_e32 v59, v59
	v_mul_f32_e32 v58, v58, v185
	v_sqrt_f32_e32 v185, v190
	v_exp_f32_e32 v60, v60
	v_rcp_f32_e32 v57, v57
	v_mul_f32_e32 v56, v218, v56
	v_fmamk_f32 v187, v61, 0xbfb8aa3b, v237
	v_mul_f32_e32 v185, v59, v185
	v_add_f32_e32 v59, 1.0, v60
	v_exp_f32_e32 v56, v56
	v_exp_f32_e32 v61, v187
	v_mul_f32_e32 v57, v218, v57
	v_rcp_f32_e32 v60, v59
	v_exp_f32_e32 v59, v57
	v_fma_f32 v186, -v56, v56, 1.0
	v_add_f32_e32 v57, 1.0, v61
	v_sqrt_f32_e32 v186, v186
	v_rcp_f32_e32 v61, v57
	v_fma_f32 v57, -v59, v59, 1.0
	v_sqrt_f32_e32 v187, v57
	v_mul_f32_e32 v60, v60, v186
	v_mul_f32_e32 v60, v60, v177
	v_mul_f32_e32 v177, v59, v56
	v_mul_f32_e32 v61, v61, v187
	v_mul_f32_e32 v61, v61, v184
	v_mul_f32_e32 v177, v55, v177
	v_mul_f32_e32 v186, v54, v177
	v_fma_f32 v177, 0, v59, v61
	v_mul_f32_e32 v57, v185, v183
	v_fma_f32 v177, v56, v177, v60
	v_fma_f32 v177, v55, v177, v57
	v_fma_f32 v189, v54, v177, v58
	v_mov_b32_e32 v188, v186
	v_mov_b32_e32 v177, v189
	s_nop 0
	v_permlane16_swap_b32_e32 v186, v188
	v_permlane16_swap_b32_e32 v189, v177
	v_mov_b32_e32 v183, v188
	v_mov_b32_e32 v185, v177
	v_mov_b32_e32 v187, v186
	v_permlane32_swap_b32_e32 v188, v183
	v_mov_b32_e32 v184, v189
	v_permlane32_swap_b32_e32 v177, v185
	v_permlane32_swap_b32_e32 v186, v187
	v_permlane32_swap_b32_e32 v189, v184
	v_fmac_f32_e32 v184, v185, v187
	v_mul_f32_e32 v187, v187, v183
	v_fmac_f32_e32 v177, v184, v188
	v_mul_f32_e32 v188, v187, v188
	s_and_saveexec_b64 s[28:29], s[10:11]
	v_mul_f32_e32 v191, v177, v186
	v_mul_f32_e32 v190, v188, v186
	v_add_f32_e32 v191, v191, v189
	ds_write_b64 v150, v[190:191] offset:53248
	s_or_b64 exec, exec, s[28:29]
	v_lshlrev_b32_e32 v197, 16, v219
	v_lshlrev_b32_e32 v195, 16, v220
	v_lshlrev_b32_e32 v194, 16, v221
	v_fmamk_f32 v46, v46, 0xbfb8aa3b, v238
	v_exp_f32_e32 v46, v46
	v_fmamk_f32 v47, v47, 0xbfb8aa3b, v238
	v_fmamk_f32 v50, v50, 0xbfb8aa3b, v239
	v_exp_f32_e32 v47, v47
	v_add_f32_e32 v46, 1.0, v46
	v_rcp_f32_e32 v46, v46
	v_exp_f32_e32 v50, v50
	v_add_f32_e32 v47, 1.0, v47
	v_rcp_f32_e32 v47, v47
	v_mul_f32_e32 v46, v223, v46
	v_add_f32_e32 v186, 1.0, v50
	v_exp_f32_e32 v50, v46
; template <bool PASS_C>
; DEVI void lru_item(const P& p, int item, int next_item, uint4& u0, uint4& u1, uint4& u2, float& cpre, char* smem) {
;     ...
;         for (int d = 0; d < 2; ++d) {
;             const float ba = prm[(5 + d) * 64 + ch], bx = prm[(7 + d) * 64 + ch], nsp8 = prm[(9 + d) * 64 + ch];
; #pragma unroll
;             for (int j = 0; j < 4; ++j) {
;                 const float r = __builtin_amdgcn_rcpf(1.0f + __builtin_amdgcn_exp2f(__builtin_fmaf(acc[(2 * d) * 4 + nn][j], -LOG2E, ba)));
;                 const float ig = __builtin_amdgcn_rcpf(1.0f + __builtin_amdgcn_exp2f(__builtin_fmaf(acc[(2 * d + 1) * 4 + nn][j], -LOG2E, bx)));
;                 const float a_ = __builtin_amdgcn_exp2f(nsp8 * r);
;                 av[nn][d][j] = a_;
;                 bv[nn][d][j] = __builtin_amdgcn_sqrtf(__builtin_fmaf(-a_, a_, 1.0f)) * ig * uc[j];
;             }
;             float A = 1.f, Bq = 0.f;
;             if (d == 0) {
; #pragma unroll
;                 for (int j = 0; j < 4; ++j) { Bq = av[nn][d][j] * Bq + bv[nn][d][j]; A *= av[nn][d][j]; }
;             } else {
; #pragma unroll
;                 for (int j = 3; j >= 0; --j) { Bq = av[nn][d][j] * Bq + bv[nn][d][j]; A *= av[nn][d][j]; }
;             }
;             float Ag[4], Bg[4];
;             rowgather4(A, Ag); rowgather4(Bq, Bg);
;             float AW = 1.f, BW = 0.f, AP = 1.f, BP = 0.f;
;             if (d == 0) {
; #pragma unroll
;                 for (int g = 0; g < 4; ++g) {
;                     if (g == fq) { AP = AW; BP = BW; }
;                     BW = Ag[g] * BW + Bg[g]; AW *= Ag[g];
;                 }
;             } else {
; #pragma unroll
;                 for (int g = 3; g >= 0; --g) {
;                     if (g == fq) { AP = AW; BP = BW; }
;                     BW = Ag[g] * BW + Bg[g]; AW *= Ag[g];
;                 }
;             }
;             apre[nn][d] = AP; bpre[nn][d] = BP;
;             if (fq == 0) { wagg[((w * 2 + d) * 64 + ch) * 2 + 0] = AW; wagg[((w * 2 + d) * 64 + ch) * 2 + 1] = BW; }
;         }
	v_rcp_f32_e32 v46, v186
	v_fmamk_f32 v51, v51, 0xbfb8aa3b, v239
	v_mul_f32_e32 v47, v223, v47
	v_fma_f32 v186, -v50, v50, 1.0
	v_sqrt_f32_e32 v186, v186
	v_exp_f32_e32 v51, v51
	v_exp_f32_e32 v47, v47
	v_fmamk_f32 v48, v48, 0xbfb8aa3b, v238
	v_exp_f32_e32 v48, v48
	v_mul_f32_e32 v46, v46, v186
	v_add_f32_e32 v51, 1.0, v51
	v_fma_f32 v186, -v47, v47, 1.0
	v_rcp_f32_e32 v51, v51
	v_sqrt_f32_e32 v186, v186
	v_add_f32_e32 v48, 1.0, v48
	v_rcp_f32_e32 v48, v48
	v_fmamk_f32 v49, v49, 0xbfb8aa3b, v238
	v_mul_f32_e32 v51, v51, v186
	v_exp_f32_e32 v186, v49
	v_mul_f32_e32 v48, v223, v48
	v_exp_f32_e32 v49, v48
	v_fmamk_f32 v52, v52, 0xbfb8aa3b, v239
	v_add_f32_e32 v48, 1.0, v186
	v_rcp_f32_e32 v48, v48
	v_fmamk_f32 v191, v53, 0xbfb8aa3b, v239
	v_exp_f32_e32 v189, v191
	v_exp_f32_e32 v52, v52
	v_mul_f32_e32 v48, v223, v48
	v_exp_f32_e32 v53, v48
	v_add_f32_e32 v48, 1.0, v189
	v_add_f32_e32 v52, 1.0, v52
	v_fma_f32 v186, -v49, v49, 1.0
	v_rcp_f32_e32 v189, v48
	v_fma_f32 v48, -v53, v53, 1.0
	v_rcp_f32_e32 v52, v52
	v_sqrt_f32_e32 v186, v186
	v_sqrt_f32_e32 v190, v48
	v_mul_f32_e32 v46, v46, v197
	v_mul_f32_e32 v48, v51, v195
	v_mul_f32_e32 v51, v52, v186
	v_mul_f32_e32 v52, v189, v190
	v_fma_f32 v189, 0, v50, v46
	v_lshlrev_b32_e32 v196, 16, v222
	v_mul_f32_e32 v51, v51, v194
	v_mul_f32_e32 v186, v50, v47
	v_fma_f32 v189, v47, v189, v48
	v_mul_f32_e32 v52, v52, v196
	v_mul_f32_e32 v186, v49, v186
	v_fma_f32 v189, v49, v189, v51
	v_mul_f32_e32 v186, v53, v186
	v_fma_f32 v189, v53, v189, v52
	v_mov_b32_e32 v192, v186
	v_mov_b32_e32 v190, v189
	s_nop 0
	v_permlane16_swap_b32_e32 v186, v192
	v_permlane16_swap_b32_e32 v189, v190
	v_mov_b32_e32 v193, v186
	v_mov_b32_e32 v191, v189
	s_nop 0
	v_permlane32_swap_b32_e32 v186, v193
	v_mov_b32_e32 v199, v192
	v_permlane32_swap_b32_e32 v189, v191
	v_mov_b32_e32 v200, v190
	v_permlane32_swap_b32_e32 v192, v199
	s_nop 0
	v_permlane32_swap_b32_e32 v190, v200
	v_fmac_f32_e32 v190, v189, v192
	v_mul_f32_e32 v192, v186, v192
	v_fmac_f32_e32 v191, v190, v193
	v_mul_f32_e32 v193, v192, v193
	s_and_saveexec_b64 s[28:29], s[10:11]
	v_mul_f32_e32 v201, v191, v199
	v_mul_f32_e32 v202, v193, v199
	v_add_f32_e32 v203, v201, v200
	ds_write_b64 v151, v[202:203] offset:52736
	s_or_b64 exec, exec, s[28:29]
	v_fmamk_f32 v38, v38, 0xbfb8aa3b, v240
	v_exp_f32_e32 v38, v38
	v_fmamk_f32 v39, v39, 0xbfb8aa3b, v240
	v_exp_f32_e32 v39, v39
	v_fmamk_f32 v42, v42, 0xbfb8aa3b, v241
	v_add_f32_e32 v38, 1.0, v38
	v_rcp_f32_e32 v38, v38
	v_add_f32_e32 v39, 1.0, v39
	v_exp_f32_e32 v42, v42
	v_rcp_f32_e32 v39, v39
	v_mul_f32_e32 v38, v224, v38
	v_exp_f32_e32 v38, v38
	v_fmamk_f32 v40, v40, 0xbfb8aa3b, v240
	v_fmamk_f32 v43, v43, 0xbfb8aa3b, v241
	v_add_f32_e32 v42, 1.0, v42
	v_mul_f32_e32 v39, v224, v39
	v_fma_f32 v201, -v38, v38, 1.0
	v_exp_f32_e32 v40, v40
	v_fmamk_f32 v41, v41, 0xbfb8aa3b, v240
	v_exp_f32_e32 v43, v43
	v_rcp_f32_e32 v42, v42
	v_exp_f32_e32 v39, v39
	v_sqrt_f32_e32 v201, v201
	v_exp_f32_e32 v41, v41
	v_add_f32_e32 v40, 1.0, v40
	v_add_f32_e32 v43, 1.0, v43
	v_fma_f32 v202, -v39, v39, 1.0
	v_mul_f32_e32 v42, v42, v201
	v_fmamk_f32 v44, v44, 0xbfb8aa3b, v241
	v_rcp_f32_e32 v40, v40
	v_add_f32_e32 v41, 1.0, v41
	v_rcp_f32_e32 v43, v43
	v_mul_f32_e32 v42, v42, v197
	v_sqrt_f32_e32 v197, v202
	v_exp_f32_e32 v44, v44
	v_rcp_f32_e32 v41, v41
	v_mul_f32_e32 v40, v224, v40
	v_fmamk_f32 v199, v45, 0xbfb8aa3b, v241
	v_mul_f32_e32 v197, v43, v197
	v_add_f32_e32 v43, 1.0, v44
	v_exp_f32_e32 v40, v40
	v_exp_f32_e32 v45, v199
	v_mul_f32_e32 v41, v224, v41
	v_rcp_f32_e32 v44, v43
	v_exp_f32_e32 v43, v41
	v_fma_f32 v198, -v40, v40, 1.0
	v_add_f32_e32 v41, 1.0, v45
	v_sqrt_f32_e32 v198, v198
	v_rcp_f32_e32 v45, v41
	v_fma_f32 v41, -v43, v43, 1.0
	v_sqrt_f32_e32 v199, v41
	v_mul_f32_e32 v44, v44, v198
	v_mul_f32_e32 v44, v44, v194
	v_mul_f32_e32 v194, v43, v40
	v_mul_f32_e32 v45, v45, v199
	v_mul_f32_e32 v45, v45, v196
	v_mul_f32_e32 v194, v39, v194
	v_mul_f32_e32 v198, v38, v194
	v_fma_f32 v194, 0, v43, v45
	v_mul_f32_e32 v41, v197, v195
	v_fma_f32 v194, v40, v194, v44
	v_fma_f32 v194, v39, v194, v41
	v_fma_f32 v200, v38, v194, v42
	v_mov_b32_e32 v201, v198
	v_mov_b32_e32 v194, v200
	s_nop 0
	v_permlane16_swap_b32_e32 v198, v201
	v_permlane16_swap_b32_e32 v200, v194
	v_mov_b32_e32 v195, v201
	v_mov_b32_e32 v197, v194
	v_mov_b32_e32 v199, v198
	v_permlane32_swap_b32_e32 v201, v195
	v_mov_b32_e32 v196, v200
	v_permlane32_swap_b32_e32 v194, v197
	v_permlane32_swap_b32_e32 v198, v199
	v_permlane32_swap_b32_e32 v200, v196
	v_fmac_f32_e32 v196, v197, v199
	v_mul_f32_e32 v199, v199, v195
	v_fmac_f32_e32 v194, v196, v201
	v_mul_f32_e32 v201, v199, v201
	s_and_saveexec_b64 s[28:29], s[10:11]
	v_mul_f32_e32 v203, v194, v198
	v_mul_f32_e32 v202, v201, v198
	v_add_f32_e32 v203, v203, v200
	ds_write_b64 v151, v[202:203] offset:53248
	s_or_b64 exec, exec, s[28:29]
	v_lshlrev_b32_e32 v209, 16, v225
	v_lshlrev_b32_e32 v207, 16, v226
	v_lshlrev_b32_e32 v206, 16, v227
	v_fmamk_f32 v30, v30, 0xbfb8aa3b, v242
	v_exp_f32_e32 v30, v30
	v_fmamk_f32 v31, v31, 0xbfb8aa3b, v242
	v_fmamk_f32 v34, v34, 0xbfb8aa3b, v243
	v_exp_f32_e32 v31, v31
	v_add_f32_e32 v30, 1.0, v30
	v_rcp_f32_e32 v30, v30
	v_exp_f32_e32 v34, v34
	v_add_f32_e32 v31, 1.0, v31
	v_rcp_f32_e32 v31, v31
	v_mul_f32_e32 v30, v229, v30
	v_add_f32_e32 v198, 1.0, v34
	v_exp_f32_e32 v34, v30
	v_rcp_f32_e32 v30, v198
	v_fmamk_f32 v35, v35, 0xbfb8aa3b, v243
	v_mul_f32_e32 v31, v229, v31
	v_fma_f32 v198, -v34, v34, 1.0
	v_sqrt_f32_e32 v198, v198
	v_exp_f32_e32 v35, v35
	v_exp_f32_e32 v31, v31
	v_fmamk_f32 v32, v32, 0xbfb8aa3b, v242
	v_exp_f32_e32 v32, v32
	v_mul_f32_e32 v30, v30, v198
	v_add_f32_e32 v35, 1.0, v35
; template <bool PASS_C>
; DEVI void lru_item(const P& p, int item, int next_item, uint4& u0, uint4& u1, uint4& u2, float& cpre, char* smem) {
;     ...
;         for (int d = 0; d < 2; ++d) {
;             const float ba = prm[(5 + d) * 64 + ch], bx = prm[(7 + d) * 64 + ch], nsp8 = prm[(9 + d) * 64 + ch];
; #pragma unroll
;             for (int j = 0; j < 4; ++j) {
;                 const float r = __builtin_amdgcn_rcpf(1.0f + __builtin_amdgcn_exp2f(__builtin_fmaf(acc[(2 * d) * 4 + nn][j], -LOG2E, ba)));
;                 const float ig = __builtin_amdgcn_rcpf(1.0f + __builtin_amdgcn_exp2f(__builtin_fmaf(acc[(2 * d + 1) * 4 + nn][j], -LOG2E, bx)));
;                 const float a_ = __builtin_amdgcn_exp2f(nsp8 * r);
;                 av[nn][d][j] = a_;
;                 bv[nn][d][j] = __builtin_amdgcn_sqrtf(__builtin_fmaf(-a_, a_, 1.0f)) * ig * uc[j];
;             }
;             float A = 1.f, Bq = 0.f;
;             if (d == 0) {
; #pragma unroll
;                 for (int j = 0; j < 4; ++j) { Bq = av[nn][d][j] * Bq + bv[nn][d][j]; A *= av[nn][d][j]; }
;             } else {
; #pragma unroll
;                 for (int j = 3; j >= 0; --j) { Bq = av[nn][d][j] * Bq + bv[nn][d][j]; A *= av[nn][d][j]; }
;             }
;             float Ag[4], Bg[4];
;             rowgather4(A, Ag); rowgather4(Bq, Bg);
;             float AW = 1.f, BW = 0.f, AP = 1.f, BP = 0.f;
;             if (d == 0) {
; #pragma unroll
;                 for (int g = 0; g < 4; ++g) {
;                     if (g == fq) { AP = AW; BP = BW; }
;                     BW = Ag[g] * BW + Bg[g]; AW *= Ag[g];
;                 }
;             } else {
; #pragma unroll
;                 for (int g = 3; g >= 0; --g) {
;                     if (g == fq) { AP = AW; BP = BW; }
;                     BW = Ag[g] * BW + Bg[g]; AW *= Ag[g];
;                 }
;             }
;             apre[nn][d] = AP; bpre[nn][d] = BP;
;             if (fq == 0) { wagg[((w * 2 + d) * 64 + ch) * 2 + 0] = AW; wagg[((w * 2 + d) * 64 + ch) * 2 + 1] = BW; }
;         }
	v_fma_f32 v198, -v31, v31, 1.0
	v_rcp_f32_e32 v35, v35
	v_sqrt_f32_e32 v198, v198
	v_add_f32_e32 v32, 1.0, v32
	v_rcp_f32_e32 v32, v32
	v_fmamk_f32 v33, v33, 0xbfb8aa3b, v242
	v_mul_f32_e32 v35, v35, v198
	v_exp_f32_e32 v198, v33
	v_mul_f32_e32 v32, v229, v32
	v_exp_f32_e32 v33, v32
	v_fmamk_f32 v36, v36, 0xbfb8aa3b, v243
	v_add_f32_e32 v32, 1.0, v198
	v_rcp_f32_e32 v32, v32
	v_fmamk_f32 v203, v37, 0xbfb8aa3b, v243
	v_exp_f32_e32 v200, v203
	v_exp_f32_e32 v36, v36
	v_mul_f32_e32 v32, v229, v32
	v_exp_f32_e32 v37, v32
	v_add_f32_e32 v32, 1.0, v200
	v_add_f32_e32 v36, 1.0, v36
	v_fma_f32 v198, -v33, v33, 1.0
	v_rcp_f32_e32 v200, v32
	v_fma_f32 v32, -v37, v37, 1.0
	v_rcp_f32_e32 v36, v36
	v_sqrt_f32_e32 v198, v198
	v_sqrt_f32_e32 v202, v32
	v_mul_f32_e32 v30, v30, v209
	v_mul_f32_e32 v32, v35, v207
	v_mul_f32_e32 v35, v36, v198
	v_mul_f32_e32 v36, v200, v202
	v_fma_f32 v200, 0, v34, v30
	v_lshlrev_b32_e32 v208, 16, v228
	v_mul_f32_e32 v35, v35, v206
	v_mul_f32_e32 v198, v34, v31
	v_fma_f32 v200, v31, v200, v32
	v_mul_f32_e32 v36, v36, v208
	v_mul_f32_e32 v198, v33, v198
	v_fma_f32 v200, v33, v200, v35
	v_mul_f32_e32 v198, v37, v198
	v_fma_f32 v200, v37, v200, v36
	v_mov_b32_e32 v204, v198
	v_mov_b32_e32 v202, v200
	s_nop 0
	v_permlane16_swap_b32_e32 v198, v204
	v_permlane16_swap_b32_e32 v200, v202
	v_mov_b32_e32 v205, v198
	v_mov_b32_e32 v203, v200
	s_nop 0
	v_permlane32_swap_b32_e32 v198, v205
	v_mov_b32_e32 v211, v204
	v_permlane32_swap_b32_e32 v200, v203
	v_mov_b32_e32 v212, v202
	v_permlane32_swap_b32_e32 v204, v211
	s_nop 0
	v_permlane32_swap_b32_e32 v202, v212
	v_fmac_f32_e32 v202, v200, v204
	v_mul_f32_e32 v204, v198, v204
	v_fmac_f32_e32 v203, v202, v205
	v_mul_f32_e32 v205, v204, v205
	s_and_saveexec_b64 s[28:29], s[10:11]
	v_mul_f32_e32 v213, v203, v211
	v_mul_f32_e32 v214, v205, v211
	v_add_f32_e32 v215, v213, v212
	ds_write_b64 v152, v[214:215] offset:52736
	s_or_b64 exec, exec, s[28:29]
	v_fmamk_f32 v22, v22, 0xbfb8aa3b, v244
	v_exp_f32_e32 v22, v22
	v_fmamk_f32 v23, v23, 0xbfb8aa3b, v244
	v_exp_f32_e32 v23, v23
	v_fmamk_f32 v26, v26, 0xbfb8aa3b, v245
	v_add_f32_e32 v22, 1.0, v22
	v_rcp_f32_e32 v22, v22
	v_add_f32_e32 v23, 1.0, v23
	v_exp_f32_e32 v26, v26
	v_rcp_f32_e32 v23, v23
	v_mul_f32_e32 v22, v231, v22
	v_exp_f32_e32 v22, v22
	v_fmamk_f32 v24, v24, 0xbfb8aa3b, v244
	v_fmamk_f32 v27, v27, 0xbfb8aa3b, v245
	v_add_f32_e32 v26, 1.0, v26
	v_mul_f32_e32 v23, v231, v23
	v_fma_f32 v213, -v22, v22, 1.0
	v_exp_f32_e32 v24, v24
	v_fmamk_f32 v25, v25, 0xbfb8aa3b, v244
	v_exp_f32_e32 v27, v27
	v_rcp_f32_e32 v26, v26
	v_exp_f32_e32 v23, v23
	v_sqrt_f32_e32 v213, v213
	v_exp_f32_e32 v25, v25
	v_add_f32_e32 v24, 1.0, v24
	v_add_f32_e32 v27, 1.0, v27
	v_fma_f32 v214, -v23, v23, 1.0
	v_mul_f32_e32 v26, v26, v213
	v_fmamk_f32 v28, v28, 0xbfb8aa3b, v245
	v_rcp_f32_e32 v24, v24
	v_add_f32_e32 v25, 1.0, v25
	v_rcp_f32_e32 v27, v27
	v_mul_f32_e32 v26, v26, v209
	v_sqrt_f32_e32 v209, v214
	v_exp_f32_e32 v28, v28
	v_rcp_f32_e32 v25, v25
	v_mul_f32_e32 v24, v231, v24
	v_fmamk_f32 v211, v29, 0xbfb8aa3b, v245
	v_mul_f32_e32 v209, v27, v209
	v_add_f32_e32 v27, 1.0, v28
	v_exp_f32_e32 v24, v24
	v_exp_f32_e32 v29, v211
	v_mul_f32_e32 v25, v231, v25
	v_rcp_f32_e32 v28, v27
	v_exp_f32_e32 v27, v25
	v_fma_f32 v210, -v24, v24, 1.0
	v_add_f32_e32 v25, 1.0, v29
	v_sqrt_f32_e32 v210, v210
	v_rcp_f32_e32 v29, v25
	v_fma_f32 v25, -v27, v27, 1.0
	v_sqrt_f32_e32 v211, v25
	v_mul_f32_e32 v28, v28, v210
	v_mul_f32_e32 v28, v28, v206
	v_mul_f32_e32 v206, v27, v24
	v_mul_f32_e32 v29, v29, v211
	v_mul_f32_e32 v29, v29, v208
	v_mul_f32_e32 v206, v23, v206
	v_mul_f32_e32 v212, v22, v206
	v_fma_f32 v206, 0, v27, v29
	v_mul_f32_e32 v25, v209, v207
	v_fma_f32 v206, v24, v206, v28
	v_fma_f32 v206, v23, v206, v25
	v_fma_f32 v213, v22, v206, v26
	v_mov_b32_e32 v211, v212
	v_mov_b32_e32 v207, v213
	s_nop 0
	v_permlane16_swap_b32_e32 v212, v211
	v_permlane16_swap_b32_e32 v213, v207
	v_mov_b32_e32 v206, v211
	v_mov_b32_e32 v209, v207
	v_mov_b32_e32 v210, v212
	v_permlane32_swap_b32_e32 v211, v206
	v_mov_b32_e32 v208, v213
	v_permlane32_swap_b32_e32 v207, v209
	v_permlane32_swap_b32_e32 v212, v210
	v_permlane32_swap_b32_e32 v213, v208
	v_fmac_f32_e32 v208, v209, v210
	v_mul_f32_e32 v210, v210, v206
	v_fmac_f32_e32 v207, v208, v211
	v_mul_f32_e32 v211, v210, v211
	s_and_saveexec_b64 s[28:29], s[10:11]
	v_mul_f32_e32 v214, v207, v212
	v_mul_f32_e32 v212, v211, v212
	v_add_f32_e32 v213, v214, v213
	ds_write_b64 v152, v[212:213] offset:53248
	s_or_b64 exec, exec, s[28:29]
	s_waitcnt lgkmcnt(0)
	s_barrier
; template <bool PASS_C>
; DEVI void lru_item(const P& p, int item, int next_item, uint4& u0, uint4& u1, uint4& u2, float& cpre, char* smem) {
;     ...
; #pragma unroll
;         for (int nn = 0; nn < 4; ++nn) {
;             const int ch = 16 * nn + fr;
;             float y[4];
;             {
;                 float hw = carry[ch];
; #pragma unroll
;                 for (int ww = 0; ww < 4; ++ww)
;                     if (ww < w) hw = wagg[((ww * 2 + 0) * 64 + ch) * 2] * hw + wagg[((ww * 2 + 0) * 64 + ch) * 2 + 1];
;                 float hh = apre[nn][0] * hw + bpre[nn][0];
; #pragma unroll
;                 for (int j = 0; j < 4; ++j) { hh = av[nn][0][j] * hh + bv[nn][0][j]; y[j] = hh; }
;             }
;             {
;                 float hw = carry[64 + ch];
; #pragma unroll
;     ...
;                     if (ww > w) hw = wagg[((ww * 2 + 1) * 64 + ch) * 2] * hw + wagg[((ww * 2 + 1) * 64 + ch) * 2 + 1];
;                 float hh = apre[nn][1] * hw + bpre[nn][1];
; #pragma unroll
;                 for (int j = 3; j >= 0; --j) { hh = av[nn][1][j] * hh + bv[nn][1][j]; y[j] += hh; }
;             }
; #pragma unroll
;             for (int j = 0; j < 4; ++j) ytile[(16 * w + 4 * fq + j) * 66 + ch] = y[j];
;         }
	ds_read_b32 v244, v122 offset:56832
	ds_read_b32 v245, v122 offset:57088
	ds_read_b64 v[232:233], v123 offset:52736
	ds_read_b64 v[234:235], v123 offset:53760
	ds_read_b64 v[236:237], v123 offset:54784
	ds_read_b64 v[238:239], v123 offset:56320
	ds_read_b64 v[240:241], v123 offset:55296
	ds_read_b64 v[242:243], v123 offset:54272
	ds_read_b32 v246, v122 offset:56896
	ds_read_b32 v247, v122 offset:57152
	ds_read_b64 v[218:219], v154 offset:52736
	ds_read_b64 v[220:221], v154 offset:53760
	ds_read_b64 v[222:223], v154 offset:54784
	ds_read_b64 v[224:225], v154 offset:56320
	ds_read_b64 v[226:227], v154 offset:55296
	ds_read_b64 v[228:229], v154 offset:54272
	s_waitcnt lgkmcnt(8)
	v_fma_f32 v248, v232, v244, v233
	v_cndmask_b32_e64 v212, v244, v248, s[4:5]
	v_fma_f32 v248, v234, v212, v235
	v_cndmask_b32_e64 v212, v212, v248, s[18:19]
	v_fma_f32 v248, v236, v212, v237
	v_cndmask_b32_e64 v212, v212, v248, s[20:21]
	v_fma_f32 v248, v238, v245, v239
	v_cndmask_b32_e64 v213, v245, v248, s[24:25]
	v_fma_f32 v248, v240, v213, v241
	v_cndmask_b32_e64 v213, v213, v248, s[8:9]
	v_fma_f32 v248, v242, v213, v243
	v_cndmask_b32_e64 v213, v213, v248, s[2:3]
	v_cndmask_b32_e64 v103, 1.0, v103, s[12:13]
	v_cndmask_b32_e64 v105, 0, v105, s[12:13]
	v_cndmask_b32_e64 v103, v103, v159, s[14:15]
	v_cndmask_b32_e64 v105, v105, v157, s[14:15]
	v_cndmask_b32_e64 v103, v103, v160, s[16:17]
	v_cndmask_b32_e64 v105, v105, v158, s[16:17]
	v_fmac_f32_e32 v105, v103, v212
	v_fmac_f32_e32 v87, v89, v105
	v_fmac_f32_e32 v93, v91, v87
	v_cndmask_b32_e64 v89, 1.0, v162, s[14:15]
	v_cndmask_b32_e64 v91, 0, v164, s[14:15]
	v_cndmask_b32_e64 v89, v89, v166, s[12:13]
	v_cndmask_b32_e64 v91, v91, v163, s[12:13]
	v_cndmask_b32_e64 v89, v89, v167, s[10:11]
	v_cndmask_b32_e64 v91, v91, v161, s[10:11]
	v_fmac_f32_e32 v91, v89, v213
	v_fmac_f32_e32 v77, v75, v91
	v_fmac_f32_e32 v76, v72, v77
	v_fmac_f32_e32 v73, v71, v76
	v_fmac_f32_e32 v97, v95, v93
	v_fmac_f32_e32 v74, v70, v73
	v_fmac_f32_e32 v99, v101, v97
	v_add_f32_e32 v71, v93, v73
	v_add_f32_e32 v73, v87, v74
	v_add_u32_e32 v70, 0x8c00, v153
	v_add_f32_e32 v75, v99, v77
	v_add_f32_e32 v72, v97, v76
	ds_write2_b32 v70, v73, v71 offset1:66
	ds_write2_b32 v70, v72, v75 offset0:132 offset1:198
	ds_read_b32 v244, v122 offset:56960
	ds_read_b32 v245, v122 offset:57216
	ds_read_b64 v[232:233], v155 offset:52736
	ds_read_b64 v[234:235], v155 offset:53760
	ds_read_b64 v[236:237], v155 offset:54784
	ds_read_b64 v[238:239], v155 offset:56320
	ds_read_b64 v[240:241], v155 offset:55296
	ds_read_b64 v[242:243], v155 offset:54272
	s_waitcnt lgkmcnt(10)
	v_fma_f32 v248, v218, v246, v219
	v_cndmask_b32_e64 v71, v246, v248, s[4:5]
	v_fma_f32 v248, v220, v71, v221
	v_cndmask_b32_e64 v71, v71, v248, s[18:19]
	v_fma_f32 v248, v222, v71, v223
	v_cndmask_b32_e64 v71, v71, v248, s[20:21]
	v_fma_f32 v248, v224, v247, v225
	v_cndmask_b32_e64 v72, v247, v248, s[24:25]
	v_fma_f32 v248, v226, v72, v227
	v_cndmask_b32_e64 v72, v72, v248, s[8:9]
	v_fma_f32 v248, v228, v72, v229
	v_cndmask_b32_e64 v72, v72, v248, s[2:3]
	v_cndmask_b32_e64 v73, 1.0, v165, s[12:13]
	v_cndmask_b32_e64 v74, 0, v168, s[12:13]
	v_cndmask_b32_e64 v73, v73, v171, s[14:15]
	v_cndmask_b32_e64 v74, v74, v169, s[14:15]
	v_cndmask_b32_e64 v73, v73, v173, s[16:17]
	v_cndmask_b32_e64 v74, v74, v170, s[16:17]
	v_fmac_f32_e32 v74, v73, v71
	v_fmac_f32_e32 v62, v66, v74
	v_fmac_f32_e32 v64, v63, v62
	v_fmac_f32_e32 v67, v65, v64
	v_cndmask_b32_e64 v63, 1.0, v183, s[14:15]
	v_cndmask_b32_e64 v65, 0, v185, s[14:15]
	v_cndmask_b32_e64 v63, v63, v187, s[12:13]
	v_cndmask_b32_e64 v65, v65, v184, s[12:13]
	v_cndmask_b32_e64 v63, v63, v188, s[10:11]
	v_cndmask_b32_e64 v65, v65, v177, s[10:11]
	v_fmac_f32_e32 v65, v63, v72
	v_fmac_f32_e32 v61, v59, v65
	v_fmac_f32_e32 v60, v56, v61
	v_fmac_f32_e32 v57, v55, v60
	v_fmac_f32_e32 v58, v54, v57
	v_fmac_f32_e32 v68, v69, v67
	v_add_f32_e32 v55, v64, v57
	v_add_f32_e32 v54, v62, v58
	v_add_f32_e32 v59, v68, v61
	v_add_f32_e32 v56, v67, v60
	ds_write2_b32 v70, v54, v55 offset0:16 offset1:82
	ds_write2_b32 v70, v56, v59 offset0:148 offset1:214
	ds_read_b32 v246, v122 offset:57024
	ds_read_b32 v247, v122 offset:57280
	ds_read_b64 v[218:219], v156 offset:52736
	ds_read_b64 v[220:221], v156 offset:53760
	ds_read_b64 v[222:223], v156 offset:54784
	ds_read_b64 v[224:225], v156 offset:56320
	ds_read_b64 v[226:227], v156 offset:55296
	ds_read_b64 v[228:229], v156 offset:54272
	s_waitcnt lgkmcnt(10)
	v_fma_f32 v248, v232, v244, v233
	v_cndmask_b32_e64 v54, v244, v248, s[4:5]
	v_fma_f32 v248, v234, v54, v235
	v_cndmask_b32_e64 v54, v54, v248, s[18:19]
	v_fma_f32 v248, v236, v54, v237
	v_cndmask_b32_e64 v54, v54, v248, s[20:21]
	v_fma_f32 v248, v238, v245, v239
	v_cndmask_b32_e64 v55, v245, v248, s[24:25]
	v_fma_f32 v248, v240, v55, v241
	v_cndmask_b32_e64 v55, v55, v248, s[8:9]
	v_fma_f32 v248, v242, v55, v243
	v_cndmask_b32_e64 v55, v55, v248, s[2:3]
	v_cndmask_b32_e64 v56, 1.0, v186, s[12:13]
	v_cndmask_b32_e64 v57, 0, v189, s[12:13]
	v_cndmask_b32_e64 v56, v56, v192, s[14:15]
	v_cndmask_b32_e64 v57, v57, v190, s[14:15]
	v_cndmask_b32_e64 v56, v56, v193, s[16:17]
	v_cndmask_b32_e64 v57, v57, v191, s[16:17]
	v_fmac_f32_e32 v57, v56, v54
	v_fmac_f32_e32 v46, v50, v57
	v_fmac_f32_e32 v48, v47, v46
	v_fmac_f32_e32 v51, v49, v48
	v_cndmask_b32_e64 v47, 1.0, v195, s[14:15]
	v_cndmask_b32_e64 v49, 0, v197, s[14:15]
	v_cndmask_b32_e64 v47, v47, v199, s[12:13]
	v_cndmask_b32_e64 v49, v49, v196, s[12:13]
	v_cndmask_b32_e64 v47, v47, v201, s[10:11]
	v_cndmask_b32_e64 v49, v49, v194, s[10:11]
	v_fmac_f32_e32 v49, v47, v55
	v_fmac_f32_e32 v45, v43, v49
	v_fmac_f32_e32 v44, v40, v45
	v_fmac_f32_e32 v41, v39, v44
	v_fmac_f32_e32 v42, v38, v41
	v_fmac_f32_e32 v52, v53, v51
	v_add_f32_e32 v39, v48, v41
	v_add_f32_e32 v38, v46, v42
	v_add_f32_e32 v43, v52, v45
	v_add_f32_e32 v40, v51, v44
	ds_write2_b32 v70, v38, v39 offset0:32 offset1:98
	ds_write2_b32 v70, v40, v43 offset0:164 offset1:230
	s_waitcnt lgkmcnt(2)
	v_fma_f32 v248, v218, v246, v219
	v_cndmask_b32_e64 v38, v246, v248, s[4:5]
	v_fma_f32 v248, v220, v38, v221
	v_cndmask_b32_e64 v38, v38, v248, s[18:19]
	v_fma_f32 v248, v222, v38, v223
	v_cndmask_b32_e64 v38, v38, v248, s[20:21]
	v_fma_f32 v248, v224, v247, v225
	v_cndmask_b32_e64 v39, v247, v248, s[24:25]
	v_fma_f32 v248, v226, v39, v227
	v_cndmask_b32_e64 v39, v39, v248, s[8:9]
	v_fma_f32 v248, v228, v39, v229
	v_cndmask_b32_e64 v39, v39, v248, s[2:3]
	s_branch .LBB0_720

; DEVI int opaque_tid() { int t = (int)threadIdx.x; asm volatile("" : "+v"(t)); return t; }
; template <bool TRANS, class Epi>
; DEVI void gemm_tile(const bf16_t* __restrict__ A0, const bf16_t* __restrict__ A1, int ksplit, int lda,
;                     const bf16_t* __restrict__ Bt, int ldb, int nk, char* smem, const Epi& epi, int row0, int col0) {
;     const int tid = opaque_tid(), lane = tid & 63, w = tid >> 6, wr = w >> 1, wc = w & 1, fr = lane & 15, fq = lane >> 4;
;     f32x4 acc[4][4];
; #pragma unroll
;     for (int m = 0; m < 4; ++m)
; #pragma unroll
;         for (int n = 0; n < 4; ++n) acc[m][n] = (f32x4){0.f, 0.f, 0.f, 0.f};
;     const int srow = w * 8 + (lane >> 3), sch = (lane & 7) ^ ((lane >> 3) & 7);
;     const size_t aoff = (size_t)srow * lda + sch * 8, boff = (size_t)srow * ldb + sch * 8;
;     const int ldsoff = w * 1024 + lane * 16;
;     auto issue = [&](int kt, int buf) {
;         const bf16_t* ap = (kt < ksplit ? A0 + (size_t)kt * 64 : A1 + (size_t)(kt - ksplit) * 64) + aoff;
;         const bf16_t* bp = Bt + (size_t)kt * 64 + boff;
;         char* sa = smem + buf * 32768 + ldsoff;
;         char* sb = sa + 16384;
; #pragma unroll
;         for (int i = 0; i < 4; ++i) __builtin_amdgcn_global_load_lds((const unsigned*)(ap + (size_t)(32 * i) * lda), (unsigned*)(sa + i * 4096), 16, 0, 0);
; #pragma unroll
;         for (int i = 0; i < 4; ++i) __builtin_amdgcn_global_load_lds((const unsigned*)(bp + (size_t)(32 * i) * ldb), (unsigned*)(sb + i * 4096), 16, 0, 0);
;     };
;     __syncthreads();
;     issue(0, 0);
;     asm volatile("s_waitcnt vmcnt(0)" ::: "memory");
;     __syncthreads();
; __global__ void __launch_bounds__(256, 2) fwd_megakernel(P p) {
;     ...
;         for (int L = bid; L < 272 * 8; L += G) {
;             int pm, pn; tile_map(L, 272, 8, pm, pn);
;             gemm_tile<true>(bufA + (size_t)pm * 128 * 1024, bufD + (size_t)pm * 128 * 1024, 16, 1024, WO0T + (size_t)pn * 128 * 2048, 2048, 32, smem, ef, pm * 128, pn * 128);
.LBB0_1191:
	s_and_b32 s0, s15, 7
	s_mulk_i32 s0, 0x110
	s_ashr_i32 s12, s15, 3
	s_add_i32 s0, s0, s12
	s_ashr_i32 s12, s0, 31
	s_lshr_b32 s12, s12, 26
	s_add_i32 s12, s0, s12
	s_ashr_i32 s13, s12, 6
	s_and_b32 s12, s12, 0xffc0
	s_sub_i32 s0, s0, s12
	s_bfe_i32 s12, s0, 0x80000
	s_bfe_u32 s12, s12, 0x3000c
	s_add_i32 s12, s0, s12
	s_bfe_i32 s14, s12, 0x80000
	s_and_b32 s12, s12, 0xf8
	s_sub_i32 s0, s0, s12
	s_lshl_b32 s13, s13, 3
	s_sext_i32_i8 s0, s0
	s_add_i32 s12, s13, s0
	v_mov_b32_e32 v71, v172
	s_sext_i32_i16 s14, s14
	s_ashr_i32 s13, s12, 31
	s_lshr_b32 s14, s14, 3
	v_ashrrev_i32_e32 v3, 6, v71
	v_bfe_u32 v1, v71, 3, 3
	s_lshl_b64 s[18:19], s[12:13], 18
	v_and_b32_e32 v2, 63, v71
	v_lshl_or_b32 v0, v3, 3, v1
	s_add_u32 s16, s90, s18
	v_bitop3_b32 v7, v1, v71, 7 bitop3:0x78
	v_ashrrev_i32_e32 v1, 31, v0
	v_lshlrev_b32_e32 v4, 10, v3
	v_lshlrev_b32_e32 v5, 4, v2
	s_addc_u32 s17, s91, s19
	v_lshlrev_b64 v[66:67], 10, v[0:1]
	v_add3_u32 v75, 0, v4, v5
	s_add_u32 s13, s54, s18
	v_lshl_or_b32 v66, v7, 3, v66
	v_readfirstlane_b32 s0, v75
	v_add_u32_e32 v8, 0x1000, v75
	s_addc_u32 s28, s55, s19
	s_bfe_i64 s[18:19], s[14:15], 0x100000
	v_and_b32_e32 v74, 1, v3
	v_lshl_add_u64 v[2:3], v[66:67], 1, s[16:17]
	s_mov_b32 m0, s0
	v_readfirstlane_b32 s0, v8
	v_add_u32_e32 v8, 0x2000, v75
	s_lshl_b64 s[18:19], s[18:19], 19
	v_readlane_b32 s20, v230, 21
	s_barrier
	global_load_lds_dwordx4 v[2:3], off
	v_lshl_add_u64 v[4:5], v[2:3], 0, s[2:3]
	s_mov_b32 m0, s0
	v_readfirstlane_b32 s0, v8
	v_readlane_b32 s21, v230, 22
	s_add_u32 s18, s20, s18
	global_load_lds_dwordx4 v[4:5], off
	v_lshl_add_u64 v[4:5], v[2:3], 0, s[4:5]
	s_mov_b32 m0, s0
	s_addc_u32 s19, s21, s19
	global_load_lds_dwordx4 v[4:5], off
	v_add_u32_e32 v4, 0x3000, v75
	v_lshlrev_b64 v[0:1], 12, v[0:1]
	v_readfirstlane_b32 s0, v4
	v_lshl_add_u64 v[0:1], s[18:19], 0, v[0:1]
	v_lshlrev_b32_e32 v64, 4, v7
	v_lshl_add_u64 v[2:3], v[2:3], 0, s[6:7]
	s_mov_b32 m0, s0
	v_lshl_add_u64 v[68:69], v[0:1], 0, v[64:65]
	v_add_u32_e32 v0, 0x4000, v75
	global_load_lds_dwordx4 v[2:3], off
	v_readfirstlane_b32 s0, v0
	v_add_u32_e32 v2, 0x5000, v75
	s_mov_b32 m0, s0
	v_readfirstlane_b32 s0, v2
	v_add_u32_e32 v2, 0x6000, v75
	global_load_lds_dwordx4 v[68:69], off
	v_lshl_add_u64 v[0:1], v[68:69], 0, s[4:5]
	s_mov_b32 m0, s0
	v_readfirstlane_b32 s0, v2
	v_add_u32_e32 v2, 0x7000, v75
	global_load_lds_dwordx4 v[0:1], off
	v_lshl_add_u64 v[0:1], v[68:69], 0, s[8:9]
	s_mov_b32 m0, s0
	v_readfirstlane_b32 s0, v2
	global_load_lds_dwordx4 v[0:1], off
	v_lshl_add_u64 v[0:1], v[68:69], 0, s[10:11]
	s_mov_b32 m0, s0
	v_bfe_u32 v70, v71, 4, 2
	global_load_lds_dwordx4 v[0:1], off
	v_and_b32_e32 v73, 15, v71
	v_bitop3_b32 v0, v70, v71, 7 bitop3:0x78
	v_ashrrev_i32_e32 v72, 7, v71
	v_and_b32_e32 v6, 7, v71
	v_lshlrev_b32_e32 v78, 4, v0
	v_lshlrev_b32_e32 v0, 7, v73
	v_lshl_or_b32 v76, v72, 13, v0
	v_lshl_or_b32 v64, v74, 13, v0
	v_bitop3_b32 v0, v70, v6, 4 bitop3:0x36
	v_lshlrev_b32_e32 v77, 4, v0
	s_mov_b32 s0, -15
	s_mov_b64 s[18:19], 0x80
	s_mov_b32 s29, s1
	s_mov_b32 s26, s1
	v_mov_b32_e32 v0, 0
	v_mov_b32_e32 v1, v65
	v_mov_b32_e32 v2, v65
	v_mov_b32_e32 v3, v65
	v_mov_b32_e32 v4, 0
	v_mov_b32_e32 v5, v65
	v_mov_b32_e32 v6, v65
	v_mov_b32_e32 v7, v65
	v_mov_b32_e32 v8, 0
	v_mov_b32_e32 v9, v65
	v_mov_b32_e32 v10, v65
	v_mov_b32_e32 v11, v65
	v_mov_b32_e32 v12, 0
	v_mov_b32_e32 v13, v65
	v_mov_b32_e32 v14, v65
	v_mov_b32_e32 v15, v65
	v_mov_b32_e32 v16, 0
	v_mov_b32_e32 v17, v65
	v_mov_b32_e32 v18, v65
	v_mov_b32_e32 v19, v65
	v_mov_b32_e32 v20, 0
	v_mov_b32_e32 v21, v65
	v_mov_b32_e32 v22, v65
	v_mov_b32_e32 v23, v65
	v_mov_b32_e32 v24, 0
	v_mov_b32_e32 v25, v65
	v_mov_b32_e32 v26, v65
	v_mov_b32_e32 v27, v65
	v_mov_b32_e32 v28, 0
	v_mov_b32_e32 v29, v65
	v_mov_b32_e32 v30, v65
	v_mov_b32_e32 v31, v65
	v_mov_b32_e32 v32, 0
	v_mov_b32_e32 v33, v65
	v_mov_b32_e32 v34, v65
	v_mov_b32_e32 v35, v65
	v_mov_b32_e32 v36, 0
	v_mov_b32_e32 v37, v65
	v_mov_b32_e32 v38, v65
	v_mov_b32_e32 v39, v65
	v_mov_b32_e32 v40, 0
	v_mov_b32_e32 v41, v65
	v_mov_b32_e32 v42, v65
	v_mov_b32_e32 v43, v65
	v_mov_b32_e32 v44, 0
	v_mov_b32_e32 v45, v65
	v_mov_b32_e32 v46, v65
	v_mov_b32_e32 v47, v65
	v_mov_b32_e32 v48, 0
	v_mov_b32_e32 v49, v65
	v_mov_b32_e32 v50, v65
	v_mov_b32_e32 v51, v65
	v_mov_b32_e32 v52, 0
	v_mov_b32_e32 v53, v65
	v_mov_b32_e32 v54, v65
	v_mov_b32_e32 v55, v65
	v_mov_b32_e32 v56, 0
	v_mov_b32_e32 v57, v65
	v_mov_b32_e32 v58, v65
	v_mov_b32_e32 v59, v65
	v_mov_b32_e32 v60, 0
	v_mov_b32_e32 v61, v65
	v_mov_b32_e32 v62, v65
	v_mov_b32_e32 v63, v65
	s_waitcnt vmcnt(0) lgkmcnt(0)
	s_barrier
	s_branch .LBB0_1193

; DEVI int opaque_tid() { int t = (int)threadIdx.x; asm volatile("" : "+v"(t)); return t; }
; template <bool TRANS, class Epi>
; DEVI void gemm_tile(const bf16_t* __restrict__ A0, const bf16_t* __restrict__ A1, int ksplit, int lda,
;                     const bf16_t* __restrict__ Bt, int ldb, int nk, char* smem, const Epi& epi, int row0, int col0) {
;     const int tid = opaque_tid(), lane = tid & 63, w = tid >> 6, wr = w >> 1, wc = w & 1, fr = lane & 15, fq = lane >> 4;
;     f32x4 acc[4][4];
; #pragma unroll
;     for (int m = 0; m < 4; ++m)
; #pragma unroll
;         for (int n = 0; n < 4; ++n) acc[m][n] = (f32x4){0.f, 0.f, 0.f, 0.f};
;     const int srow = w * 8 + (lane >> 3), sch = (lane & 7) ^ ((lane >> 3) & 7);
;     const size_t aoff = (size_t)srow * lda + sch * 8, boff = (size_t)srow * ldb + sch * 8;
;     const int ldsoff = w * 1024 + lane * 16;
;     auto issue = [&](int kt, int buf) {
;         const bf16_t* ap = (kt < ksplit ? A0 + (size_t)kt * 64 : A1 + (size_t)(kt - ksplit) * 64) + aoff;
;         const bf16_t* bp = Bt + (size_t)kt * 64 + boff;
;         char* sa = smem + buf * 32768 + ldsoff;
;         char* sb = sa + 16384;
; #pragma unroll
;         for (int i = 0; i < 4; ++i) __builtin_amdgcn_global_load_lds((const unsigned*)(ap + (size_t)(32 * i) * lda), (unsigned*)(sa + i * 4096), 16, 0, 0);
; #pragma unroll
;         for (int i = 0; i < 4; ++i) __builtin_amdgcn_global_load_lds((const unsigned*)(bp + (size_t)(32 * i) * ldb), (unsigned*)(sb + i * 4096), 16, 0, 0);
;     };
;     __syncthreads();
;     issue(0, 0);
;     asm volatile("s_waitcnt vmcnt(0)" ::: "memory");
;     __syncthreads();
; __global__ void __launch_bounds__(256, 2) fwd_megakernel(P p) {
;     ...
;         for (int L = bid; L < 272 * 18; L += G) {
;             int pm, pn; tile_map(L, 272, 18, pm, pn);
;             const bool isctx = (pm % 34) < 2;
;             if (isctx && (pn < 8 || pn > 9)) continue;
;             gemm_tile<true>(bufA + (size_t)pm * 128 * 1024, bufA, 1 << 30, 1024, W1T + (size_t)pn * 128 * 1024, 1024, 16, smem, ea, pm * 128, pn * 128);
.LBB0_1336:
	s_and_b32 s2, s53, 7
	s_mulk_i32 s2, 0x264
	s_ashr_i32 s3, s53, 3
	s_add_i32 s2, s2, s3
	s_mul_hi_i32 s3, s2, 0x38e38e39
	s_lshr_b32 s4, s3, 31
	s_ashr_i32 s3, s3, 5
	s_add_i32 s3, s3, s4
	s_lshl_b32 s4, s3, 3
	s_mulk_i32 s3, 0x90
	s_sub_i32 s2, s2, s3
	s_bfe_u32 s3, s2, 0x3001c
	s_add_i32 s3, s2, s3
	s_sext_i32_i16 s3, s3
	s_lshr_b32 s3, s3, 3
	s_lshl_b32 s5, s3, 3
	s_sub_i32 s2, s2, s5
	s_sext_i32_i16 s2, s2
	s_add_i32 s2, s4, s2
	s_sext_i32_i16 s4, s3
	s_mul_hi_i32 s3, s2, 0x78787879
	s_lshr_b32 s5, s3, 31
	s_ashr_i32 s3, s3, 4
	s_add_i32 s3, s3, s5
	s_mul_i32 s3, s3, 34
	s_sub_i32 s3, s2, s3
	s_cmp_lt_i32 s3, 2
	s_cselect_b64 s[34:35], -1, 0
	s_add_i32 s3, s4, -10
	s_cmp_lt_u32 s3, -2
	s_cselect_b64 s[36:37], -1, 0
	s_and_b64 s[34:35], s[34:35], s[36:37]
	s_and_b64 vcc, exec, s[34:35]
	s_cbranch_vccnz .LBB0_1335
	v_mov_b32_e32 v70, v172
	s_ashr_i32 s3, s2, 31
	v_ashrrev_i32_e32 v3, 6, v70
	v_bfe_u32 v1, v70, 3, 3
	v_and_b32_e32 v2, 63, v70
	v_lshl_or_b32 v0, v3, 3, v1
	s_lshl_b64 s[34:35], s[2:3], 18
	v_bitop3_b32 v4, v1, v70, 7 bitop3:0x78
	v_ashrrev_i32_e32 v1, 31, v0
	v_lshlrev_b32_e32 v6, 10, v3
	v_lshlrev_b32_e32 v7, 4, v2
	s_add_u32 s36, s90, s34
	v_lshlrev_b64 v[0:1], 11, v[0:1]
	v_lshlrev_b32_e32 v9, 4, v4
	v_add3_u32 v74, 0, v6, v7
	s_addc_u32 s37, s91, s35
	v_and_b32_e32 v73, 1, v3
	v_or_b32_e32 v2, v0, v9
	v_mov_b32_e32 v3, v1
	v_readfirstlane_b32 s3, v74
	v_add_u32_e32 v10, 0x1000, v74
	v_lshl_add_u64 v[4:5], s[36:37], 0, v[2:3]
	s_mov_b32 m0, s3
	v_readfirstlane_b32 s3, v10
	v_add_u32_e32 v10, 0x2000, v74
	s_barrier
	global_load_lds_dwordx4 v[4:5], off
	v_lshl_add_u64 v[6:7], v[4:5], 0, s[8:9]
	s_mov_b32 m0, s3
	v_readfirstlane_b32 s3, v10
	global_load_lds_dwordx4 v[6:7], off
	v_lshl_add_u64 v[6:7], v[4:5], 0, s[10:11]
	s_mov_b32 m0, s3
	s_ashr_i32 s5, s4, 31
	global_load_lds_dwordx4 v[6:7], off
	v_add_u32_e32 v6, 0x3000, v74
	s_lshl_b64 s[44:45], s[4:5], 18
	v_readfirstlane_b32 s3, v6
	v_lshl_add_u64 v[4:5], v[4:5], 0, s[12:13]
	s_mov_b32 m0, s3
	s_add_u32 s56, s58, s44
	global_load_lds_dwordx4 v[4:5], off
	v_add_u32_e32 v4, 0x4000, v74
	s_addc_u32 s57, s59, s45
	v_readfirstlane_b32 s3, v4
	v_add_u32_e32 v6, 0x5000, v74
	v_lshl_add_u64 v[2:3], s[56:57], 0, v[2:3]
	s_mov_b32 m0, s3
	v_readfirstlane_b32 s3, v6
	v_add_u32_e32 v6, 0x6000, v74
	global_load_lds_dwordx4 v[2:3], off
	v_lshl_add_u64 v[4:5], v[2:3], 0, s[8:9]
	s_mov_b32 m0, s3
	v_readfirstlane_b32 s3, v6
	global_load_lds_dwordx4 v[4:5], off
	v_lshl_add_u64 v[4:5], v[2:3], 0, s[10:11]
	s_mov_b32 m0, s3
	v_lshl_add_u64 v[2:3], v[2:3], 0, s[12:13]
	global_load_lds_dwordx4 v[4:5], off
	v_add_u32_e32 v4, 0x7000, v74
	v_bfe_u32 v72, v70, 4, 2
	v_readfirstlane_b32 s3, v4
	s_mov_b32 m0, s3
	v_and_b32_e32 v71, 15, v70
	global_load_lds_dwordx4 v[2:3], off
	v_bitop3_b32 v2, v72, v70, 7 bitop3:0x78
	v_ashrrev_i32_e32 v64, 7, v70
	v_and_b32_e32 v8, 7, v70
	v_lshlrev_b32_e32 v79, 4, v2
	v_lshlrev_b32_e32 v2, 7, v71
	v_lshl_or_b32 v77, v64, 13, v2
	v_lshl_or_b32 v75, v73, 13, v2
	v_bitop3_b32 v2, v72, v8, 4 bitop3:0x36
	v_lshlrev_b32_e32 v78, 4, v2
	v_lshl_add_u64 v[2:3], s[34:35], 0, v[0:1]
	v_lshl_add_u64 v[0:1], s[44:45], 0, v[0:1]
	v_or_b32_e32 v0, v0, v9
	v_or_b32_e32 v2, v2, v9
	v_lshl_add_u64 v[68:69], s[90:91], 0, v[0:1]
	v_mov_b32_e32 v0, 0
	v_lshl_add_u64 v[66:67], s[90:91], 0, v[2:3]
	s_mov_b32 s3, 0
	s_mov_b64 s[34:35], 0
	v_mov_b32_e32 v1, v0
	v_mov_b32_e32 v2, v0
	v_mov_b32_e32 v3, v0
	v_mov_b32_e32 v4, v0
	v_mov_b32_e32 v5, v0
	v_mov_b32_e32 v6, v0
	v_mov_b32_e32 v7, v0
	v_mov_b32_e32 v8, v0
	v_mov_b32_e32 v9, v0
	v_mov_b32_e32 v10, v0
	v_mov_b32_e32 v11, v0
	v_mov_b32_e32 v12, v0
	v_mov_b32_e32 v13, v0
	v_mov_b32_e32 v14, v0
	v_mov_b32_e32 v15, v0
	v_mov_b32_e32 v16, v0
	v_mov_b32_e32 v17, v0
	v_mov_b32_e32 v18, v0
	v_mov_b32_e32 v19, v0
	v_mov_b32_e32 v20, v0
	v_mov_b32_e32 v21, v0
	v_mov_b32_e32 v22, v0
	v_mov_b32_e32 v23, v0
	v_mov_b32_e32 v24, v0
	v_mov_b32_e32 v25, v0
	v_mov_b32_e32 v26, v0
	v_mov_b32_e32 v27, v0
	v_mov_b32_e32 v28, v0
	v_mov_b32_e32 v29, v0
	v_mov_b32_e32 v30, v0
	v_mov_b32_e32 v31, v0
	v_mov_b32_e32 v32, v0
	v_mov_b32_e32 v33, v0
	v_mov_b32_e32 v34, v0
	v_mov_b32_e32 v35, v0
	v_mov_b32_e32 v36, v0
	v_mov_b32_e32 v37, v0
	v_mov_b32_e32 v38, v0
	v_mov_b32_e32 v39, v0
	v_mov_b32_e32 v40, v0
	v_mov_b32_e32 v41, v0
	v_mov_b32_e32 v42, v0
	v_mov_b32_e32 v43, v0
	v_mov_b32_e32 v44, v0
	v_mov_b32_e32 v45, v0
	v_mov_b32_e32 v46, v0
	v_mov_b32_e32 v47, v0
	v_mov_b32_e32 v48, v0
	v_mov_b32_e32 v49, v0
	v_mov_b32_e32 v50, v0
	v_mov_b32_e32 v51, v0
	v_mov_b32_e32 v52, v0
	v_mov_b32_e32 v53, v0
	v_mov_b32_e32 v54, v0
	v_mov_b32_e32 v55, v0
	v_mov_b32_e32 v56, v0
	v_mov_b32_e32 v57, v0
	v_mov_b32_e32 v58, v0
	v_mov_b32_e32 v59, v0
	v_mov_b32_e32 v60, v0
	v_mov_b32_e32 v61, v0
	v_mov_b32_e32 v62, v0
	v_mov_b32_e32 v63, v0
	s_waitcnt vmcnt(0) lgkmcnt(0)
	s_barrier

; DEVI int opaque_tid() { int t = (int)threadIdx.x; asm volatile("" : "+v"(t)); return t; }
; template <bool TRANS, class Epi>
; DEVI void gemm_tile(const bf16_t* __restrict__ A0, const bf16_t* __restrict__ A1, int ksplit, int lda,
;                     const bf16_t* __restrict__ Bt, int ldb, int nk, char* smem, const Epi& epi, int row0, int col0) {
;     const int tid = opaque_tid(), lane = tid & 63, w = tid >> 6, wr = w >> 1, wc = w & 1, fr = lane & 15, fq = lane >> 4;
;     f32x4 acc[4][4];
; #pragma unroll
;     for (int m = 0; m < 4; ++m)
; #pragma unroll
;         for (int n = 0; n < 4; ++n) acc[m][n] = (f32x4){0.f, 0.f, 0.f, 0.f};
;     const int srow = w * 8 + (lane >> 3), sch = (lane & 7) ^ ((lane >> 3) & 7);
;     const size_t aoff = (size_t)srow * lda + sch * 8, boff = (size_t)srow * ldb + sch * 8;
;     const int ldsoff = w * 1024 + lane * 16;
;     auto issue = [&](int kt, int buf) {
;         const bf16_t* ap = (kt < ksplit ? A0 + (size_t)kt * 64 : A1 + (size_t)(kt - ksplit) * 64) + aoff;
;         const bf16_t* bp = Bt + (size_t)kt * 64 + boff;
;         char* sa = smem + buf * 32768 + ldsoff;
;         char* sb = sa + 16384;
; #pragma unroll
;         for (int i = 0; i < 4; ++i) __builtin_amdgcn_global_load_lds((const unsigned*)(ap + (size_t)(32 * i) * lda), (unsigned*)(sa + i * 4096), 16, 0, 0);
; #pragma unroll
;         for (int i = 0; i < 4; ++i) __builtin_amdgcn_global_load_lds((const unsigned*)(bp + (size_t)(32 * i) * ldb), (unsigned*)(sb + i * 4096), 16, 0, 0);
;     };
;     __syncthreads();
;     issue(0, 0);
;     asm volatile("s_waitcnt vmcnt(0)" ::: "memory");
;     __syncthreads();
; __global__ void __launch_bounds__(256, 2) fwd_megakernel(P p) {
;     ...
;         for (int L = bid; L < 272 * 2; L += G) {
;             int pm, pn; tile_map(L, 272, 2, pm, pn);
;             gemm_tile<false>(bufA + (size_t)pm * 128 * 1024, bufA, 1 << 30, 1024, W1T + (size_t)(2304 + pn * 128) * 1024, 1024, 16, smem, eb, pm * 128, pn * 128);
.LBB0_1371:
	s_and_b32 s2, s36, 7
	s_mulk_i32 s2, 0x44
	s_ashr_i32 s26, s36, 3
	s_add_i32 s2, s2, s26
	s_ashr_i32 s26, s2, 31
	s_lshr_b32 s26, s26, 28
	s_add_i32 s26, s2, s26
	s_ashr_i32 s28, s26, 4
	s_and_b32 s26, s26, 0xfff0
	s_sub_i32 s2, s2, s26
	s_bfe_i32 s26, s2, 0x80000
	s_bfe_u32 s26, s26, 0x3000c
	s_add_i32 s26, s2, s26
	s_bfe_i32 s29, s26, 0x80000
	s_and_b32 s26, s26, 0xf8
	s_sub_i32 s2, s2, s26
	s_lshl_b32 s28, s28, 3
	s_sext_i32_i8 s2, s2
	s_add_i32 s28, s28, s2
	s_sext_i32_i16 s37, s29
	s_ashr_i32 s29, s28, 31
	s_lshl_b64 s[30:31], s[28:29], 18
	v_mov_b32_e32 v8, v172
	s_add_u32 s38, s90, s30
	s_addc_u32 s39, s91, s31
	v_ashrrev_i32_e32 v3, 6, v8
	v_bfe_u32 v1, v8, 3, 3
	s_lshl_b32 s2, s37, 4
	v_and_b32_e32 v2, 63, v8
	v_lshl_or_b32 v0, v3, 3, v1
	s_and_b32 s29, s2, 0xffffff80
	v_bitop3_b32 v4, v1, v8, 7 bitop3:0x78
	v_ashrrev_i32_e32 v1, 31, v0
	v_lshlrev_b32_e32 v6, 10, v3
	v_lshlrev_b32_e32 v7, 4, v2
	s_add_i32 s2, s29, 0x900
	v_lshlrev_b64 v[0:1], 11, v[0:1]
	v_lshlrev_b32_e32 v10, 4, v4
	v_add3_u32 v73, 0, v6, v7
	s_lshl_b64 s[42:43], s[2:3], 11
	v_and_b32_e32 v72, 1, v3
	v_or_b32_e32 v2, v0, v10
	v_mov_b32_e32 v3, v1
	v_readfirstlane_b32 s2, v73
	v_add_u32_e32 v11, 0x1000, v73
	v_lshl_add_u64 v[4:5], s[38:39], 0, v[2:3]
	s_mov_b32 m0, s2
	v_readfirstlane_b32 s2, v11
	v_add_u32_e32 v11, 0x2000, v73
	s_barrier
	global_load_lds_dwordx4 v[4:5], off
	v_lshl_add_u64 v[6:7], v[4:5], 0, s[4:5]
	s_mov_b32 m0, s2
	v_readfirstlane_b32 s2, v11
	global_load_lds_dwordx4 v[6:7], off
	v_lshl_add_u64 v[6:7], v[4:5], 0, s[6:7]
	s_mov_b32 m0, s2
	v_lshl_add_u64 v[4:5], v[4:5], 0, s[8:9]
	global_load_lds_dwordx4 v[6:7], off
	v_add_u32_e32 v6, 0x3000, v73
	s_add_u32 s44, s58, s42
	v_readfirstlane_b32 s2, v6
	s_mov_b32 m0, s2
	s_addc_u32 s45, s59, s43
	global_load_lds_dwordx4 v[4:5], off
	v_add_u32_e32 v4, 0x4000, v73
	v_add_u32_e32 v6, 0x5000, v73
	v_readfirstlane_b32 s2, v4
	v_lshl_add_u64 v[2:3], s[44:45], 0, v[2:3]
	s_mov_b32 m0, s2
	v_readfirstlane_b32 s2, v6
	v_add_u32_e32 v6, 0x6000, v73
	global_load_lds_dwordx4 v[2:3], off
	v_lshl_add_u64 v[4:5], v[2:3], 0, s[4:5]
	s_mov_b32 m0, s2
	v_readfirstlane_b32 s2, v6
	global_load_lds_dwordx4 v[4:5], off
	v_lshl_add_u64 v[4:5], v[2:3], 0, s[6:7]
	s_mov_b32 m0, s2
	v_lshl_add_u64 v[2:3], v[2:3], 0, s[8:9]
	global_load_lds_dwordx4 v[4:5], off
	v_add_u32_e32 v4, 0x7000, v73
	v_bfe_u32 v64, v8, 4, 2
	v_readfirstlane_b32 s2, v4
	s_mov_b32 m0, s2
	v_and_b32_e32 v70, 15, v8
	global_load_lds_dwordx4 v[2:3], off
	v_bitop3_b32 v2, v64, v8, 7 bitop3:0x78
	v_ashrrev_i32_e32 v71, 7, v8
	v_and_b32_e32 v9, 7, v8
	v_lshlrev_b32_e32 v77, 4, v2
	v_lshlrev_b32_e32 v2, 7, v70
	v_lshl_or_b32 v75, v71, 13, v2
	v_lshl_or_b32 v74, v72, 13, v2
	v_bitop3_b32 v2, v64, v9, 4 bitop3:0x36
	v_lshlrev_b32_e32 v76, 4, v2
	v_lshl_add_u64 v[2:3], s[30:31], 0, v[0:1]
	v_lshl_add_u64 v[0:1], v[0:1], 0, s[42:43]
	v_or_b32_e32 v2, v2, v10
	v_or_b32_e32 v0, v0, v10
	v_lshl_add_u64 v[66:67], s[90:91], 0, v[2:3]
	v_lshl_add_u64 v[68:69], s[90:91], 0, v[0:1]
	s_mov_b64 s[30:31], 0
	s_mov_b32 s2, 0
	v_mov_b32_e32 v0, 0
	v_mov_b32_e32 v1, v65
	v_mov_b32_e32 v2, v65
	v_mov_b32_e32 v3, v65
	v_mov_b32_e32 v4, 0
	v_mov_b32_e32 v5, v65
	v_mov_b32_e32 v6, v65
	v_mov_b32_e32 v7, v65
	v_mov_b32_e32 v8, 0
	v_mov_b32_e32 v9, v65
	v_mov_b32_e32 v10, v65
	v_mov_b32_e32 v11, v65
	v_mov_b32_e32 v12, 0
	v_mov_b32_e32 v13, v65
	v_mov_b32_e32 v14, v65
	v_mov_b32_e32 v15, v65
	v_mov_b32_e32 v16, 0
	v_mov_b32_e32 v17, v65
	v_mov_b32_e32 v18, v65
	v_mov_b32_e32 v19, v65
	v_mov_b32_e32 v20, 0
	v_mov_b32_e32 v21, v65
	v_mov_b32_e32 v22, v65
	v_mov_b32_e32 v23, v65
	v_mov_b32_e32 v24, 0
	v_mov_b32_e32 v25, v65
	v_mov_b32_e32 v26, v65
	v_mov_b32_e32 v27, v65
	v_mov_b32_e32 v28, 0
	v_mov_b32_e32 v29, v65
	v_mov_b32_e32 v30, v65
	v_mov_b32_e32 v31, v65
	v_mov_b32_e32 v32, 0
	v_mov_b32_e32 v33, v65
	v_mov_b32_e32 v34, v65
	v_mov_b32_e32 v35, v65
	v_mov_b32_e32 v36, 0
	v_mov_b32_e32 v37, v65
	v_mov_b32_e32 v38, v65
	v_mov_b32_e32 v39, v65
	v_mov_b32_e32 v40, 0
	v_mov_b32_e32 v41, v65
	v_mov_b32_e32 v42, v65
	v_mov_b32_e32 v43, v65
	v_mov_b32_e32 v44, 0
	v_mov_b32_e32 v45, v65
	v_mov_b32_e32 v46, v65
	v_mov_b32_e32 v47, v65
	v_mov_b32_e32 v48, 0
	v_mov_b32_e32 v49, v65
	v_mov_b32_e32 v50, v65
	v_mov_b32_e32 v51, v65
	v_mov_b32_e32 v52, 0
	v_mov_b32_e32 v53, v65
	v_mov_b32_e32 v54, v65
	v_mov_b32_e32 v55, v65
	v_mov_b32_e32 v56, 0
	v_mov_b32_e32 v57, v65
	v_mov_b32_e32 v58, v65
	v_mov_b32_e32 v59, v65
	v_mov_b32_e32 v60, 0
	v_mov_b32_e32 v61, v65
	v_mov_b32_e32 v62, v65
	v_mov_b32_e32 v63, v65
	s_waitcnt vmcnt(0) lgkmcnt(0)
	s_barrier
